# GEMM loops of P1,P3,P4,P5,P8: 8 phases merged into 4 double phases (32-MFMA segments, 8 barriers per iteration instead of 16; A-quarter refills delayed one phase; counted vmcnt per load segment)
# baseline (speedup 1.0000x reference)
.LBB0_50:
	v_mov_b32_e32 v133, v3
	v_lshl_add_u64 v[12:13], s[44:45], 0, v[132:133]
	v_mov_b32_e32 v137, v3
	s_lshl_b32 s1, s1, 5
	v_lshl_add_u64 v[14:15], s[44:45], 0, v[136:137]
	v_mov_b32_e32 v1, v3
	s_and_b32 s24, s1, 0x60
	s_add_i32 m0, s52, 0x18000
	v_lshl_add_u64 v[12:13], v[12:13], 0, s[76:77]
	s_lshr_b32 s22, s20, 3
	v_lshl_add_u64 v[16:17], s[42:43], 0, v[0:1]
	v_mov_b32_e32 v135, v3
	s_lshl_b32 s23, s0, 13
	s_lshl_b32 s1, s24, 7
	s_waitcnt vmcnt(2)
	s_barrier
	global_load_lds_dwordx4 v[12:13], off
	v_lshl_add_u64 v[12:13], v[14:15], 0, s[76:77]
	s_add_i32 m0, s52, 0x1a000
	s_add_i32 s56, s52, 0x8000
	s_add_i32 s57, s52, 0xa000
	v_lshl_add_u64 v[18:19], s[42:43], 0, v[134:135]
	global_load_lds_dwordx4 v[12:13], off
	v_lshl_add_u64 v[12:13], v[16:17], 0, s[76:77]
	s_mov_b32 m0, s56
	s_add_u32 s20, s44, 0xb0080
	global_load_lds_dwordx4 v[12:13], off
	v_lshl_add_u64 v[12:13], v[18:19], 0, s[76:77]
	s_mov_b32 m0, s57
	s_addc_u32 s21, s45, 0
	global_load_lds_dwordx4 v[12:13], off
	s_add_i32 m0, s52, 0x1c000
	v_lshl_add_u64 v[12:13], s[20:21], 0, v[132:133]
	global_load_lds_dwordx4 v[12:13], off
	v_lshl_add_u64 v[12:13], s[20:21], 0, v[136:137]
	s_add_i32 m0, s52, 0x1e000
	s_movk_i32 s2, 0xb00
	global_load_lds_dwordx4 v[12:13], off
	v_lshrrev_b32_e32 v12, 1, v2
	v_and_b32_e32 v12, 24, v12
	v_and_b32_e32 v13, 15, v2
	v_lshlrev_b32_e32 v14, 1, v12
	v_lshlrev_b32_e32 v2, 2, v2
	v_lshl_or_b32 v142, s0, 6, v13
	v_lshl_or_b32 v13, v13, 6, v14
	v_and_b32_e32 v2, 32, v2
	v_bitop3_b32 v16, v13, s23, v2 bitop3:0xde
	v_bitop3_b32 v143, v13, s1, v2 bitop3:0xde
	v_lshrrev_b32_e32 v4, 1, v4
	v_mul_lo_u32 v2, v6, s2
	s_mov_b32 s3, 0xb000
	v_mad_u64_u32 v[14:15], s[0:1], v4, s3, v[2:3]
	v_or_b32_e32 v2, v14, v5
	v_add_lshl_u32 v2, v2, v7, 1
	s_mov_b64 s[4:5], 0xb0080
	v_lshl_add_u64 v[138:139], v[2:3], 0, s[4:5]
	v_lshrrev_b32_e32 v4, 1, v8
	v_mul_lo_u32 v2, v10, s2
	v_mad_u64_u32 v[4:5], s[0:1], v4, s3, v[2:3]
	s_waitcnt vmcnt(6)
	v_or_b32_e32 v2, v4, v9
	v_add_lshl_u32 v2, v2, v11, 1
	s_sext_i32_i8 s62, s22
	v_lshl_add_u64 v[140:141], v[2:3], 0, s[4:5]
	s_mov_b32 s58, 0
	v_add_u32_e32 v144, 0, v16
	s_lshl_b32 s72, s24, 1
	v_lshlrev_b32_e32 v2, 1, v12
	s_mov_b64 s[0:1], s[42:43]
	s_mov_b64 s[40:41], s[44:45]
	s_barrier
	s_waitcnt vmcnt(0)

.LBB0_58:
	s_add_u32 s44, s42, 0x100
	s_addc_u32 s45, s43, 0
	ds_read_b128 v[146:149], v194
	ds_read_b128 v[150:153], v194 offset:1024
	ds_read_b128 v[154:157], v194 offset:2048
	ds_read_b128 v[158:161], v194 offset:3072
	s_cmp_eq_u32 s22, 40
	s_cselect_b32 s49, s1, s45
	s_cselect_b32 s48, s0, s44
	s_cselect_b32 s47, s41, s21
	s_cselect_b32 s46, s40, s20
	s_add_i32 m0, s52, 0xc000
	ds_read_b128 v[162:165], v144
	ds_read_b128 v[166:169], v144 offset:1024
	ds_read_b128 v[170:173], v144 offset:2048
	ds_read_b128 v[174:177], v144 offset:3072
	ds_read_b128 v[178:181], v144 offset:4096
	ds_read_b128 v[182:185], v144 offset:5120
	ds_read_b128 v[186:189], v144 offset:6144
	global_load_lds_dwordx4 v138, s[42:43]
	s_add_i32 m0, s52, 0xe000
	ds_read_b128 v[190:193], v144 offset:7168
	global_load_lds_dwordx4 v140, s[42:43]
	ds_read_b128 v[202:205], v194 offset:16384
	ds_read_b128 v[206:209], v194 offset:17408
	ds_read_b128 v[210:213], v194 offset:18432
	ds_read_b128 v[214:217], v194 offset:19456
	s_waitcnt vmcnt(8)
	s_barrier
	s_waitcnt lgkmcnt(0)
	v_mfma_f32_16x16x32_bf16 v[128:131], v[146:149], v[162:165], v[128:131]
	v_mfma_f32_16x16x32_bf16 v[124:127], v[154:157], v[162:165], v[124:127]
	v_mfma_f32_16x16x32_bf16 v[120:123], v[146:149], v[170:173], v[120:123]
	v_mfma_f32_16x16x32_bf16 v[116:119], v[154:157], v[170:173], v[116:119]
	v_mfma_f32_16x16x32_bf16 v[104:107], v[146:149], v[178:181], v[104:107]
	v_mfma_f32_16x16x32_bf16 v[100:103], v[154:157], v[178:181], v[100:103]
	v_mfma_f32_16x16x32_bf16 v[88:91], v[146:149], v[186:189], v[88:91]
	v_mfma_f32_16x16x32_bf16 v[84:87], v[154:157], v[186:189], v[84:87]
	v_mfma_f32_16x16x32_bf16 v[128:131], v[150:153], v[166:169], v[128:131]
	v_mfma_f32_16x16x32_bf16 v[124:127], v[158:161], v[166:169], v[124:127]
	v_mfma_f32_16x16x32_bf16 v[120:123], v[150:153], v[174:177], v[120:123]
	v_mfma_f32_16x16x32_bf16 v[116:119], v[158:161], v[174:177], v[116:119]
	v_mfma_f32_16x16x32_bf16 v[104:107], v[150:153], v[182:185], v[104:107]
	v_mfma_f32_16x16x32_bf16 v[100:103], v[158:161], v[182:185], v[100:103]
	v_mfma_f32_16x16x32_bf16 v[88:91], v[150:153], v[190:193], v[88:91]
	v_mfma_f32_16x16x32_bf16 v[84:87], v[158:161], v[190:193], v[84:87]
	v_mfma_f32_16x16x32_bf16 v[112:115], v[202:205], v[162:165], v[112:115]
	v_mfma_f32_16x16x32_bf16 v[108:111], v[210:213], v[162:165], v[108:111]
	v_mfma_f32_16x16x32_bf16 v[96:99], v[202:205], v[170:173], v[96:99]
	v_mfma_f32_16x16x32_bf16 v[92:95], v[210:213], v[170:173], v[92:95]
	v_mfma_f32_16x16x32_bf16 v[80:83], v[202:205], v[178:181], v[80:83]
	v_mfma_f32_16x16x32_bf16 v[76:79], v[210:213], v[178:181], v[76:79]
	v_mfma_f32_16x16x32_bf16 v[72:75], v[202:205], v[186:189], v[72:75]
	v_mfma_f32_16x16x32_bf16 v[68:71], v[210:213], v[186:189], v[68:71]
	v_mfma_f32_16x16x32_bf16 v[112:115], v[206:209], v[166:169], v[112:115]
	v_mfma_f32_16x16x32_bf16 v[108:111], v[214:217], v[166:169], v[108:111]
	v_mfma_f32_16x16x32_bf16 v[96:99], v[206:209], v[174:177], v[96:99]
	v_mfma_f32_16x16x32_bf16 v[92:95], v[214:217], v[174:177], v[92:95]
	v_mfma_f32_16x16x32_bf16 v[80:83], v[206:209], v[182:185], v[80:83]
	v_mfma_f32_16x16x32_bf16 v[76:79], v[214:217], v[182:185], v[76:79]
	v_mfma_f32_16x16x32_bf16 v[72:75], v[206:209], v[190:193], v[72:75]
	v_mfma_f32_16x16x32_bf16 v[68:71], v[214:217], v[190:193], v[68:71]
	s_barrier
	ds_read_b128 v[162:165], v144 offset:16384
	ds_read_b128 v[166:169], v144 offset:17408
	ds_read_b128 v[170:173], v144 offset:18432
	ds_read_b128 v[174:177], v144 offset:19456
	s_add_i32 m0, s37, 0x10000
	ds_read_b128 v[178:181], v144 offset:20480
	global_load_lds_dwordx4 v132, s[46:47]
	s_add_i32 m0, s37, 0x12000
	ds_read_b128 v[182:185], v144 offset:21504
	global_load_lds_dwordx4 v136, s[46:47]
	s_mov_b32 m0, s52
	ds_read_b128 v[186:189], v144 offset:22528
	global_load_lds_dwordx4 v0, s[48:49]
	s_mov_b32 m0, s53
	ds_read_b128 v[190:193], v144 offset:23552
	global_load_lds_dwordx4 v134, s[48:49]
	s_add_i32 m0, s37, 0x14000
	s_add_u32 s24, s46, 0xb0000
	s_addc_u32 s25, s47, 0
	global_load_lds_dwordx4 v132, s[24:25]
	s_add_i32 m0, s37, 0x16000
	s_waitcnt vmcnt(7)
	global_load_lds_dwordx4 v136, s[24:25]
	s_barrier
	s_waitcnt lgkmcnt(0)
	v_mfma_f32_16x16x32_bf16 v[64:67], v[146:149], v[162:165], v[64:67]
	v_mfma_f32_16x16x32_bf16 v[60:63], v[154:157], v[162:165], v[60:63]
	v_mfma_f32_16x16x32_bf16 v[56:59], v[146:149], v[170:173], v[56:59]
	v_mfma_f32_16x16x32_bf16 v[52:55], v[154:157], v[170:173], v[52:55]
	v_mfma_f32_16x16x32_bf16 v[40:43], v[146:149], v[178:181], v[40:43]
	v_mfma_f32_16x16x32_bf16 v[36:39], v[154:157], v[178:181], v[36:39]
	v_mfma_f32_16x16x32_bf16 v[24:27], v[146:149], v[186:189], v[24:27]
	v_mfma_f32_16x16x32_bf16 v[16:19], v[154:157], v[186:189], v[16:19]
	v_mfma_f32_16x16x32_bf16 v[64:67], v[150:153], v[166:169], v[64:67]
	v_mfma_f32_16x16x32_bf16 v[60:63], v[158:161], v[166:169], v[60:63]
	v_mfma_f32_16x16x32_bf16 v[56:59], v[150:153], v[174:177], v[56:59]
	v_mfma_f32_16x16x32_bf16 v[52:55], v[158:161], v[174:177], v[52:55]
	v_mfma_f32_16x16x32_bf16 v[40:43], v[150:153], v[182:185], v[40:43]
	v_mfma_f32_16x16x32_bf16 v[36:39], v[158:161], v[182:185], v[36:39]
	v_mfma_f32_16x16x32_bf16 v[24:27], v[150:153], v[190:193], v[24:27]
	v_mfma_f32_16x16x32_bf16 v[16:19], v[158:161], v[190:193], v[16:19]
	v_mfma_f32_16x16x32_bf16 v[48:51], v[202:205], v[162:165], v[48:51]
	v_mfma_f32_16x16x32_bf16 v[44:47], v[210:213], v[162:165], v[44:47]
	v_mfma_f32_16x16x32_bf16 v[32:35], v[202:205], v[170:173], v[32:35]
	v_mfma_f32_16x16x32_bf16 v[28:31], v[210:213], v[170:173], v[28:31]
	v_mfma_f32_16x16x32_bf16 v[20:23], v[202:205], v[178:181], v[20:23]
	v_mfma_f32_16x16x32_bf16 v[12:15], v[210:213], v[178:181], v[12:15]
	v_mfma_f32_16x16x32_bf16 v[8:11], v[202:205], v[186:189], v[8:11]
	v_mfma_f32_16x16x32_bf16 v[4:7], v[210:213], v[186:189], v[4:7]
	v_mfma_f32_16x16x32_bf16 v[48:51], v[206:209], v[166:169], v[48:51]
	v_mfma_f32_16x16x32_bf16 v[44:47], v[214:217], v[166:169], v[44:47]
	v_mfma_f32_16x16x32_bf16 v[32:35], v[206:209], v[174:177], v[32:35]
	v_mfma_f32_16x16x32_bf16 v[28:31], v[214:217], v[174:177], v[28:31]
	v_mfma_f32_16x16x32_bf16 v[20:23], v[206:209], v[182:185], v[20:23]
	v_mfma_f32_16x16x32_bf16 v[12:15], v[214:217], v[182:185], v[12:15]
	v_mfma_f32_16x16x32_bf16 v[8:11], v[206:209], v[190:193], v[8:11]
	v_mfma_f32_16x16x32_bf16 v[4:7], v[214:217], v[190:193], v[4:7]
	s_barrier
	ds_read_b128 v[146:149], v194 offset:32768
	ds_read_b128 v[150:153], v194 offset:33792
	ds_read_b128 v[154:157], v194 offset:34816
	ds_read_b128 v[158:161], v194 offset:35840
	s_add_u32 s24, s48, 0xb0000
	s_addc_u32 s25, s49, 0
	s_mov_b32 m0, s54
	ds_read_b128 v[162:165], v144 offset:32768
	ds_read_b128 v[166:169], v144 offset:33792
	ds_read_b128 v[170:173], v144 offset:34816
	ds_read_b128 v[174:177], v144 offset:35840
	ds_read_b128 v[178:181], v144 offset:36864
	ds_read_b128 v[182:185], v144 offset:37888
	ds_read_b128 v[186:189], v144 offset:38912
	global_load_lds_dwordx4 v0, s[24:25]
	s_mov_b32 m0, s55
	ds_read_b128 v[190:193], v144 offset:39936
	global_load_lds_dwordx4 v134, s[24:25]
	ds_read_b128 v[202:205], v194 offset:49152
	ds_read_b128 v[206:209], v194 offset:50176
	ds_read_b128 v[210:213], v194 offset:51200
	ds_read_b128 v[214:217], v194 offset:52224
	s_waitcnt vmcnt(8)
	s_barrier
	s_waitcnt lgkmcnt(0)
	v_mfma_f32_16x16x32_bf16 v[128:131], v[146:149], v[162:165], v[128:131]
	v_mfma_f32_16x16x32_bf16 v[124:127], v[154:157], v[162:165], v[124:127]
	v_mfma_f32_16x16x32_bf16 v[120:123], v[146:149], v[170:173], v[120:123]
	v_mfma_f32_16x16x32_bf16 v[116:119], v[154:157], v[170:173], v[116:119]
	v_mfma_f32_16x16x32_bf16 v[104:107], v[146:149], v[178:181], v[104:107]
	v_mfma_f32_16x16x32_bf16 v[100:103], v[154:157], v[178:181], v[100:103]
	v_mfma_f32_16x16x32_bf16 v[88:91], v[146:149], v[186:189], v[88:91]
	v_mfma_f32_16x16x32_bf16 v[84:87], v[154:157], v[186:189], v[84:87]
	v_mfma_f32_16x16x32_bf16 v[128:131], v[150:153], v[166:169], v[128:131]
	v_mfma_f32_16x16x32_bf16 v[124:127], v[158:161], v[166:169], v[124:127]
	v_mfma_f32_16x16x32_bf16 v[120:123], v[150:153], v[174:177], v[120:123]
	v_mfma_f32_16x16x32_bf16 v[116:119], v[158:161], v[174:177], v[116:119]
	v_mfma_f32_16x16x32_bf16 v[104:107], v[150:153], v[182:185], v[104:107]
	v_mfma_f32_16x16x32_bf16 v[100:103], v[158:161], v[182:185], v[100:103]
	v_mfma_f32_16x16x32_bf16 v[88:91], v[150:153], v[190:193], v[88:91]
	v_mfma_f32_16x16x32_bf16 v[84:87], v[158:161], v[190:193], v[84:87]
	v_mfma_f32_16x16x32_bf16 v[112:115], v[202:205], v[162:165], v[112:115]
	v_mfma_f32_16x16x32_bf16 v[108:111], v[210:213], v[162:165], v[108:111]
	v_mfma_f32_16x16x32_bf16 v[96:99], v[202:205], v[170:173], v[96:99]
	v_mfma_f32_16x16x32_bf16 v[92:95], v[210:213], v[170:173], v[92:95]
	v_mfma_f32_16x16x32_bf16 v[80:83], v[202:205], v[178:181], v[80:83]
	v_mfma_f32_16x16x32_bf16 v[76:79], v[210:213], v[178:181], v[76:79]
	v_mfma_f32_16x16x32_bf16 v[72:75], v[202:205], v[186:189], v[72:75]
	v_mfma_f32_16x16x32_bf16 v[68:71], v[210:213], v[186:189], v[68:71]
	v_mfma_f32_16x16x32_bf16 v[112:115], v[206:209], v[166:169], v[112:115]
	v_mfma_f32_16x16x32_bf16 v[108:111], v[214:217], v[166:169], v[108:111]
	v_mfma_f32_16x16x32_bf16 v[96:99], v[206:209], v[174:177], v[96:99]
	v_mfma_f32_16x16x32_bf16 v[92:95], v[214:217], v[174:177], v[92:95]
	v_mfma_f32_16x16x32_bf16 v[80:83], v[206:209], v[182:185], v[80:83]
	v_mfma_f32_16x16x32_bf16 v[76:79], v[214:217], v[182:185], v[76:79]
	v_mfma_f32_16x16x32_bf16 v[72:75], v[206:209], v[190:193], v[72:75]
	v_mfma_f32_16x16x32_bf16 v[68:71], v[214:217], v[190:193], v[68:71]
	s_barrier
	ds_read_b128 v[162:165], v144 offset:49152
	ds_read_b128 v[166:169], v144 offset:50176
	ds_read_b128 v[170:173], v144 offset:51200
	ds_read_b128 v[174:177], v144 offset:52224
	ds_read_b128 v[178:181], v144 offset:53248
	ds_read_b128 v[182:185], v144 offset:54272
	s_add_i32 m0, s37, 0x18000
	s_add_u32 s98, s46, 0x80
	s_addc_u32 s99, s47, 0
	global_load_lds_dwordx4 v132, s[98:99]
	s_add_i32 m0, s37, 0x1a000
	ds_read_b128 v[186:189], v144 offset:55296
	global_load_lds_dwordx4 v136, s[98:99]
	s_mov_b32 m0, s56
	s_add_u32 s98, s48, 0x80
	s_addc_u32 s99, s49, 0
	global_load_lds_dwordx4 v0, s[98:99]
	s_mov_b32 m0, s57
	ds_read_b128 v[190:193], v144 offset:56320
	global_load_lds_dwordx4 v134, s[98:99]
	s_add_i32 m0, s37, 0x1c000
	s_add_u32 s24, s46, 0xb0080
	s_addc_u32 s25, s47, 0
	global_load_lds_dwordx4 v132, s[24:25]
	s_add_i32 m0, s37, 0x1e000
	s_waitcnt vmcnt(7)
	global_load_lds_dwordx4 v136, s[24:25]
	s_barrier
	s_waitcnt lgkmcnt(0)
	v_mfma_f32_16x16x32_bf16 v[64:67], v[146:149], v[162:165], v[64:67]
	v_mfma_f32_16x16x32_bf16 v[60:63], v[154:157], v[162:165], v[60:63]
	v_mfma_f32_16x16x32_bf16 v[56:59], v[146:149], v[170:173], v[56:59]
	v_mfma_f32_16x16x32_bf16 v[52:55], v[154:157], v[170:173], v[52:55]
	v_mfma_f32_16x16x32_bf16 v[40:43], v[146:149], v[178:181], v[40:43]
	v_mfma_f32_16x16x32_bf16 v[36:39], v[154:157], v[178:181], v[36:39]
	v_mfma_f32_16x16x32_bf16 v[24:27], v[146:149], v[186:189], v[24:27]
	v_mfma_f32_16x16x32_bf16 v[16:19], v[154:157], v[186:189], v[16:19]
	v_mfma_f32_16x16x32_bf16 v[64:67], v[150:153], v[166:169], v[64:67]
	v_mfma_f32_16x16x32_bf16 v[60:63], v[158:161], v[166:169], v[60:63]
	v_mfma_f32_16x16x32_bf16 v[56:59], v[150:153], v[174:177], v[56:59]
	v_mfma_f32_16x16x32_bf16 v[52:55], v[158:161], v[174:177], v[52:55]
	v_mfma_f32_16x16x32_bf16 v[40:43], v[150:153], v[182:185], v[40:43]
	v_mfma_f32_16x16x32_bf16 v[36:39], v[158:161], v[182:185], v[36:39]
	v_mfma_f32_16x16x32_bf16 v[24:27], v[150:153], v[190:193], v[24:27]
	v_mfma_f32_16x16x32_bf16 v[16:19], v[158:161], v[190:193], v[16:19]
	v_mfma_f32_16x16x32_bf16 v[48:51], v[202:205], v[162:165], v[48:51]
	v_mfma_f32_16x16x32_bf16 v[44:47], v[210:213], v[162:165], v[44:47]
	v_mfma_f32_16x16x32_bf16 v[32:35], v[202:205], v[170:173], v[32:35]
	v_mfma_f32_16x16x32_bf16 v[28:31], v[210:213], v[170:173], v[28:31]
	v_mfma_f32_16x16x32_bf16 v[20:23], v[202:205], v[178:181], v[20:23]
	v_mfma_f32_16x16x32_bf16 v[12:15], v[210:213], v[178:181], v[12:15]
	v_mfma_f32_16x16x32_bf16 v[8:11], v[202:205], v[186:189], v[8:11]
	v_mfma_f32_16x16x32_bf16 v[4:7], v[210:213], v[186:189], v[4:7]
	v_mfma_f32_16x16x32_bf16 v[48:51], v[206:209], v[166:169], v[48:51]
	v_mfma_f32_16x16x32_bf16 v[44:47], v[214:217], v[166:169], v[44:47]
	v_mfma_f32_16x16x32_bf16 v[32:35], v[206:209], v[174:177], v[32:35]
	v_mfma_f32_16x16x32_bf16 v[28:31], v[214:217], v[174:177], v[28:31]
	v_mfma_f32_16x16x32_bf16 v[20:23], v[206:209], v[182:185], v[20:23]
	v_mfma_f32_16x16x32_bf16 v[12:15], v[214:217], v[182:185], v[12:15]
	v_mfma_f32_16x16x32_bf16 v[8:11], v[206:209], v[190:193], v[8:11]
	v_mfma_f32_16x16x32_bf16 v[4:7], v[214:217], v[190:193], v[4:7]
	s_add_i32 s22, s22, 2
	s_add_u32 s20, s20, 0x100
	s_addc_u32 s21, s21, 0
	s_cmp_gt_u32 s22, 41
	s_mov_b64 s[42:43], s[44:45]
	s_barrier
	s_cbranch_scc0 .LBB0_58
	v_lshl_add_u32 v146, s61, 8, v142
	v_cvt_pk_bf16_f32 v72, v72, v73
	v_cvt_pk_bf16_f32 v73, v74, v75
	v_cvt_pk_bf16_f32 v74, v68, v69
	v_add_u32_e32 v68, 0x80, v146
	s_lshl_b32 s20, s62, 8
	v_ashrrev_i32_e32 v147, 31, v146
	v_readlane_b32 s22, v252, 10
	v_cvt_pk_bf16_f32 v112, v112, v113
	v_cvt_pk_bf16_f32 v113, v114, v115
	v_cvt_pk_bf16_f32 v114, v108, v109
	v_or_b32_e32 v108, 16, v146
	v_ashrrev_i32_e32 v69, 31, v68
	v_cvt_pk_bf16_f32 v48, v48, v49
	v_cvt_pk_bf16_f32 v49, v50, v51
	v_cvt_pk_bf16_f32 v50, v44, v45
	v_add_u32_e32 v44, 0x90, v146
	s_ashr_i32 s21, s20, 31
	v_lshlrev_b64 v[148:149], 11, v[146:147]
	v_readlane_b32 s23, v252, 11
	v_ashrrev_i32_e32 v109, 31, v108
	v_cvt_pk_bf16_f32 v96, v96, v97
	v_cvt_pk_bf16_f32 v97, v98, v99
	v_cvt_pk_bf16_f32 v98, v92, v93
	v_or_b32_e32 v92, 32, v146
	v_lshlrev_b64 v[68:69], 11, v[68:69]
	v_ashrrev_i32_e32 v45, 31, v44
	v_cvt_pk_bf16_f32 v32, v32, v33
	v_cvt_pk_bf16_f32 v33, v34, v35
	v_cvt_pk_bf16_f32 v34, v28, v29
	v_add_u32_e32 v28, 0xa0, v146
	v_lshl_add_u64 v[148:149], s[22:23], 0, v[148:149]
	s_lshl_b64 s[42:43], s[20:21], 1
	v_lshlrev_b64 v[108:109], 11, v[108:109]
	v_ashrrev_i32_e32 v93, 31, v92
	v_cvt_pk_bf16_f32 v80, v80, v81
	v_cvt_pk_bf16_f32 v81, v82, v83
	v_cvt_pk_bf16_f32 v82, v76, v77
	v_or_b32_e32 v76, 48, v146
	v_lshl_add_u64 v[68:69], s[22:23], 0, v[68:69]
	v_lshlrev_b64 v[44:45], 11, v[44:45]
	v_ashrrev_i32_e32 v29, 31, v28
	v_cvt_pk_bf16_f32 v20, v20, v21
	v_cvt_pk_bf16_f32 v21, v22, v23
	v_cvt_pk_bf16_f32 v22, v12, v13
	v_add_u32_e32 v12, 0xb0, v146
	v_lshl_add_u64 v[148:149], v[148:149], 0, s[42:43]
	v_lshl_add_u64 v[108:109], s[22:23], 0, v[108:109]
	v_lshlrev_b64 v[92:93], 11, v[92:93]
	v_ashrrev_i32_e32 v77, 31, v76
	v_lshl_add_u64 v[68:69], v[68:69], 0, s[42:43]
	v_lshl_add_u64 v[44:45], s[22:23], 0, v[44:45]
	v_lshlrev_b64 v[28:29], 11, v[28:29]
	v_ashrrev_i32_e32 v13, 31, v12
	v_lshl_add_u64 v[148:149], v[148:149], 0, s[72:73]
	v_lshl_add_u64 v[108:109], v[108:109], 0, s[42:43]
	v_lshl_add_u64 v[92:93], s[22:23], 0, v[92:93]
	v_lshlrev_b64 v[76:77], 11, v[76:77]
	v_lshl_add_u64 v[68:69], v[68:69], 0, s[72:73]
	v_lshl_add_u64 v[44:45], v[44:45], 0, s[42:43]
	v_lshl_add_u64 v[28:29], s[22:23], 0, v[28:29]
	v_lshlrev_b64 v[12:13], 11, v[12:13]
	v_lshl_add_u64 v[148:149], v[148:149], 0, v[2:3]
	v_cvt_pk_bf16_f32 v115, v110, v111
	v_lshl_add_u64 v[108:109], v[108:109], 0, s[72:73]
	v_lshl_add_u64 v[92:93], v[92:93], 0, s[42:43]
	v_lshl_add_u64 v[76:77], s[22:23], 0, v[76:77]
	v_lshl_add_u64 v[68:69], v[68:69], 0, v[2:3]
	v_cvt_pk_bf16_f32 v51, v46, v47
	v_lshl_add_u64 v[44:45], v[44:45], 0, s[72:73]
	v_lshl_add_u64 v[28:29], v[28:29], 0, s[42:43]
	v_lshl_add_u64 v[12:13], s[22:23], 0, v[12:13]
	global_store_dwordx4 v[148:149], v[112:115], off offset:256
	v_cvt_pk_bf16_f32 v99, v94, v95
	v_lshl_add_u64 v[92:93], v[92:93], 0, s[72:73]
	v_lshl_add_u64 v[112:113], v[108:109], 0, v[2:3]
	v_lshl_add_u64 v[76:77], v[76:77], 0, s[42:43]
	global_store_dwordx4 v[68:69], v[48:51], off offset:256
	v_cvt_pk_bf16_f32 v35, v30, v31
	v_lshl_add_u64 v[28:29], v[28:29], 0, s[72:73]
	v_lshl_add_u64 v[48:49], v[44:45], 0, v[2:3]
	v_lshl_add_u64 v[12:13], v[12:13], 0, s[42:43]
	global_store_dwordx4 v[112:113], v[96:99], off offset:256
	v_cvt_pk_bf16_f32 v83, v78, v79
	v_lshl_add_u64 v[76:77], v[76:77], 0, s[72:73]
	v_lshl_add_u64 v[96:97], v[92:93], 0, v[2:3]
	global_store_dwordx4 v[48:49], v[32:35], off offset:256
	v_cvt_pk_bf16_f32 v23, v14, v15
	v_lshl_add_u64 v[12:13], v[12:13], 0, s[72:73]
	v_lshl_add_u64 v[32:33], v[28:29], 0, v[2:3]
	v_cvt_pk_bf16_f32 v128, v128, v129
	v_cvt_pk_bf16_f32 v129, v130, v131
	v_cvt_pk_bf16_f32 v130, v124, v125
	v_cvt_pk_bf16_f32 v131, v126, v127
	v_cvt_pk_bf16_f32 v108, v120, v121
	v_cvt_pk_bf16_f32 v109, v122, v123
	v_cvt_pk_bf16_f32 v110, v116, v117
	v_cvt_pk_bf16_f32 v111, v118, v119
	v_cvt_pk_bf16_f32 v92, v104, v105
	v_cvt_pk_bf16_f32 v93, v106, v107
	v_cvt_pk_bf16_f32 v94, v100, v101
	v_cvt_pk_bf16_f32 v95, v102, v103
	global_store_dwordx4 v[96:97], v[80:83], off offset:256
	v_cvt_pk_bf16_f32 v78, v84, v85
	v_cvt_pk_bf16_f32 v79, v86, v87
	v_lshl_add_u64 v[80:81], v[76:77], 0, v[2:3]
	v_cvt_pk_bf16_f32 v76, v88, v89
	v_cvt_pk_bf16_f32 v77, v90, v91
	v_cvt_pk_bf16_f32 v75, v70, v71
	v_cvt_pk_bf16_f32 v64, v64, v65
	v_cvt_pk_bf16_f32 v65, v66, v67
	v_cvt_pk_bf16_f32 v66, v60, v61
	v_cvt_pk_bf16_f32 v67, v62, v63
	v_cvt_pk_bf16_f32 v44, v56, v57
	v_cvt_pk_bf16_f32 v45, v58, v59
	v_cvt_pk_bf16_f32 v46, v52, v53
	v_cvt_pk_bf16_f32 v47, v54, v55
	v_cvt_pk_bf16_f32 v28, v40, v41
	v_cvt_pk_bf16_f32 v29, v42, v43
	v_cvt_pk_bf16_f32 v30, v36, v37
	v_cvt_pk_bf16_f32 v31, v38, v39
	global_store_dwordx4 v[32:33], v[20:23], off offset:256
	v_cvt_pk_bf16_f32 v14, v16, v17
	v_cvt_pk_bf16_f32 v15, v18, v19
	v_lshl_add_u64 v[20:21], v[12:13], 0, v[2:3]
	v_cvt_pk_bf16_f32 v12, v24, v25
	v_cvt_pk_bf16_f32 v13, v26, v27
	v_cvt_pk_bf16_f32 v8, v8, v9
	v_cvt_pk_bf16_f32 v9, v10, v11
	v_cvt_pk_bf16_f32 v10, v4, v5
	v_cvt_pk_bf16_f32 v11, v6, v7
	s_and_b64 vcc, exec, s[38:39]
	s_mov_b32 s62, s59
	s_mov_b32 s61, s60
	s_mov_b64 s[44:45], s[40:41]
	s_mov_b64 s[42:43], s[0:1]
	global_store_dwordx4 v[148:149], v[128:131], off
	global_store_dwordx4 v[112:113], v[108:111], off
	global_store_dwordx4 v[96:97], v[92:95], off
	global_store_dwordx4 v[80:81], v[76:79], off
	global_store_dwordx4 v[80:81], v[72:75], off offset:256
	global_store_dwordx4 v[68:69], v[64:67], off
	global_store_dwordx4 v[48:49], v[44:47], off
	global_store_dwordx4 v[32:33], v[28:31], off
	global_store_dwordx4 v[20:21], v[12:15], off
	global_store_dwordx4 v[20:21], v[8:11], off offset:256
	s_cbranch_vccz .LBB0_51
	s_waitcnt vmcnt(0)
	s_cmpk_gt_u32 s36, 0xff
	s_cbranch_scc1 .LBB0_62
	s_barrier

.LBB0_128:
	s_and_b32 s1, 0xffff, s22
	s_cmp_lg_u32 s1, 0
	s_cselect_b64 s[24:25], -1, 0
	s_cmp_lg_u64 s[24:25], 0
	s_addc_u32 s58, s20, 0
	s_lshl_b32 s1, s23, 5
	s_and_b32 s24, s1, 0x60
	s_add_i32 m0, s54, 0x18000
	v_lshl_add_u64 v[10:11], v[10:11], 0, s[76:77]
	s_lshl_b32 s20, s21, 13
	s_lshl_b32 s25, s24, 7
	s_waitcnt vmcnt(2)
	s_barrier
	global_load_lds_dwordx4 v[10:11], off
	v_lshl_add_u64 v[8:9], v[8:9], 0, s[76:77]
	s_add_i32 m0, s54, 0x1a000
	s_add_i32 s59, s54, 0x8000
	s_add_i32 s60, s54, 0xa000
	global_load_lds_dwordx4 v[8:9], off
	v_lshl_add_u64 v[6:7], v[6:7], 0, s[76:77]
	s_mov_b32 m0, s59
	s_add_u32 s22, s50, 0x40080
	global_load_lds_dwordx4 v[6:7], off
	v_lshl_add_u64 v[4:5], v[4:5], 0, s[76:77]
	s_mov_b32 m0, s60
	s_addc_u32 s23, s51, 0
	global_load_lds_dwordx4 v[4:5], off
	s_add_i32 m0, s54, 0x1c000
	v_lshl_add_u64 v[4:5], s[22:23], 0, v[132:133]
	global_load_lds_dwordx4 v[4:5], off
	v_lshl_add_u64 v[4:5], s[22:23], 0, v[136:137]
	s_add_i32 m0, s54, 0x1e000
	s_sext_i32_i8 s1, s38
	global_load_lds_dwordx4 v[4:5], off
	v_lshrrev_b32_e32 v4, 1, v2
	v_and_b32_e32 v4, 24, v4
	v_and_b32_e32 v5, 15, v2
	v_lshlrev_b32_e32 v6, 1, v4
	v_lshlrev_b32_e32 v2, 2, v2
	v_lshl_or_b32 v142, s21, 6, v5
	v_lshl_or_b32 v5, v5, 6, v6
	v_and_b32_e32 v2, 32, v2
	v_bitop3_b32 v6, v5, s20, v2 bitop3:0xde
	v_bitop3_b32 v143, v5, s25, v2 bitop3:0xde
	v_lshlrev_b32_e32 v2, 14, v12
	v_and_b32_e32 v2, 0xffff8000, v2
	v_lshl_add_u32 v2, v13, 11, v2
	v_and_b32_e32 v5, 1, v12
	v_lshl_or_b32 v2, v5, 6, v2
	v_lshl_add_u32 v138, v14, 1, v2
	v_lshlrev_b32_e32 v2, 14, v15
	v_and_b32_e32 v2, 0xffff8000, v2
	s_waitcnt vmcnt(6)
	v_lshl_add_u32 v2, v16, 11, v2
	v_and_b32_e32 v5, 1, v15
	v_lshl_or_b32 v2, v5, 6, v2
	s_mov_b32 s61, 0
	s_ashr_i32 s62, s58, 31
	v_mov_b32_e32 v139, v3
	v_lshl_add_u32 v140, v17, 1, v2
	v_mov_b32_e32 v141, v3
	v_add_u32_e32 v144, 0, v6
	s_lshl_b32 s72, s24, 1
	v_lshlrev_b32_e32 v2, 1, v4
	s_mov_b64 s[44:45], s[48:49]
	s_mov_b64 s[46:47], s[50:51]
	s_barrier

.LBB0_136:
	s_add_u32 s23, s48, 0xfffc0080
	s_addc_u32 s24, s49, -1
	ds_read_b128 v[146:149], v194
	ds_read_b128 v[150:153], v194 offset:1024
	ds_read_b128 v[154:157], v194 offset:2048
	ds_read_b128 v[158:161], v194 offset:3072
	s_cmp_eq_u32 s22, 12
	s_cselect_b32 s53, s45, s24
	s_cselect_b32 s52, s44, s23
	s_cselect_b32 s51, s47, s21
	s_cselect_b32 s50, s46, s20
	s_add_i32 m0, s54, 0xc000
	ds_read_b128 v[162:165], v144
	ds_read_b128 v[166:169], v144 offset:1024
	ds_read_b128 v[170:173], v144 offset:2048
	ds_read_b128 v[174:177], v144 offset:3072
	ds_read_b128 v[178:181], v144 offset:4096
	ds_read_b128 v[182:185], v144 offset:5120
	ds_read_b128 v[186:189], v144 offset:6144
	global_load_lds_dwordx4 v138, s[48:49]
	s_add_i32 m0, s54, 0xe000
	ds_read_b128 v[190:193], v144 offset:7168
	global_load_lds_dwordx4 v140, s[48:49]
	ds_read_b128 v[202:205], v194 offset:16384
	ds_read_b128 v[206:209], v194 offset:17408
	ds_read_b128 v[210:213], v194 offset:18432
	ds_read_b128 v[214:217], v194 offset:19456
	s_waitcnt vmcnt(8)
	s_barrier
	s_waitcnt lgkmcnt(0)
	v_mfma_f32_16x16x32_bf16 v[128:131], v[146:149], v[162:165], v[128:131]
	v_mfma_f32_16x16x32_bf16 v[124:127], v[154:157], v[162:165], v[124:127]
	v_mfma_f32_16x16x32_bf16 v[120:123], v[146:149], v[170:173], v[120:123]
	v_mfma_f32_16x16x32_bf16 v[116:119], v[154:157], v[170:173], v[116:119]
	v_mfma_f32_16x16x32_bf16 v[104:107], v[146:149], v[178:181], v[104:107]
	v_mfma_f32_16x16x32_bf16 v[100:103], v[154:157], v[178:181], v[100:103]
	v_mfma_f32_16x16x32_bf16 v[88:91], v[146:149], v[186:189], v[88:91]
	v_mfma_f32_16x16x32_bf16 v[84:87], v[154:157], v[186:189], v[84:87]
	v_mfma_f32_16x16x32_bf16 v[128:131], v[150:153], v[166:169], v[128:131]
	v_mfma_f32_16x16x32_bf16 v[124:127], v[158:161], v[166:169], v[124:127]
	v_mfma_f32_16x16x32_bf16 v[120:123], v[150:153], v[174:177], v[120:123]
	v_mfma_f32_16x16x32_bf16 v[116:119], v[158:161], v[174:177], v[116:119]
	v_mfma_f32_16x16x32_bf16 v[104:107], v[150:153], v[182:185], v[104:107]
	v_mfma_f32_16x16x32_bf16 v[100:103], v[158:161], v[182:185], v[100:103]
	v_mfma_f32_16x16x32_bf16 v[88:91], v[150:153], v[190:193], v[88:91]
	v_mfma_f32_16x16x32_bf16 v[84:87], v[158:161], v[190:193], v[84:87]
	v_mfma_f32_16x16x32_bf16 v[112:115], v[202:205], v[162:165], v[112:115]
	v_mfma_f32_16x16x32_bf16 v[108:111], v[210:213], v[162:165], v[108:111]
	v_mfma_f32_16x16x32_bf16 v[96:99], v[202:205], v[170:173], v[96:99]
	v_mfma_f32_16x16x32_bf16 v[92:95], v[210:213], v[170:173], v[92:95]
	v_mfma_f32_16x16x32_bf16 v[80:83], v[202:205], v[178:181], v[80:83]
	v_mfma_f32_16x16x32_bf16 v[76:79], v[210:213], v[178:181], v[76:79]
	v_mfma_f32_16x16x32_bf16 v[72:75], v[202:205], v[186:189], v[72:75]
	v_mfma_f32_16x16x32_bf16 v[68:71], v[210:213], v[186:189], v[68:71]
	v_mfma_f32_16x16x32_bf16 v[112:115], v[206:209], v[166:169], v[112:115]
	v_mfma_f32_16x16x32_bf16 v[108:111], v[214:217], v[166:169], v[108:111]
	v_mfma_f32_16x16x32_bf16 v[96:99], v[206:209], v[174:177], v[96:99]
	v_mfma_f32_16x16x32_bf16 v[92:95], v[214:217], v[174:177], v[92:95]
	v_mfma_f32_16x16x32_bf16 v[80:83], v[206:209], v[182:185], v[80:83]
	v_mfma_f32_16x16x32_bf16 v[76:79], v[214:217], v[182:185], v[76:79]
	v_mfma_f32_16x16x32_bf16 v[72:75], v[206:209], v[190:193], v[72:75]
	v_mfma_f32_16x16x32_bf16 v[68:71], v[214:217], v[190:193], v[68:71]
	s_barrier
	ds_read_b128 v[162:165], v144 offset:16384
	ds_read_b128 v[166:169], v144 offset:17408
	ds_read_b128 v[170:173], v144 offset:18432
	ds_read_b128 v[174:177], v144 offset:19456
	s_add_i32 m0, s37, 0x10000
	ds_read_b128 v[178:181], v144 offset:20480
	global_load_lds_dwordx4 v132, s[50:51]
	s_add_i32 m0, s37, 0x12000
	ds_read_b128 v[182:185], v144 offset:21504
	global_load_lds_dwordx4 v136, s[50:51]
	s_mov_b32 m0, s54
	ds_read_b128 v[186:189], v144 offset:22528
	global_load_lds_dwordx4 v0, s[52:53]
	s_mov_b32 m0, s55
	ds_read_b128 v[190:193], v144 offset:23552
	global_load_lds_dwordx4 v134, s[52:53]
	s_add_i32 m0, s37, 0x14000
	s_add_u32 s24, s50, 0x40000
	s_addc_u32 s25, s51, 0
	global_load_lds_dwordx4 v132, s[24:25]
	s_add_i32 m0, s37, 0x16000
	s_waitcnt vmcnt(7)
	global_load_lds_dwordx4 v136, s[24:25]
	s_barrier
	s_waitcnt lgkmcnt(0)
	v_mfma_f32_16x16x32_bf16 v[64:67], v[146:149], v[162:165], v[64:67]
	v_mfma_f32_16x16x32_bf16 v[60:63], v[154:157], v[162:165], v[60:63]
	v_mfma_f32_16x16x32_bf16 v[56:59], v[146:149], v[170:173], v[56:59]
	v_mfma_f32_16x16x32_bf16 v[52:55], v[154:157], v[170:173], v[52:55]
	v_mfma_f32_16x16x32_bf16 v[40:43], v[146:149], v[178:181], v[40:43]
	v_mfma_f32_16x16x32_bf16 v[36:39], v[154:157], v[178:181], v[36:39]
	v_mfma_f32_16x16x32_bf16 v[24:27], v[146:149], v[186:189], v[24:27]
	v_mfma_f32_16x16x32_bf16 v[16:19], v[154:157], v[186:189], v[16:19]
	v_mfma_f32_16x16x32_bf16 v[64:67], v[150:153], v[166:169], v[64:67]
	v_mfma_f32_16x16x32_bf16 v[60:63], v[158:161], v[166:169], v[60:63]
	v_mfma_f32_16x16x32_bf16 v[56:59], v[150:153], v[174:177], v[56:59]
	v_mfma_f32_16x16x32_bf16 v[52:55], v[158:161], v[174:177], v[52:55]
	v_mfma_f32_16x16x32_bf16 v[40:43], v[150:153], v[182:185], v[40:43]
	v_mfma_f32_16x16x32_bf16 v[36:39], v[158:161], v[182:185], v[36:39]
	v_mfma_f32_16x16x32_bf16 v[24:27], v[150:153], v[190:193], v[24:27]
	v_mfma_f32_16x16x32_bf16 v[16:19], v[158:161], v[190:193], v[16:19]
	v_mfma_f32_16x16x32_bf16 v[48:51], v[202:205], v[162:165], v[48:51]
	v_mfma_f32_16x16x32_bf16 v[44:47], v[210:213], v[162:165], v[44:47]
	v_mfma_f32_16x16x32_bf16 v[32:35], v[202:205], v[170:173], v[32:35]
	v_mfma_f32_16x16x32_bf16 v[28:31], v[210:213], v[170:173], v[28:31]
	v_mfma_f32_16x16x32_bf16 v[20:23], v[202:205], v[178:181], v[20:23]
	v_mfma_f32_16x16x32_bf16 v[12:15], v[210:213], v[178:181], v[12:15]
	v_mfma_f32_16x16x32_bf16 v[8:11], v[202:205], v[186:189], v[8:11]
	v_mfma_f32_16x16x32_bf16 v[4:7], v[210:213], v[186:189], v[4:7]
	v_mfma_f32_16x16x32_bf16 v[48:51], v[206:209], v[166:169], v[48:51]
	v_mfma_f32_16x16x32_bf16 v[44:47], v[214:217], v[166:169], v[44:47]
	v_mfma_f32_16x16x32_bf16 v[32:35], v[206:209], v[174:177], v[32:35]
	v_mfma_f32_16x16x32_bf16 v[28:31], v[214:217], v[174:177], v[28:31]
	v_mfma_f32_16x16x32_bf16 v[20:23], v[206:209], v[182:185], v[20:23]
	v_mfma_f32_16x16x32_bf16 v[12:15], v[214:217], v[182:185], v[12:15]
	v_mfma_f32_16x16x32_bf16 v[8:11], v[206:209], v[190:193], v[8:11]
	v_mfma_f32_16x16x32_bf16 v[4:7], v[214:217], v[190:193], v[4:7]
	s_barrier
	ds_read_b128 v[146:149], v194 offset:32768
	ds_read_b128 v[150:153], v194 offset:33792
	ds_read_b128 v[154:157], v194 offset:34816
	ds_read_b128 v[158:161], v194 offset:35840
	s_add_u32 s24, s52, 0x40000
	s_addc_u32 s25, s53, 0
	s_mov_b32 m0, s56
	ds_read_b128 v[162:165], v144 offset:32768
	ds_read_b128 v[166:169], v144 offset:33792
	ds_read_b128 v[170:173], v144 offset:34816
	ds_read_b128 v[174:177], v144 offset:35840
	ds_read_b128 v[178:181], v144 offset:36864
	ds_read_b128 v[182:185], v144 offset:37888
	ds_read_b128 v[186:189], v144 offset:38912
	global_load_lds_dwordx4 v0, s[24:25]
	s_mov_b32 m0, s57
	ds_read_b128 v[190:193], v144 offset:39936
	global_load_lds_dwordx4 v134, s[24:25]
	ds_read_b128 v[202:205], v194 offset:49152
	ds_read_b128 v[206:209], v194 offset:50176
	ds_read_b128 v[210:213], v194 offset:51200
	ds_read_b128 v[214:217], v194 offset:52224
	s_waitcnt vmcnt(8)
	s_barrier
	s_waitcnt lgkmcnt(0)
	v_mfma_f32_16x16x32_bf16 v[128:131], v[146:149], v[162:165], v[128:131]
	v_mfma_f32_16x16x32_bf16 v[124:127], v[154:157], v[162:165], v[124:127]
	v_mfma_f32_16x16x32_bf16 v[120:123], v[146:149], v[170:173], v[120:123]
	v_mfma_f32_16x16x32_bf16 v[116:119], v[154:157], v[170:173], v[116:119]
	v_mfma_f32_16x16x32_bf16 v[104:107], v[146:149], v[178:181], v[104:107]
	v_mfma_f32_16x16x32_bf16 v[100:103], v[154:157], v[178:181], v[100:103]
	v_mfma_f32_16x16x32_bf16 v[88:91], v[146:149], v[186:189], v[88:91]
	v_mfma_f32_16x16x32_bf16 v[84:87], v[154:157], v[186:189], v[84:87]
	v_mfma_f32_16x16x32_bf16 v[128:131], v[150:153], v[166:169], v[128:131]
	v_mfma_f32_16x16x32_bf16 v[124:127], v[158:161], v[166:169], v[124:127]
	v_mfma_f32_16x16x32_bf16 v[120:123], v[150:153], v[174:177], v[120:123]
	v_mfma_f32_16x16x32_bf16 v[116:119], v[158:161], v[174:177], v[116:119]
	v_mfma_f32_16x16x32_bf16 v[104:107], v[150:153], v[182:185], v[104:107]
	v_mfma_f32_16x16x32_bf16 v[100:103], v[158:161], v[182:185], v[100:103]
	v_mfma_f32_16x16x32_bf16 v[88:91], v[150:153], v[190:193], v[88:91]
	v_mfma_f32_16x16x32_bf16 v[84:87], v[158:161], v[190:193], v[84:87]
	v_mfma_f32_16x16x32_bf16 v[112:115], v[202:205], v[162:165], v[112:115]
	v_mfma_f32_16x16x32_bf16 v[108:111], v[210:213], v[162:165], v[108:111]
	v_mfma_f32_16x16x32_bf16 v[96:99], v[202:205], v[170:173], v[96:99]
	v_mfma_f32_16x16x32_bf16 v[92:95], v[210:213], v[170:173], v[92:95]
	v_mfma_f32_16x16x32_bf16 v[80:83], v[202:205], v[178:181], v[80:83]
	v_mfma_f32_16x16x32_bf16 v[76:79], v[210:213], v[178:181], v[76:79]
	v_mfma_f32_16x16x32_bf16 v[72:75], v[202:205], v[186:189], v[72:75]
	v_mfma_f32_16x16x32_bf16 v[68:71], v[210:213], v[186:189], v[68:71]
	v_mfma_f32_16x16x32_bf16 v[112:115], v[206:209], v[166:169], v[112:115]
	v_mfma_f32_16x16x32_bf16 v[108:111], v[214:217], v[166:169], v[108:111]
	v_mfma_f32_16x16x32_bf16 v[96:99], v[206:209], v[174:177], v[96:99]
	v_mfma_f32_16x16x32_bf16 v[92:95], v[214:217], v[174:177], v[92:95]
	v_mfma_f32_16x16x32_bf16 v[80:83], v[206:209], v[182:185], v[80:83]
	v_mfma_f32_16x16x32_bf16 v[76:79], v[214:217], v[182:185], v[76:79]
	v_mfma_f32_16x16x32_bf16 v[72:75], v[206:209], v[190:193], v[72:75]
	v_mfma_f32_16x16x32_bf16 v[68:71], v[214:217], v[190:193], v[68:71]
	s_barrier
	ds_read_b128 v[162:165], v144 offset:49152
	ds_read_b128 v[166:169], v144 offset:50176
	ds_read_b128 v[170:173], v144 offset:51200
	ds_read_b128 v[174:177], v144 offset:52224
	ds_read_b128 v[178:181], v144 offset:53248
	ds_read_b128 v[182:185], v144 offset:54272
	s_add_i32 m0, s37, 0x18000
	s_add_u32 s98, s50, 0x80
	s_addc_u32 s99, s51, 0
	global_load_lds_dwordx4 v132, s[98:99]
	s_add_i32 m0, s37, 0x1a000
	ds_read_b128 v[186:189], v144 offset:55296
	global_load_lds_dwordx4 v136, s[98:99]
	s_mov_b32 m0, s59
	s_add_u32 s98, s52, 0x80
	s_addc_u32 s99, s53, 0
	global_load_lds_dwordx4 v0, s[98:99]
	s_mov_b32 m0, s60
	ds_read_b128 v[190:193], v144 offset:56320
	global_load_lds_dwordx4 v134, s[98:99]
	s_add_i32 m0, s37, 0x1c000
	s_add_u32 s24, s50, 0x40080
	s_addc_u32 s25, s51, 0
	global_load_lds_dwordx4 v132, s[24:25]
	s_add_i32 m0, s37, 0x1e000
	s_waitcnt vmcnt(7)
	global_load_lds_dwordx4 v136, s[24:25]
	s_barrier
	s_waitcnt lgkmcnt(0)
	v_mfma_f32_16x16x32_bf16 v[64:67], v[146:149], v[162:165], v[64:67]
	v_mfma_f32_16x16x32_bf16 v[60:63], v[154:157], v[162:165], v[60:63]
	v_mfma_f32_16x16x32_bf16 v[56:59], v[146:149], v[170:173], v[56:59]
	v_mfma_f32_16x16x32_bf16 v[52:55], v[154:157], v[170:173], v[52:55]
	v_mfma_f32_16x16x32_bf16 v[40:43], v[146:149], v[178:181], v[40:43]
	v_mfma_f32_16x16x32_bf16 v[36:39], v[154:157], v[178:181], v[36:39]
	v_mfma_f32_16x16x32_bf16 v[24:27], v[146:149], v[186:189], v[24:27]
	v_mfma_f32_16x16x32_bf16 v[16:19], v[154:157], v[186:189], v[16:19]
	v_mfma_f32_16x16x32_bf16 v[64:67], v[150:153], v[166:169], v[64:67]
	v_mfma_f32_16x16x32_bf16 v[60:63], v[158:161], v[166:169], v[60:63]
	v_mfma_f32_16x16x32_bf16 v[56:59], v[150:153], v[174:177], v[56:59]
	v_mfma_f32_16x16x32_bf16 v[52:55], v[158:161], v[174:177], v[52:55]
	v_mfma_f32_16x16x32_bf16 v[40:43], v[150:153], v[182:185], v[40:43]
	v_mfma_f32_16x16x32_bf16 v[36:39], v[158:161], v[182:185], v[36:39]
	v_mfma_f32_16x16x32_bf16 v[24:27], v[150:153], v[190:193], v[24:27]
	v_mfma_f32_16x16x32_bf16 v[16:19], v[158:161], v[190:193], v[16:19]
	v_mfma_f32_16x16x32_bf16 v[48:51], v[202:205], v[162:165], v[48:51]
	v_mfma_f32_16x16x32_bf16 v[44:47], v[210:213], v[162:165], v[44:47]
	v_mfma_f32_16x16x32_bf16 v[32:35], v[202:205], v[170:173], v[32:35]
	v_mfma_f32_16x16x32_bf16 v[28:31], v[210:213], v[170:173], v[28:31]
	v_mfma_f32_16x16x32_bf16 v[20:23], v[202:205], v[178:181], v[20:23]
	v_mfma_f32_16x16x32_bf16 v[12:15], v[210:213], v[178:181], v[12:15]
	v_mfma_f32_16x16x32_bf16 v[8:11], v[202:205], v[186:189], v[8:11]
	v_mfma_f32_16x16x32_bf16 v[4:7], v[210:213], v[186:189], v[4:7]
	v_mfma_f32_16x16x32_bf16 v[48:51], v[206:209], v[166:169], v[48:51]
	v_mfma_f32_16x16x32_bf16 v[44:47], v[214:217], v[166:169], v[44:47]
	v_mfma_f32_16x16x32_bf16 v[32:35], v[206:209], v[174:177], v[32:35]
	v_mfma_f32_16x16x32_bf16 v[28:31], v[214:217], v[174:177], v[28:31]
	v_mfma_f32_16x16x32_bf16 v[20:23], v[206:209], v[182:185], v[20:23]
	v_mfma_f32_16x16x32_bf16 v[12:15], v[214:217], v[182:185], v[12:15]
	v_mfma_f32_16x16x32_bf16 v[8:11], v[206:209], v[190:193], v[8:11]
	v_mfma_f32_16x16x32_bf16 v[4:7], v[214:217], v[190:193], v[4:7]
	s_add_i32 s22, s22, 2
	s_add_u32 s48, s48, 0x100
	s_addc_u32 s49, s49, 0
	s_add_u32 s20, s20, 0x100
	s_addc_u32 s21, s21, 0
	s_cmp_gt_u32 s22, 13
	s_barrier
	s_cbranch_scc0 .LBB0_136
	v_lshl_add_u32 v146, s0, 8, v142
	v_cvt_pk_bf16_f32 v72, v72, v73
	v_cvt_pk_bf16_f32 v73, v74, v75
	v_cvt_pk_bf16_f32 v74, v68, v69
	v_add_u32_e32 v68, 0x80, v146
	s_lshl_b32 s0, s1, 8
	v_ashrrev_i32_e32 v147, 31, v146
	v_readlane_b32 s20, v252, 12
	v_cvt_pk_bf16_f32 v112, v112, v113
	v_cvt_pk_bf16_f32 v113, v114, v115
	v_cvt_pk_bf16_f32 v114, v108, v109
	v_or_b32_e32 v108, 16, v146
	v_ashrrev_i32_e32 v69, 31, v68
	v_cvt_pk_bf16_f32 v48, v48, v49
	v_cvt_pk_bf16_f32 v49, v50, v51
	v_cvt_pk_bf16_f32 v50, v44, v45
	v_add_u32_e32 v44, 0x90, v146
	s_ashr_i32 s1, s0, 31
	v_lshlrev_b64 v[148:149], 11, v[146:147]
	v_readlane_b32 s21, v252, 13
	v_ashrrev_i32_e32 v109, 31, v108
	v_cvt_pk_bf16_f32 v96, v96, v97
	v_cvt_pk_bf16_f32 v97, v98, v99
	v_cvt_pk_bf16_f32 v98, v92, v93
	v_or_b32_e32 v92, 32, v146
	v_lshlrev_b64 v[68:69], 11, v[68:69]
	v_ashrrev_i32_e32 v45, 31, v44
	v_cvt_pk_bf16_f32 v32, v32, v33
	v_cvt_pk_bf16_f32 v33, v34, v35
	v_cvt_pk_bf16_f32 v34, v28, v29
	v_add_u32_e32 v28, 0xa0, v146
	v_lshl_add_u64 v[148:149], s[20:21], 0, v[148:149]
	s_lshl_b64 s[0:1], s[0:1], 1
	v_lshlrev_b64 v[108:109], 11, v[108:109]
	v_ashrrev_i32_e32 v93, 31, v92
	v_cvt_pk_bf16_f32 v80, v80, v81
	v_cvt_pk_bf16_f32 v81, v82, v83
	v_cvt_pk_bf16_f32 v82, v76, v77
	v_or_b32_e32 v76, 48, v146
	v_lshl_add_u64 v[68:69], s[20:21], 0, v[68:69]
	v_lshlrev_b64 v[44:45], 11, v[44:45]
	v_ashrrev_i32_e32 v29, 31, v28
	v_cvt_pk_bf16_f32 v20, v20, v21
	v_cvt_pk_bf16_f32 v21, v22, v23
	v_cvt_pk_bf16_f32 v22, v12, v13
	v_add_u32_e32 v12, 0xb0, v146
	v_lshl_add_u64 v[148:149], v[148:149], 0, s[0:1]
	v_lshl_add_u64 v[108:109], s[20:21], 0, v[108:109]
	v_lshlrev_b64 v[92:93], 11, v[92:93]
	v_ashrrev_i32_e32 v77, 31, v76
	v_lshl_add_u64 v[68:69], v[68:69], 0, s[0:1]
	v_lshl_add_u64 v[44:45], s[20:21], 0, v[44:45]
	v_lshlrev_b64 v[28:29], 11, v[28:29]
	v_ashrrev_i32_e32 v13, 31, v12
	v_lshl_add_u64 v[148:149], v[148:149], 0, s[72:73]
	v_lshl_add_u64 v[108:109], v[108:109], 0, s[0:1]
	v_lshl_add_u64 v[92:93], s[20:21], 0, v[92:93]
	v_lshlrev_b64 v[76:77], 11, v[76:77]
	v_lshl_add_u64 v[68:69], v[68:69], 0, s[72:73]
	v_lshl_add_u64 v[44:45], v[44:45], 0, s[0:1]
	v_lshl_add_u64 v[28:29], s[20:21], 0, v[28:29]
	v_lshlrev_b64 v[12:13], 11, v[12:13]
	v_lshl_add_u64 v[148:149], v[148:149], 0, v[2:3]
	v_cvt_pk_bf16_f32 v115, v110, v111
	v_lshl_add_u64 v[108:109], v[108:109], 0, s[72:73]
	v_lshl_add_u64 v[92:93], v[92:93], 0, s[0:1]
	v_lshl_add_u64 v[76:77], s[20:21], 0, v[76:77]
	v_lshl_add_u64 v[68:69], v[68:69], 0, v[2:3]
	v_cvt_pk_bf16_f32 v51, v46, v47
	v_lshl_add_u64 v[44:45], v[44:45], 0, s[72:73]
	v_lshl_add_u64 v[28:29], v[28:29], 0, s[0:1]
	v_lshl_add_u64 v[12:13], s[20:21], 0, v[12:13]
	global_store_dwordx4 v[148:149], v[112:115], off offset:256
	v_cvt_pk_bf16_f32 v99, v94, v95
	v_lshl_add_u64 v[92:93], v[92:93], 0, s[72:73]
	v_lshl_add_u64 v[112:113], v[108:109], 0, v[2:3]
	v_lshl_add_u64 v[76:77], v[76:77], 0, s[0:1]
	global_store_dwordx4 v[68:69], v[48:51], off offset:256
	v_cvt_pk_bf16_f32 v35, v30, v31
	v_lshl_add_u64 v[28:29], v[28:29], 0, s[72:73]
	v_lshl_add_u64 v[48:49], v[44:45], 0, v[2:3]
	v_lshl_add_u64 v[12:13], v[12:13], 0, s[0:1]
	global_store_dwordx4 v[112:113], v[96:99], off offset:256
	v_cvt_pk_bf16_f32 v83, v78, v79
	v_lshl_add_u64 v[76:77], v[76:77], 0, s[72:73]
	v_lshl_add_u64 v[96:97], v[92:93], 0, v[2:3]
	global_store_dwordx4 v[48:49], v[32:35], off offset:256
	v_cvt_pk_bf16_f32 v23, v14, v15
	v_lshl_add_u64 v[12:13], v[12:13], 0, s[72:73]
	v_lshl_add_u64 v[32:33], v[28:29], 0, v[2:3]
	v_cvt_pk_bf16_f32 v128, v128, v129
	v_cvt_pk_bf16_f32 v129, v130, v131
	v_cvt_pk_bf16_f32 v130, v124, v125
	v_cvt_pk_bf16_f32 v131, v126, v127
	v_cvt_pk_bf16_f32 v108, v120, v121
	v_cvt_pk_bf16_f32 v109, v122, v123
	v_cvt_pk_bf16_f32 v110, v116, v117
	v_cvt_pk_bf16_f32 v111, v118, v119
	v_cvt_pk_bf16_f32 v92, v104, v105
	v_cvt_pk_bf16_f32 v93, v106, v107
	v_cvt_pk_bf16_f32 v94, v100, v101
	v_cvt_pk_bf16_f32 v95, v102, v103
	global_store_dwordx4 v[96:97], v[80:83], off offset:256
	v_cvt_pk_bf16_f32 v78, v84, v85
	v_cvt_pk_bf16_f32 v79, v86, v87
	v_lshl_add_u64 v[80:81], v[76:77], 0, v[2:3]
	v_cvt_pk_bf16_f32 v76, v88, v89
	v_cvt_pk_bf16_f32 v77, v90, v91
	v_cvt_pk_bf16_f32 v75, v70, v71
	v_cvt_pk_bf16_f32 v64, v64, v65
	v_cvt_pk_bf16_f32 v65, v66, v67
	v_cvt_pk_bf16_f32 v66, v60, v61
	v_cvt_pk_bf16_f32 v67, v62, v63
	v_cvt_pk_bf16_f32 v44, v56, v57
	v_cvt_pk_bf16_f32 v45, v58, v59
	v_cvt_pk_bf16_f32 v46, v52, v53
	v_cvt_pk_bf16_f32 v47, v54, v55
	v_cvt_pk_bf16_f32 v28, v40, v41
	v_cvt_pk_bf16_f32 v29, v42, v43
	v_cvt_pk_bf16_f32 v30, v36, v37
	v_cvt_pk_bf16_f32 v31, v38, v39
	global_store_dwordx4 v[32:33], v[20:23], off offset:256
	v_cvt_pk_bf16_f32 v14, v16, v17
	v_cvt_pk_bf16_f32 v15, v18, v19
	v_lshl_add_u64 v[20:21], v[12:13], 0, v[2:3]
	v_cvt_pk_bf16_f32 v12, v24, v25
	v_cvt_pk_bf16_f32 v13, v26, v27
	v_cvt_pk_bf16_f32 v8, v8, v9
	v_cvt_pk_bf16_f32 v9, v10, v11
	v_cvt_pk_bf16_f32 v10, v4, v5
	v_cvt_pk_bf16_f32 v11, v6, v7
	s_and_b64 vcc, exec, s[38:39]
	s_mov_b32 s1, s40
	s_mov_b32 s0, s42
	s_mov_b64 s[50:51], s[46:47]
	s_mov_b64 s[48:49], s[44:45]
	global_store_dwordx4 v[148:149], v[128:131], off
	global_store_dwordx4 v[112:113], v[108:111], off
	global_store_dwordx4 v[96:97], v[92:95], off
	global_store_dwordx4 v[80:81], v[76:79], off
	global_store_dwordx4 v[80:81], v[72:75], off offset:256
	global_store_dwordx4 v[68:69], v[64:67], off
	global_store_dwordx4 v[48:49], v[44:47], off
	global_store_dwordx4 v[32:33], v[28:31], off
	global_store_dwordx4 v[20:21], v[12:15], off
	global_store_dwordx4 v[20:21], v[8:11], off offset:256
	s_cbranch_vccz .LBB0_129
	s_waitcnt vmcnt(0)
	s_cmpk_gt_u32 s31, 0xff
	s_cbranch_scc1 .LBB0_140
	s_barrier

.LBB0_165:
	s_and_b32 s21, 0xffff, s21
	s_cmp_lg_u32 s21, 0
	s_cselect_b64 s[22:23], -1, 0
	s_cmp_lg_u64 s[22:23], 0
	v_and_b32_e32 v18, 15, v2
	s_addc_u32 s58, s30, 0
	v_lshl_or_b32 v144, s0, 6, v18
	s_lshl_b32 s23, s0, 13
	s_lshl_b32 s0, s1, 5
	s_and_b32 s24, s0, 0x60
	s_add_i32 m0, s53, 0x18000
	v_lshl_add_u64 v[8:9], v[8:9], 0, s[76:77]
	s_lshl_b32 s25, s24, 7
	s_waitcnt vmcnt(2)
	s_barrier
	global_load_lds_dwordx4 v[8:9], off
	v_lshl_add_u64 v[6:7], v[6:7], 0, s[76:77]
	s_add_i32 m0, s53, 0x1a000
	s_add_i32 s59, s53, 0x8000
	s_add_i32 s60, s53, 0xa000
	global_load_lds_dwordx4 v[6:7], off
	v_lshl_add_u64 v[4:5], v[4:5], 0, s[76:77]
	s_mov_b32 m0, s59
	s_add_u32 s0, s44, 0xc0080
	global_load_lds_dwordx4 v[4:5], off
	v_lshl_add_u64 v[0:1], v[0:1], 0, s[76:77]
	s_mov_b32 m0, s60
	s_addc_u32 s1, s45, 0
	global_load_lds_dwordx4 v[0:1], off
	s_add_i32 m0, s53, 0x1c000
	v_lshl_add_u64 v[0:1], s[0:1], 0, v[138:139]
	global_load_lds_dwordx4 v[0:1], off
	v_lshl_add_u64 v[0:1], s[0:1], 0, v[142:143]
	s_add_i32 m0, s53, 0x1e000
	v_lshrrev_b32_e32 v19, 1, v2
	global_load_lds_dwordx4 v[0:1], off
	v_and_b32_e32 v0, 24, v19
	v_lshlrev_b32_e32 v1, 1, v0
	v_lshlrev_b32_e32 v2, 2, v2
	v_lshl_or_b32 v1, v18, 6, v1
	v_and_b32_e32 v2, 32, v2
	s_movk_i32 s3, 0x1a00
	v_bitop3_b32 v4, v1, s23, v2 bitop3:0xde
	v_bitop3_b32 v157, v1, s25, v2 bitop3:0xde
	v_or_b32_e32 v159, s24, v0
	v_lshrrev_b32_e32 v1, 1, v10
	v_mul_lo_u32 v0, v12, s3
	s_mov_b32 s2, 0x1a000
	v_mad_u64_u32 v[0:1], s[0:1], v1, s2, v[0:1]
	v_or_b32_e32 v0, v0, v11
	v_add_lshl_u32 v2, v0, v13, 1
	v_lshrrev_b32_e32 v1, 1, v14
	v_mul_lo_u32 v0, v16, s3
	v_mad_u64_u32 v[0:1], s[0:1], v1, s2, v[0:1]
	s_mov_b64 s[4:5], 0x1a0080
	v_or_b32_e32 v0, v0, v15
	v_lshl_add_u64 v[160:161], v[2:3], 0, s[4:5]
	v_add_lshl_u32 v2, v0, v17, 1
	s_waitcnt vmcnt(6)
	v_lshl_add_u64 v[162:163], v[2:3], 0, s[4:5]
	v_mov_b32_e32 v2, v3
	v_or_b32_e32 v148, 32, v144
	v_or_b32_e32 v150, 48, v144
	v_add_u32_e32 v152, 0x80, v144
	v_add_u32_e32 v154, 0x90, v144
	v_add_u32_e32 v156, 0xa0, v144
	v_add_u32_e32 v158, 0xb0, v144
	v_mov_b32_e32 v0, v3
	v_mov_b32_e32 v1, v3
	v_add_u32_e32 v172, 0, v4
	v_mov_b64_e32 v[22:23], v[2:3]
	v_mov_b64_e32 v[26:27], v[2:3]
	v_mov_b64_e32 v[30:31], v[2:3]
	v_mov_b64_e32 v[34:35], v[2:3]
	v_mov_b64_e32 v[38:39], v[2:3]
	v_mov_b64_e32 v[42:43], v[2:3]
	v_mov_b64_e32 v[46:47], v[2:3]
	v_mov_b64_e32 v[50:51], v[2:3]
	v_mov_b64_e32 v[54:55], v[2:3]
	v_mov_b64_e32 v[58:59], v[2:3]
	v_mov_b64_e32 v[62:63], v[2:3]
	v_mov_b64_e32 v[66:67], v[2:3]
	v_mov_b64_e32 v[70:71], v[2:3]
	v_mov_b64_e32 v[74:75], v[2:3]
	v_mov_b64_e32 v[78:79], v[2:3]
	v_mov_b64_e32 v[82:83], v[2:3]
	v_mov_b64_e32 v[86:87], v[2:3]
	v_mov_b64_e32 v[90:91], v[2:3]
	v_mov_b64_e32 v[94:95], v[2:3]
	v_mov_b64_e32 v[98:99], v[2:3]
	v_mov_b64_e32 v[102:103], v[2:3]
	v_mov_b64_e32 v[106:107], v[2:3]
	v_mov_b64_e32 v[18:19], v[2:3]
	v_mov_b64_e32 v[14:15], v[2:3]
	v_mov_b64_e32 v[110:111], v[2:3]
	v_mov_b64_e32 v[114:115], v[2:3]
	v_mov_b64_e32 v[118:119], v[2:3]
	v_mov_b64_e32 v[122:123], v[2:3]
	v_mov_b64_e32 v[126:127], v[2:3]
	v_mov_b64_e32 v[130:131], v[2:3]
	v_mov_b64_e32 v[10:11], v[2:3]
	v_mov_b64_e32 v[6:7], v[2:3]
	s_mov_b32 s57, 0
	s_mov_b32 s21, 1
	s_mov_b32 s22, 32
	v_or_b32_e32 v146, 16, v144
	v_ashrrev_i32_e32 v145, 31, v148
	v_ashrrev_i32_e32 v147, 31, v150
	v_ashrrev_i32_e32 v149, 31, v152
	v_ashrrev_i32_e32 v151, 31, v154
	v_ashrrev_i32_e32 v153, 31, v156
	v_ashrrev_i32_e32 v155, 31, v158
	s_ashr_i32 s61, s50, 31
	v_mov_b64_e32 v[20:21], v[0:1]
	v_mov_b64_e32 v[24:25], v[0:1]
	v_mov_b64_e32 v[28:29], v[0:1]
	v_mov_b64_e32 v[32:33], v[0:1]
	v_mov_b64_e32 v[36:37], v[0:1]
	v_mov_b64_e32 v[40:41], v[0:1]
	v_mov_b64_e32 v[44:45], v[0:1]
	v_mov_b64_e32 v[48:49], v[0:1]
	v_mov_b64_e32 v[52:53], v[0:1]
	v_mov_b64_e32 v[56:57], v[0:1]
	v_mov_b64_e32 v[60:61], v[0:1]
	v_mov_b64_e32 v[64:65], v[0:1]
	v_mov_b64_e32 v[68:69], v[0:1]
	v_mov_b64_e32 v[72:73], v[0:1]
	v_mov_b64_e32 v[76:77], v[0:1]
	v_mov_b64_e32 v[80:81], v[0:1]
	v_mov_b64_e32 v[84:85], v[0:1]
	v_mov_b64_e32 v[88:89], v[0:1]
	v_mov_b64_e32 v[92:93], v[0:1]
	v_mov_b64_e32 v[96:97], v[0:1]
	v_mov_b64_e32 v[100:101], v[0:1]
	v_mov_b64_e32 v[104:105], v[0:1]
	v_mov_b64_e32 v[16:17], v[0:1]
	v_mov_b64_e32 v[12:13], v[0:1]
	v_mov_b64_e32 v[108:109], v[0:1]
	v_mov_b64_e32 v[112:113], v[0:1]
	v_mov_b64_e32 v[116:117], v[0:1]
	v_mov_b64_e32 v[120:121], v[0:1]
	v_mov_b64_e32 v[124:125], v[0:1]
	v_mov_b64_e32 v[128:129], v[0:1]
	v_mov_b64_e32 v[8:9], v[0:1]
	v_mov_b64_e32 v[4:5], v[0:1]
	s_mov_b64 s[0:1], s[40:41]
	s_mov_b64 s[42:43], s[44:45]
	s_barrier
	s_branch .LBB0_168

.LBB0_175:
	s_add_i32 s26, s27, 2
	s_add_u32 s44, s40, 0x100
	s_addc_u32 s45, s41, 0
	ds_read_b128 v[132:135], v1
	ds_read_b128 v[164:167], v1 offset:1024
	ds_read_b128 v[168:171], v1 offset:2048
	ds_read_b128 v[174:177], v1 offset:3072
	s_cmp_eq_u32 s23, s27
	s_cselect_b32 s49, s1, s45
	s_cselect_b32 s48, s0, s44
	s_cselect_b32 s47, s43, s25
	s_cselect_b32 s46, s42, s24
	s_add_i32 m0, s53, 0xc000
	ds_read_b128 v[178:181], v172
	ds_read_b128 v[182:185], v172 offset:1024
	ds_read_b128 v[186:189], v172 offset:2048
	ds_read_b128 v[190:193], v172 offset:3072
	ds_read_b128 v[202:205], v172 offset:4096
	ds_read_b128 v[206:209], v172 offset:5120
	ds_read_b128 v[210:213], v172 offset:6144
	global_load_lds_dwordx4 v160, s[40:41]
	s_add_i32 m0, s53, 0xe000
	ds_read_b128 v[214:217], v172 offset:7168
	global_load_lds_dwordx4 v162, s[40:41]
	ds_read_b128 v[236:239], v1 offset:16384
	ds_read_b128 v[240:243], v1 offset:17408
	ds_read_b128 v[244:247], v1 offset:18432
	ds_read_b128 v[248:251], v1 offset:19456
	s_waitcnt vmcnt(8)
	s_barrier
	s_waitcnt lgkmcnt(0)
	v_mfma_f32_16x16x32_bf16 v[4:7], v[132:135], v[178:181], v[4:7]
	v_mfma_f32_16x16x32_bf16 v[8:11], v[168:171], v[178:181], v[8:11]
	v_mfma_f32_16x16x32_bf16 v[128:131], v[132:135], v[186:189], v[128:131]
	v_mfma_f32_16x16x32_bf16 v[124:127], v[168:171], v[186:189], v[124:127]
	v_mfma_f32_16x16x32_bf16 v[120:123], v[132:135], v[202:205], v[120:123]
	v_mfma_f32_16x16x32_bf16 v[116:119], v[168:171], v[202:205], v[116:119]
	v_mfma_f32_16x16x32_bf16 v[112:115], v[132:135], v[210:213], v[112:115]
	v_mfma_f32_16x16x32_bf16 v[108:111], v[168:171], v[210:213], v[108:111]
	v_mfma_f32_16x16x32_bf16 v[4:7], v[164:167], v[182:185], v[4:7]
	v_mfma_f32_16x16x32_bf16 v[8:11], v[174:177], v[182:185], v[8:11]
	v_mfma_f32_16x16x32_bf16 v[128:131], v[164:167], v[190:193], v[128:131]
	v_mfma_f32_16x16x32_bf16 v[124:127], v[174:177], v[190:193], v[124:127]
	v_mfma_f32_16x16x32_bf16 v[120:123], v[164:167], v[206:209], v[120:123]
	v_mfma_f32_16x16x32_bf16 v[116:119], v[174:177], v[206:209], v[116:119]
	v_mfma_f32_16x16x32_bf16 v[112:115], v[164:167], v[214:217], v[112:115]
	v_mfma_f32_16x16x32_bf16 v[108:111], v[174:177], v[214:217], v[108:111]
	v_mfma_f32_16x16x32_bf16 v[12:15], v[236:239], v[178:181], v[12:15]
	v_mfma_f32_16x16x32_bf16 v[16:19], v[244:247], v[178:181], v[16:19]
	v_mfma_f32_16x16x32_bf16 v[104:107], v[236:239], v[186:189], v[104:107]
	v_mfma_f32_16x16x32_bf16 v[100:103], v[244:247], v[186:189], v[100:103]
	v_mfma_f32_16x16x32_bf16 v[96:99], v[236:239], v[202:205], v[96:99]
	v_mfma_f32_16x16x32_bf16 v[92:95], v[244:247], v[202:205], v[92:95]
	v_mfma_f32_16x16x32_bf16 v[88:91], v[236:239], v[210:213], v[88:91]
	v_mfma_f32_16x16x32_bf16 v[84:87], v[244:247], v[210:213], v[84:87]
	v_mfma_f32_16x16x32_bf16 v[12:15], v[240:243], v[182:185], v[12:15]
	v_mfma_f32_16x16x32_bf16 v[16:19], v[248:251], v[182:185], v[16:19]
	v_mfma_f32_16x16x32_bf16 v[104:107], v[240:243], v[190:193], v[104:107]
	v_mfma_f32_16x16x32_bf16 v[100:103], v[248:251], v[190:193], v[100:103]
	v_mfma_f32_16x16x32_bf16 v[96:99], v[240:243], v[206:209], v[96:99]
	v_mfma_f32_16x16x32_bf16 v[92:95], v[248:251], v[206:209], v[92:95]
	v_mfma_f32_16x16x32_bf16 v[88:91], v[240:243], v[214:217], v[88:91]
	v_mfma_f32_16x16x32_bf16 v[84:87], v[248:251], v[214:217], v[84:87]
	s_barrier
	ds_read_b128 v[178:181], v172 offset:16384
	ds_read_b128 v[182:185], v172 offset:17408
	ds_read_b128 v[186:189], v172 offset:18432
	ds_read_b128 v[190:193], v172 offset:19456
	s_add_i32 m0, s52, 0x10000
	ds_read_b128 v[202:205], v172 offset:20480
	global_load_lds_dwordx4 v138, s[46:47]
	s_add_i32 m0, s52, 0x12000
	ds_read_b128 v[206:209], v172 offset:21504
	global_load_lds_dwordx4 v142, s[46:47]
	s_mov_b32 m0, s53
	ds_read_b128 v[210:213], v172 offset:22528
	global_load_lds_dwordx4 v136, s[48:49]
	s_mov_b32 m0, s54
	ds_read_b128 v[214:217], v172 offset:23552
	global_load_lds_dwordx4 v140, s[48:49]
	s_add_i32 m0, s52, 0x14000
	s_add_u32 s30, s46, 0xc0000
	s_addc_u32 s31, s47, 0
	global_load_lds_dwordx4 v138, s[30:31]
	s_add_i32 m0, s52, 0x16000
	s_waitcnt vmcnt(7)
	global_load_lds_dwordx4 v142, s[30:31]
	s_barrier
	s_waitcnt lgkmcnt(0)
	v_mfma_f32_16x16x32_bf16 v[80:83], v[132:135], v[178:181], v[80:83]
	v_mfma_f32_16x16x32_bf16 v[76:79], v[168:171], v[178:181], v[76:79]
	v_mfma_f32_16x16x32_bf16 v[72:75], v[132:135], v[186:189], v[72:75]
	v_mfma_f32_16x16x32_bf16 v[68:71], v[168:171], v[186:189], v[68:71]
	v_mfma_f32_16x16x32_bf16 v[64:67], v[132:135], v[202:205], v[64:67]
	v_mfma_f32_16x16x32_bf16 v[60:63], v[168:171], v[202:205], v[60:63]
	v_mfma_f32_16x16x32_bf16 v[56:59], v[132:135], v[210:213], v[56:59]
	v_mfma_f32_16x16x32_bf16 v[52:55], v[168:171], v[210:213], v[52:55]
	v_mfma_f32_16x16x32_bf16 v[80:83], v[164:167], v[182:185], v[80:83]
	v_mfma_f32_16x16x32_bf16 v[76:79], v[174:177], v[182:185], v[76:79]
	v_mfma_f32_16x16x32_bf16 v[72:75], v[164:167], v[190:193], v[72:75]
	v_mfma_f32_16x16x32_bf16 v[68:71], v[174:177], v[190:193], v[68:71]
	v_mfma_f32_16x16x32_bf16 v[64:67], v[164:167], v[206:209], v[64:67]
	v_mfma_f32_16x16x32_bf16 v[60:63], v[174:177], v[206:209], v[60:63]
	v_mfma_f32_16x16x32_bf16 v[56:59], v[164:167], v[214:217], v[56:59]
	v_mfma_f32_16x16x32_bf16 v[52:55], v[174:177], v[214:217], v[52:55]
	v_mfma_f32_16x16x32_bf16 v[48:51], v[236:239], v[178:181], v[48:51]
	v_mfma_f32_16x16x32_bf16 v[44:47], v[244:247], v[178:181], v[44:47]
	v_mfma_f32_16x16x32_bf16 v[40:43], v[236:239], v[186:189], v[40:43]
	v_mfma_f32_16x16x32_bf16 v[36:39], v[244:247], v[186:189], v[36:39]
	v_mfma_f32_16x16x32_bf16 v[32:35], v[236:239], v[202:205], v[32:35]
	v_mfma_f32_16x16x32_bf16 v[28:31], v[244:247], v[202:205], v[28:31]
	v_mfma_f32_16x16x32_bf16 v[24:27], v[236:239], v[210:213], v[24:27]
	v_mfma_f32_16x16x32_bf16 v[20:23], v[244:247], v[210:213], v[20:23]
	v_mfma_f32_16x16x32_bf16 v[48:51], v[240:243], v[182:185], v[48:51]
	v_mfma_f32_16x16x32_bf16 v[44:47], v[248:251], v[182:185], v[44:47]
	v_mfma_f32_16x16x32_bf16 v[40:43], v[240:243], v[190:193], v[40:43]
	v_mfma_f32_16x16x32_bf16 v[36:39], v[248:251], v[190:193], v[36:39]
	v_mfma_f32_16x16x32_bf16 v[32:35], v[240:243], v[206:209], v[32:35]
	v_mfma_f32_16x16x32_bf16 v[28:31], v[248:251], v[206:209], v[28:31]
	v_mfma_f32_16x16x32_bf16 v[24:27], v[240:243], v[214:217], v[24:27]
	v_mfma_f32_16x16x32_bf16 v[20:23], v[248:251], v[214:217], v[20:23]
	s_barrier
	ds_read_b128 v[132:135], v1 offset:32768
	ds_read_b128 v[164:167], v1 offset:33792
	ds_read_b128 v[168:171], v1 offset:34816
	ds_read_b128 v[174:177], v1 offset:35840
	s_add_u32 s30, s48, 0x1a0000
	s_addc_u32 s31, s49, 0
	s_mov_b32 m0, s55
	ds_read_b128 v[178:181], v172 offset:32768
	ds_read_b128 v[182:185], v172 offset:33792
	ds_read_b128 v[186:189], v172 offset:34816
	ds_read_b128 v[190:193], v172 offset:35840
	ds_read_b128 v[202:205], v172 offset:36864
	ds_read_b128 v[206:209], v172 offset:37888
	ds_read_b128 v[210:213], v172 offset:38912
	global_load_lds_dwordx4 v136, s[30:31]
	s_mov_b32 m0, s56
	ds_read_b128 v[214:217], v172 offset:39936
	global_load_lds_dwordx4 v140, s[30:31]
	ds_read_b128 v[236:239], v1 offset:49152
	ds_read_b128 v[240:243], v1 offset:50176
	ds_read_b128 v[244:247], v1 offset:51200
	ds_read_b128 v[248:251], v1 offset:52224
	s_waitcnt vmcnt(8)
	s_barrier
	s_waitcnt lgkmcnt(0)
	v_mfma_f32_16x16x32_bf16 v[4:7], v[132:135], v[178:181], v[4:7]
	v_mfma_f32_16x16x32_bf16 v[8:11], v[168:171], v[178:181], v[8:11]
	v_mfma_f32_16x16x32_bf16 v[128:131], v[132:135], v[186:189], v[128:131]
	v_mfma_f32_16x16x32_bf16 v[124:127], v[168:171], v[186:189], v[124:127]
	v_mfma_f32_16x16x32_bf16 v[120:123], v[132:135], v[202:205], v[120:123]
	v_mfma_f32_16x16x32_bf16 v[116:119], v[168:171], v[202:205], v[116:119]
	v_mfma_f32_16x16x32_bf16 v[112:115], v[132:135], v[210:213], v[112:115]
	v_mfma_f32_16x16x32_bf16 v[108:111], v[168:171], v[210:213], v[108:111]
	v_mfma_f32_16x16x32_bf16 v[4:7], v[164:167], v[182:185], v[4:7]
	v_mfma_f32_16x16x32_bf16 v[8:11], v[174:177], v[182:185], v[8:11]
	v_mfma_f32_16x16x32_bf16 v[128:131], v[164:167], v[190:193], v[128:131]
	v_mfma_f32_16x16x32_bf16 v[124:127], v[174:177], v[190:193], v[124:127]
	v_mfma_f32_16x16x32_bf16 v[120:123], v[164:167], v[206:209], v[120:123]
	v_mfma_f32_16x16x32_bf16 v[116:119], v[174:177], v[206:209], v[116:119]
	v_mfma_f32_16x16x32_bf16 v[112:115], v[164:167], v[214:217], v[112:115]
	v_mfma_f32_16x16x32_bf16 v[108:111], v[174:177], v[214:217], v[108:111]
	v_mfma_f32_16x16x32_bf16 v[12:15], v[236:239], v[178:181], v[12:15]
	v_mfma_f32_16x16x32_bf16 v[16:19], v[244:247], v[178:181], v[16:19]
	v_mfma_f32_16x16x32_bf16 v[104:107], v[236:239], v[186:189], v[104:107]
	v_mfma_f32_16x16x32_bf16 v[100:103], v[244:247], v[186:189], v[100:103]
	v_mfma_f32_16x16x32_bf16 v[96:99], v[236:239], v[202:205], v[96:99]
	v_mfma_f32_16x16x32_bf16 v[92:95], v[244:247], v[202:205], v[92:95]
	v_mfma_f32_16x16x32_bf16 v[88:91], v[236:239], v[210:213], v[88:91]
	v_mfma_f32_16x16x32_bf16 v[84:87], v[244:247], v[210:213], v[84:87]
	v_mfma_f32_16x16x32_bf16 v[12:15], v[240:243], v[182:185], v[12:15]
	v_mfma_f32_16x16x32_bf16 v[16:19], v[248:251], v[182:185], v[16:19]
	v_mfma_f32_16x16x32_bf16 v[104:107], v[240:243], v[190:193], v[104:107]
	v_mfma_f32_16x16x32_bf16 v[100:103], v[248:251], v[190:193], v[100:103]
	v_mfma_f32_16x16x32_bf16 v[96:99], v[240:243], v[206:209], v[96:99]
	v_mfma_f32_16x16x32_bf16 v[92:95], v[248:251], v[206:209], v[92:95]
	v_mfma_f32_16x16x32_bf16 v[88:91], v[240:243], v[214:217], v[88:91]
	v_mfma_f32_16x16x32_bf16 v[84:87], v[248:251], v[214:217], v[84:87]
	s_barrier
	ds_read_b128 v[178:181], v172 offset:49152
	ds_read_b128 v[182:185], v172 offset:50176
	ds_read_b128 v[186:189], v172 offset:51200
	ds_read_b128 v[190:193], v172 offset:52224
	ds_read_b128 v[202:205], v172 offset:53248
	ds_read_b128 v[206:209], v172 offset:54272
	s_add_i32 m0, s52, 0x18000
	s_add_u32 s98, s46, 0x80
	s_addc_u32 s99, s47, 0
	global_load_lds_dwordx4 v138, s[98:99]
	s_add_i32 m0, s52, 0x1a000
	ds_read_b128 v[210:213], v172 offset:55296
	global_load_lds_dwordx4 v142, s[98:99]
	s_mov_b32 m0, s59
	s_add_u32 s98, s48, 0x80
	s_addc_u32 s99, s49, 0
	global_load_lds_dwordx4 v136, s[98:99]
	s_mov_b32 m0, s60
	ds_read_b128 v[214:217], v172 offset:56320
	global_load_lds_dwordx4 v140, s[98:99]
	s_add_i32 m0, s52, 0x1c000
	s_add_u32 s30, s46, 0xc0080
	s_addc_u32 s31, s47, 0
	global_load_lds_dwordx4 v138, s[30:31]
	s_add_i32 m0, s52, 0x1e000
	s_waitcnt vmcnt(7)
	global_load_lds_dwordx4 v142, s[30:31]
	s_barrier
	s_waitcnt lgkmcnt(0)
	v_mfma_f32_16x16x32_bf16 v[80:83], v[132:135], v[178:181], v[80:83]
	v_mfma_f32_16x16x32_bf16 v[76:79], v[168:171], v[178:181], v[76:79]
	v_mfma_f32_16x16x32_bf16 v[72:75], v[132:135], v[186:189], v[72:75]
	v_mfma_f32_16x16x32_bf16 v[68:71], v[168:171], v[186:189], v[68:71]
	v_mfma_f32_16x16x32_bf16 v[64:67], v[132:135], v[202:205], v[64:67]
	v_mfma_f32_16x16x32_bf16 v[60:63], v[168:171], v[202:205], v[60:63]
	v_mfma_f32_16x16x32_bf16 v[56:59], v[132:135], v[210:213], v[56:59]
	v_mfma_f32_16x16x32_bf16 v[52:55], v[168:171], v[210:213], v[52:55]
	v_mfma_f32_16x16x32_bf16 v[80:83], v[164:167], v[182:185], v[80:83]
	v_mfma_f32_16x16x32_bf16 v[76:79], v[174:177], v[182:185], v[76:79]
	v_mfma_f32_16x16x32_bf16 v[72:75], v[164:167], v[190:193], v[72:75]
	v_mfma_f32_16x16x32_bf16 v[68:71], v[174:177], v[190:193], v[68:71]
	v_mfma_f32_16x16x32_bf16 v[64:67], v[164:167], v[206:209], v[64:67]
	v_mfma_f32_16x16x32_bf16 v[60:63], v[174:177], v[206:209], v[60:63]
	v_mfma_f32_16x16x32_bf16 v[56:59], v[164:167], v[214:217], v[56:59]
	v_mfma_f32_16x16x32_bf16 v[52:55], v[174:177], v[214:217], v[52:55]
	v_mfma_f32_16x16x32_bf16 v[48:51], v[236:239], v[178:181], v[48:51]
	v_mfma_f32_16x16x32_bf16 v[44:47], v[244:247], v[178:181], v[44:47]
	v_mfma_f32_16x16x32_bf16 v[40:43], v[236:239], v[186:189], v[40:43]
	v_mfma_f32_16x16x32_bf16 v[36:39], v[244:247], v[186:189], v[36:39]
	v_mfma_f32_16x16x32_bf16 v[32:35], v[236:239], v[202:205], v[32:35]
	v_mfma_f32_16x16x32_bf16 v[28:31], v[244:247], v[202:205], v[28:31]
	v_mfma_f32_16x16x32_bf16 v[24:27], v[236:239], v[210:213], v[24:27]
	v_mfma_f32_16x16x32_bf16 v[20:23], v[244:247], v[210:213], v[20:23]
	v_mfma_f32_16x16x32_bf16 v[48:51], v[240:243], v[182:185], v[48:51]
	v_mfma_f32_16x16x32_bf16 v[44:47], v[248:251], v[182:185], v[44:47]
	v_mfma_f32_16x16x32_bf16 v[40:43], v[240:243], v[190:193], v[40:43]
	v_mfma_f32_16x16x32_bf16 v[36:39], v[248:251], v[190:193], v[36:39]
	v_mfma_f32_16x16x32_bf16 v[32:35], v[240:243], v[206:209], v[32:35]
	v_mfma_f32_16x16x32_bf16 v[28:31], v[248:251], v[206:209], v[28:31]
	v_mfma_f32_16x16x32_bf16 v[24:27], v[240:243], v[214:217], v[24:27]
	v_mfma_f32_16x16x32_bf16 v[20:23], v[248:251], v[214:217], v[20:23]
	s_add_u32 s24, s24, 0x100
	s_addc_u32 s25, s25, 0
	s_cmp_ge_i32 s26, s22
	s_mov_b64 s[40:41], s[44:45]
	s_mov_b32 s27, s26
	s_barrier
	s_cbranch_scc0 .LBB0_175
	s_lshl_b32 s46, s66, 8
	v_lshl_or_b32 v0, s20, 8, v159
	s_mov_b32 s44, 0xbfb8aa3b
	s_mov_b32 s45, 0xbfb8aa3b
	v_lshlrev_b32_e32 v0, 1, v0
	v_add_u32_e32 v0, 0x1000, v0
	s_cmp_lg_u32 s21, 1
	s_cbranch_scc0 .Lg2_kind1
	v_readlane_b32 s22, v252, 34
	v_readlane_b32 s23, v252, 35
	v_add_u32_e32 v2, s46, v144
	v_mad_u32_u24 v2, v2, s29, v0
	global_load_dwordx4 v[132:135], v2, s[96:97] offset:2048
	v_add_u32_e32 v2, s46, v144
	v_mad_u32_u24 v2, v2, s29, v0
	global_load_dwordx4 v[178:181], v2, s[96:97] offset:2304
	v_add_u32_e32 v2, s46, v146
	v_mad_u32_u24 v2, v2, s29, v0
	global_load_dwordx4 v[182:185], v2, s[96:97] offset:2048
	v_add_u32_e32 v2, s46, v146
	v_mad_u32_u24 v2, v2, s29, v0
	global_load_dwordx4 v[186:189], v2, s[96:97] offset:2304
	v_add_u32_e32 v2, s46, v148
	v_mad_u32_u24 v2, v2, s29, v0
	global_load_dwordx4 v[190:193], v2, s[96:97] offset:2048
	v_add_u32_e32 v2, s46, v148
	v_mad_u32_u24 v2, v2, s29, v0
	global_load_dwordx4 v[202:205], v2, s[96:97] offset:2304
	v_add_u32_e32 v2, s46, v150
	v_mad_u32_u24 v2, v2, s29, v0
	global_load_dwordx4 v[206:209], v2, s[96:97] offset:2048
	v_add_u32_e32 v2, s46, v150
	v_mad_u32_u24 v2, v2, s29, v0
	global_load_dwordx4 v[210:213], v2, s[96:97] offset:2304
	v_add_u32_e32 v2, s46, v152
	v_mad_u32_u24 v2, v2, s29, v0
	global_load_dwordx4 v[214:217], v2, s[96:97] offset:2048
	v_add_u32_e32 v2, s46, v152
	v_mad_u32_u24 v2, v2, s29, v0
	global_load_dwordx4 v[236:239], v2, s[96:97] offset:2304
	v_add_u32_e32 v2, s46, v154
	v_mad_u32_u24 v2, v2, s29, v0
	global_load_dwordx4 v[240:243], v2, s[96:97] offset:2048
	v_add_u32_e32 v2, s46, v154
	v_mad_u32_u24 v2, v2, s29, v0
	global_load_dwordx4 v[244:247], v2, s[96:97] offset:2304
	v_add_u32_e32 v2, s46, v156
	v_mad_u32_u24 v2, v2, s29, v0
	global_load_dwordx4 v[248:251], v2, s[96:97] offset:2048
	s_waitcnt vmcnt(12)
	v_lshlrev_b32_e32 v164, 16, v132
	v_and_b32_e32 v165, 0xffff0000, v132
	v_lshlrev_b32_e32 v166, 16, v133
	v_and_b32_e32 v167, 0xffff0000, v133
	v_lshlrev_b32_e32 v168, 16, v134
	v_and_b32_e32 v169, 0xffff0000, v134
	v_lshlrev_b32_e32 v170, 16, v135
	v_and_b32_e32 v171, 0xffff0000, v135
	v_add_u32_e32 v2, s46, v156
	v_mad_u32_u24 v2, v2, s29, v0
	global_load_dwordx4 v[132:135], v2, s[96:97] offset:2304
	v_add_u32_e32 v1, s46, v144
	v_lshl_add_u32 v1, v1, 11, v0
	v_med3_f32 v164, v164, s34, v227
	v_med3_f32 v165, v165, s34, v227
	v_med3_f32 v166, v166, s34, v227
	v_med3_f32 v167, v167, s34, v227
	v_med3_f32 v168, v168, s34, v227
	v_med3_f32 v169, v169, s34, v227
	v_med3_f32 v170, v170, s34, v227
	v_med3_f32 v171, v171, s34, v227
	v_pk_mul_f32 v[164:165], v[164:165], s[44:45]
	v_pk_mul_f32 v[166:167], v[166:167], s[44:45]
	v_pk_mul_f32 v[168:169], v[168:169], s[44:45]
	v_pk_mul_f32 v[170:171], v[170:171], s[44:45]
	v_exp_f32_e32 v164, v164
	v_exp_f32_e32 v165, v165
	v_exp_f32_e32 v166, v166
	v_exp_f32_e32 v167, v167
	v_exp_f32_e32 v168, v168
	v_exp_f32_e32 v169, v169
	v_exp_f32_e32 v170, v170
	v_exp_f32_e32 v171, v171
	v_pk_add_f32 v[164:165], v[164:165], 1.0 op_sel_hi:[1,0]
	v_pk_add_f32 v[166:167], v[166:167], 1.0 op_sel_hi:[1,0]
	v_pk_add_f32 v[168:169], v[168:169], 1.0 op_sel_hi:[1,0]
	v_pk_add_f32 v[170:171], v[170:171], 1.0 op_sel_hi:[1,0]
	v_rcp_f32_e32 v164, v164
	v_rcp_f32_e32 v165, v165
	v_rcp_f32_e32 v166, v166
	v_rcp_f32_e32 v167, v167
	v_rcp_f32_e32 v168, v168
	v_rcp_f32_e32 v169, v169
	v_rcp_f32_e32 v170, v170
	v_rcp_f32_e32 v171, v171
	v_pk_mul_f32 v[164:165], v[4:5], v[164:165]
	v_pk_mul_f32 v[166:167], v[6:7], v[166:167]
	v_pk_mul_f32 v[168:169], v[8:9], v[168:169]
	v_pk_mul_f32 v[170:171], v[10:11], v[170:171]
	v_cvt_pk_bf16_f32 v174, v164, v165
	v_cvt_pk_bf16_f32 v175, v166, v167
	v_cvt_pk_bf16_f32 v176, v168, v169
	v_cvt_pk_bf16_f32 v177, v170, v171
	global_store_dwordx4 v1, v[174:177], s[22:23] offset:-4096
	s_waitcnt vmcnt(13)
	v_lshlrev_b32_e32 v164, 16, v178
	v_and_b32_e32 v165, 0xffff0000, v178
	v_lshlrev_b32_e32 v166, 16, v179
	v_and_b32_e32 v167, 0xffff0000, v179
	v_lshlrev_b32_e32 v168, 16, v180
	v_and_b32_e32 v169, 0xffff0000, v180
	v_lshlrev_b32_e32 v170, 16, v181
	v_and_b32_e32 v171, 0xffff0000, v181
	v_add_u32_e32 v2, s46, v158
	v_mad_u32_u24 v2, v2, s29, v0
	global_load_dwordx4 v[178:181], v2, s[96:97] offset:2048
	v_med3_f32 v164, v164, s34, v227
	v_med3_f32 v165, v165, s34, v227
	v_med3_f32 v166, v166, s34, v227
	v_med3_f32 v167, v167, s34, v227
	v_med3_f32 v168, v168, s34, v227
	v_med3_f32 v169, v169, s34, v227
	v_med3_f32 v170, v170, s34, v227
	v_med3_f32 v171, v171, s34, v227
	v_pk_mul_f32 v[164:165], v[164:165], s[44:45]
	v_pk_mul_f32 v[166:167], v[166:167], s[44:45]
	v_pk_mul_f32 v[168:169], v[168:169], s[44:45]
	v_pk_mul_f32 v[170:171], v[170:171], s[44:45]
	v_exp_f32_e32 v164, v164
	v_exp_f32_e32 v165, v165
	v_exp_f32_e32 v166, v166
	v_exp_f32_e32 v167, v167
	v_exp_f32_e32 v168, v168
	v_exp_f32_e32 v169, v169
	v_exp_f32_e32 v170, v170
	v_exp_f32_e32 v171, v171
	v_pk_add_f32 v[164:165], v[164:165], 1.0 op_sel_hi:[1,0]
	v_pk_add_f32 v[166:167], v[166:167], 1.0 op_sel_hi:[1,0]
	v_pk_add_f32 v[168:169], v[168:169], 1.0 op_sel_hi:[1,0]
	v_pk_add_f32 v[170:171], v[170:171], 1.0 op_sel_hi:[1,0]
	v_rcp_f32_e32 v164, v164
	v_rcp_f32_e32 v165, v165
	v_rcp_f32_e32 v166, v166
	v_rcp_f32_e32 v167, v167
	v_rcp_f32_e32 v168, v168
	v_rcp_f32_e32 v169, v169
	v_rcp_f32_e32 v170, v170
	v_rcp_f32_e32 v171, v171
	v_pk_mul_f32 v[164:165], v[12:13], v[164:165]
	v_pk_mul_f32 v[166:167], v[14:15], v[166:167]
	v_pk_mul_f32 v[168:169], v[16:17], v[168:169]
	v_pk_mul_f32 v[170:171], v[18:19], v[170:171]
	v_cvt_pk_bf16_f32 v174, v164, v165
	v_cvt_pk_bf16_f32 v175, v166, v167
	v_cvt_pk_bf16_f32 v176, v168, v169
	v_cvt_pk_bf16_f32 v177, v170, v171
	global_store_dwordx4 v1, v[174:177], s[22:23] offset:-3840
	s_waitcnt vmcnt(14)
	v_lshlrev_b32_e32 v164, 16, v182
	v_and_b32_e32 v165, 0xffff0000, v182
	v_lshlrev_b32_e32 v166, 16, v183
	v_and_b32_e32 v167, 0xffff0000, v183
	v_lshlrev_b32_e32 v168, 16, v184
	v_and_b32_e32 v169, 0xffff0000, v184
	v_lshlrev_b32_e32 v170, 16, v185
	v_and_b32_e32 v171, 0xffff0000, v185
	v_add_u32_e32 v2, s46, v158
	v_mad_u32_u24 v2, v2, s29, v0
	global_load_dwordx4 v[182:185], v2, s[96:97] offset:2304
	v_add_u32_e32 v1, s46, v146
	v_lshl_add_u32 v1, v1, 11, v0
	v_med3_f32 v164, v164, s34, v227
	v_med3_f32 v165, v165, s34, v227
	v_med3_f32 v166, v166, s34, v227
	v_med3_f32 v167, v167, s34, v227
	v_med3_f32 v168, v168, s34, v227
	v_med3_f32 v169, v169, s34, v227
	v_med3_f32 v170, v170, s34, v227
	v_med3_f32 v171, v171, s34, v227
	v_pk_mul_f32 v[164:165], v[164:165], s[44:45]
	v_pk_mul_f32 v[166:167], v[166:167], s[44:45]
	v_pk_mul_f32 v[168:169], v[168:169], s[44:45]
	v_pk_mul_f32 v[170:171], v[170:171], s[44:45]
	v_exp_f32_e32 v164, v164
	v_exp_f32_e32 v165, v165
	v_exp_f32_e32 v166, v166
	v_exp_f32_e32 v167, v167
	v_exp_f32_e32 v168, v168
	v_exp_f32_e32 v169, v169
	v_exp_f32_e32 v170, v170
	v_exp_f32_e32 v171, v171
	v_pk_add_f32 v[164:165], v[164:165], 1.0 op_sel_hi:[1,0]
	v_pk_add_f32 v[166:167], v[166:167], 1.0 op_sel_hi:[1,0]
	v_pk_add_f32 v[168:169], v[168:169], 1.0 op_sel_hi:[1,0]
	v_pk_add_f32 v[170:171], v[170:171], 1.0 op_sel_hi:[1,0]
	v_rcp_f32_e32 v164, v164
	v_rcp_f32_e32 v165, v165
	v_rcp_f32_e32 v166, v166
	v_rcp_f32_e32 v167, v167
	v_rcp_f32_e32 v168, v168
	v_rcp_f32_e32 v169, v169
	v_rcp_f32_e32 v170, v170
	v_rcp_f32_e32 v171, v171
	v_pk_mul_f32 v[164:165], v[128:129], v[164:165]
	v_pk_mul_f32 v[166:167], v[130:131], v[166:167]
	v_pk_mul_f32 v[168:169], v[124:125], v[168:169]
	v_pk_mul_f32 v[170:171], v[126:127], v[170:171]
	v_cvt_pk_bf16_f32 v174, v164, v165
	v_cvt_pk_bf16_f32 v175, v166, v167
	v_cvt_pk_bf16_f32 v176, v168, v169
	v_cvt_pk_bf16_f32 v177, v170, v171
	global_store_dwordx4 v1, v[174:177], s[22:23] offset:-4096
	s_waitcnt vmcnt(15)
	v_lshlrev_b32_e32 v164, 16, v186
	v_and_b32_e32 v165, 0xffff0000, v186
	v_lshlrev_b32_e32 v166, 16, v187
	v_and_b32_e32 v167, 0xffff0000, v187
	v_lshlrev_b32_e32 v168, 16, v188
	v_and_b32_e32 v169, 0xffff0000, v188
	v_lshlrev_b32_e32 v170, 16, v189
	v_and_b32_e32 v171, 0xffff0000, v189
	v_med3_f32 v164, v164, s34, v227
	v_med3_f32 v165, v165, s34, v227
	v_med3_f32 v166, v166, s34, v227
	v_med3_f32 v167, v167, s34, v227
	v_med3_f32 v168, v168, s34, v227
	v_med3_f32 v169, v169, s34, v227
	v_med3_f32 v170, v170, s34, v227
	v_med3_f32 v171, v171, s34, v227
	v_pk_mul_f32 v[164:165], v[164:165], s[44:45]
	v_pk_mul_f32 v[166:167], v[166:167], s[44:45]
	v_pk_mul_f32 v[168:169], v[168:169], s[44:45]
	v_pk_mul_f32 v[170:171], v[170:171], s[44:45]
	v_exp_f32_e32 v164, v164
	v_exp_f32_e32 v165, v165
	v_exp_f32_e32 v166, v166
	v_exp_f32_e32 v167, v167
	v_exp_f32_e32 v168, v168
	v_exp_f32_e32 v169, v169
	v_exp_f32_e32 v170, v170
	v_exp_f32_e32 v171, v171
	v_pk_add_f32 v[164:165], v[164:165], 1.0 op_sel_hi:[1,0]
	v_pk_add_f32 v[166:167], v[166:167], 1.0 op_sel_hi:[1,0]
	v_pk_add_f32 v[168:169], v[168:169], 1.0 op_sel_hi:[1,0]
	v_pk_add_f32 v[170:171], v[170:171], 1.0 op_sel_hi:[1,0]
	v_rcp_f32_e32 v164, v164
	v_rcp_f32_e32 v165, v165
	v_rcp_f32_e32 v166, v166
	v_rcp_f32_e32 v167, v167
	v_rcp_f32_e32 v168, v168
	v_rcp_f32_e32 v169, v169
	v_rcp_f32_e32 v170, v170
	v_rcp_f32_e32 v171, v171
	v_pk_mul_f32 v[164:165], v[104:105], v[164:165]
	v_pk_mul_f32 v[166:167], v[106:107], v[166:167]
	v_pk_mul_f32 v[168:169], v[100:101], v[168:169]
	v_pk_mul_f32 v[170:171], v[102:103], v[170:171]
	v_cvt_pk_bf16_f32 v174, v164, v165
	v_cvt_pk_bf16_f32 v175, v166, v167
	v_cvt_pk_bf16_f32 v176, v168, v169
	v_cvt_pk_bf16_f32 v177, v170, v171
	global_store_dwordx4 v1, v[174:177], s[22:23] offset:-3840
	s_waitcnt vmcnt(15)
	v_lshlrev_b32_e32 v164, 16, v190
	v_and_b32_e32 v165, 0xffff0000, v190
	v_lshlrev_b32_e32 v166, 16, v191
	v_and_b32_e32 v167, 0xffff0000, v191
	v_lshlrev_b32_e32 v168, 16, v192
	v_and_b32_e32 v169, 0xffff0000, v192
	v_lshlrev_b32_e32 v170, 16, v193
	v_and_b32_e32 v171, 0xffff0000, v193
	v_add_u32_e32 v1, s46, v148
	v_lshl_add_u32 v1, v1, 11, v0
	v_med3_f32 v164, v164, s34, v227
	v_med3_f32 v165, v165, s34, v227
	v_med3_f32 v166, v166, s34, v227
	v_med3_f32 v167, v167, s34, v227
	v_med3_f32 v168, v168, s34, v227
	v_med3_f32 v169, v169, s34, v227
	v_med3_f32 v170, v170, s34, v227
	v_med3_f32 v171, v171, s34, v227
	v_pk_mul_f32 v[164:165], v[164:165], s[44:45]
	v_pk_mul_f32 v[166:167], v[166:167], s[44:45]
	v_pk_mul_f32 v[168:169], v[168:169], s[44:45]
	v_pk_mul_f32 v[170:171], v[170:171], s[44:45]
	v_exp_f32_e32 v164, v164
	v_exp_f32_e32 v165, v165
	v_exp_f32_e32 v166, v166
	v_exp_f32_e32 v167, v167
	v_exp_f32_e32 v168, v168
	v_exp_f32_e32 v169, v169
	v_exp_f32_e32 v170, v170
	v_exp_f32_e32 v171, v171
	v_pk_add_f32 v[164:165], v[164:165], 1.0 op_sel_hi:[1,0]
	v_pk_add_f32 v[166:167], v[166:167], 1.0 op_sel_hi:[1,0]
	v_pk_add_f32 v[168:169], v[168:169], 1.0 op_sel_hi:[1,0]
	v_pk_add_f32 v[170:171], v[170:171], 1.0 op_sel_hi:[1,0]
	v_rcp_f32_e32 v164, v164
	v_rcp_f32_e32 v165, v165
	v_rcp_f32_e32 v166, v166
	v_rcp_f32_e32 v167, v167
	v_rcp_f32_e32 v168, v168
	v_rcp_f32_e32 v169, v169
	v_rcp_f32_e32 v170, v170
	v_rcp_f32_e32 v171, v171
	v_pk_mul_f32 v[164:165], v[120:121], v[164:165]
	v_pk_mul_f32 v[166:167], v[122:123], v[166:167]
	v_pk_mul_f32 v[168:169], v[116:117], v[168:169]
	v_pk_mul_f32 v[170:171], v[118:119], v[170:171]
	v_cvt_pk_bf16_f32 v174, v164, v165
	v_cvt_pk_bf16_f32 v175, v166, v167
	v_cvt_pk_bf16_f32 v176, v168, v169
	v_cvt_pk_bf16_f32 v177, v170, v171
	global_store_dwordx4 v1, v[174:177], s[22:23] offset:-4096
	s_waitcnt vmcnt(15)
	v_lshlrev_b32_e32 v164, 16, v202
	v_and_b32_e32 v165, 0xffff0000, v202
	v_lshlrev_b32_e32 v166, 16, v203
	v_and_b32_e32 v167, 0xffff0000, v203
	v_lshlrev_b32_e32 v168, 16, v204
	v_and_b32_e32 v169, 0xffff0000, v204
	v_lshlrev_b32_e32 v170, 16, v205
	v_and_b32_e32 v171, 0xffff0000, v205
	v_med3_f32 v164, v164, s34, v227
	v_med3_f32 v165, v165, s34, v227
	v_med3_f32 v166, v166, s34, v227
	v_med3_f32 v167, v167, s34, v227
	v_med3_f32 v168, v168, s34, v227
	v_med3_f32 v169, v169, s34, v227
	v_med3_f32 v170, v170, s34, v227
	v_med3_f32 v171, v171, s34, v227
	v_pk_mul_f32 v[164:165], v[164:165], s[44:45]
	v_pk_mul_f32 v[166:167], v[166:167], s[44:45]
	v_pk_mul_f32 v[168:169], v[168:169], s[44:45]
	v_pk_mul_f32 v[170:171], v[170:171], s[44:45]
	v_exp_f32_e32 v164, v164
	v_exp_f32_e32 v165, v165
	v_exp_f32_e32 v166, v166
	v_exp_f32_e32 v167, v167
	v_exp_f32_e32 v168, v168
	v_exp_f32_e32 v169, v169
	v_exp_f32_e32 v170, v170
	v_exp_f32_e32 v171, v171
	v_pk_add_f32 v[164:165], v[164:165], 1.0 op_sel_hi:[1,0]
	v_pk_add_f32 v[166:167], v[166:167], 1.0 op_sel_hi:[1,0]
	v_pk_add_f32 v[168:169], v[168:169], 1.0 op_sel_hi:[1,0]
	v_pk_add_f32 v[170:171], v[170:171], 1.0 op_sel_hi:[1,0]
	v_rcp_f32_e32 v164, v164
	v_rcp_f32_e32 v165, v165
	v_rcp_f32_e32 v166, v166
	v_rcp_f32_e32 v167, v167
	v_rcp_f32_e32 v168, v168
	v_rcp_f32_e32 v169, v169
	v_rcp_f32_e32 v170, v170
	v_rcp_f32_e32 v171, v171
	v_pk_mul_f32 v[164:165], v[96:97], v[164:165]
	v_pk_mul_f32 v[166:167], v[98:99], v[166:167]
	v_pk_mul_f32 v[168:169], v[92:93], v[168:169]
	v_pk_mul_f32 v[170:171], v[94:95], v[170:171]
	v_cvt_pk_bf16_f32 v174, v164, v165
	v_cvt_pk_bf16_f32 v175, v166, v167
	v_cvt_pk_bf16_f32 v176, v168, v169
	v_cvt_pk_bf16_f32 v177, v170, v171
	global_store_dwordx4 v1, v[174:177], s[22:23] offset:-3840
	s_waitcnt vmcnt(15)
	v_lshlrev_b32_e32 v164, 16, v206
	v_and_b32_e32 v165, 0xffff0000, v206
	v_lshlrev_b32_e32 v166, 16, v207
	v_and_b32_e32 v167, 0xffff0000, v207
	v_lshlrev_b32_e32 v168, 16, v208
	v_and_b32_e32 v169, 0xffff0000, v208
	v_lshlrev_b32_e32 v170, 16, v209
	v_and_b32_e32 v171, 0xffff0000, v209
	v_add_u32_e32 v1, s46, v150
	v_lshl_add_u32 v1, v1, 11, v0
	v_med3_f32 v164, v164, s34, v227
	v_med3_f32 v165, v165, s34, v227
	v_med3_f32 v166, v166, s34, v227
	v_med3_f32 v167, v167, s34, v227
	v_med3_f32 v168, v168, s34, v227
	v_med3_f32 v169, v169, s34, v227
	v_med3_f32 v170, v170, s34, v227
	v_med3_f32 v171, v171, s34, v227
	v_pk_mul_f32 v[164:165], v[164:165], s[44:45]
	v_pk_mul_f32 v[166:167], v[166:167], s[44:45]
	v_pk_mul_f32 v[168:169], v[168:169], s[44:45]
	v_pk_mul_f32 v[170:171], v[170:171], s[44:45]
	v_exp_f32_e32 v164, v164
	v_exp_f32_e32 v165, v165
	v_exp_f32_e32 v166, v166
	v_exp_f32_e32 v167, v167
	v_exp_f32_e32 v168, v168
	v_exp_f32_e32 v169, v169
	v_exp_f32_e32 v170, v170
	v_exp_f32_e32 v171, v171
	v_pk_add_f32 v[164:165], v[164:165], 1.0 op_sel_hi:[1,0]
	v_pk_add_f32 v[166:167], v[166:167], 1.0 op_sel_hi:[1,0]
	v_pk_add_f32 v[168:169], v[168:169], 1.0 op_sel_hi:[1,0]
	v_pk_add_f32 v[170:171], v[170:171], 1.0 op_sel_hi:[1,0]
	v_rcp_f32_e32 v164, v164
	v_rcp_f32_e32 v165, v165
	v_rcp_f32_e32 v166, v166
	v_rcp_f32_e32 v167, v167
	v_rcp_f32_e32 v168, v168
	v_rcp_f32_e32 v169, v169
	v_rcp_f32_e32 v170, v170
	v_rcp_f32_e32 v171, v171
	v_pk_mul_f32 v[164:165], v[112:113], v[164:165]
	v_pk_mul_f32 v[166:167], v[114:115], v[166:167]
	v_pk_mul_f32 v[168:169], v[108:109], v[168:169]
	v_pk_mul_f32 v[170:171], v[110:111], v[170:171]
	v_cvt_pk_bf16_f32 v174, v164, v165
	v_cvt_pk_bf16_f32 v175, v166, v167
	v_cvt_pk_bf16_f32 v176, v168, v169
	v_cvt_pk_bf16_f32 v177, v170, v171
	global_store_dwordx4 v1, v[174:177], s[22:23] offset:-4096
	s_waitcnt vmcnt(15)
	v_lshlrev_b32_e32 v164, 16, v210
	v_and_b32_e32 v165, 0xffff0000, v210
	v_lshlrev_b32_e32 v166, 16, v211
	v_and_b32_e32 v167, 0xffff0000, v211
	v_lshlrev_b32_e32 v168, 16, v212
	v_and_b32_e32 v169, 0xffff0000, v212
	v_lshlrev_b32_e32 v170, 16, v213
	v_and_b32_e32 v171, 0xffff0000, v213
	v_med3_f32 v164, v164, s34, v227
	v_med3_f32 v165, v165, s34, v227
	v_med3_f32 v166, v166, s34, v227
	v_med3_f32 v167, v167, s34, v227
	v_med3_f32 v168, v168, s34, v227
	v_med3_f32 v169, v169, s34, v227
	v_med3_f32 v170, v170, s34, v227
	v_med3_f32 v171, v171, s34, v227
	v_pk_mul_f32 v[164:165], v[164:165], s[44:45]
	v_pk_mul_f32 v[166:167], v[166:167], s[44:45]
	v_pk_mul_f32 v[168:169], v[168:169], s[44:45]
	v_pk_mul_f32 v[170:171], v[170:171], s[44:45]
	v_exp_f32_e32 v164, v164
	v_exp_f32_e32 v165, v165
	v_exp_f32_e32 v166, v166
	v_exp_f32_e32 v167, v167
	v_exp_f32_e32 v168, v168
	v_exp_f32_e32 v169, v169
	v_exp_f32_e32 v170, v170
	v_exp_f32_e32 v171, v171
	v_pk_add_f32 v[164:165], v[164:165], 1.0 op_sel_hi:[1,0]
	v_pk_add_f32 v[166:167], v[166:167], 1.0 op_sel_hi:[1,0]
	v_pk_add_f32 v[168:169], v[168:169], 1.0 op_sel_hi:[1,0]
	v_pk_add_f32 v[170:171], v[170:171], 1.0 op_sel_hi:[1,0]
	v_rcp_f32_e32 v164, v164
	v_rcp_f32_e32 v165, v165
	v_rcp_f32_e32 v166, v166
	v_rcp_f32_e32 v167, v167
	v_rcp_f32_e32 v168, v168
	v_rcp_f32_e32 v169, v169
	v_rcp_f32_e32 v170, v170
	v_rcp_f32_e32 v171, v171
	v_pk_mul_f32 v[164:165], v[88:89], v[164:165]
	v_pk_mul_f32 v[166:167], v[90:91], v[166:167]
	v_pk_mul_f32 v[168:169], v[84:85], v[168:169]
	v_pk_mul_f32 v[170:171], v[86:87], v[170:171]
	v_cvt_pk_bf16_f32 v174, v164, v165
	v_cvt_pk_bf16_f32 v175, v166, v167
	v_cvt_pk_bf16_f32 v176, v168, v169
	v_cvt_pk_bf16_f32 v177, v170, v171
	global_store_dwordx4 v1, v[174:177], s[22:23] offset:-3840
	s_waitcnt vmcnt(15)
	v_lshlrev_b32_e32 v164, 16, v214
	v_and_b32_e32 v165, 0xffff0000, v214
	v_lshlrev_b32_e32 v166, 16, v215
	v_and_b32_e32 v167, 0xffff0000, v215
	v_lshlrev_b32_e32 v168, 16, v216
	v_and_b32_e32 v169, 0xffff0000, v216
	v_lshlrev_b32_e32 v170, 16, v217
	v_and_b32_e32 v171, 0xffff0000, v217
	v_add_u32_e32 v1, s46, v152
	v_lshl_add_u32 v1, v1, 11, v0
	v_med3_f32 v164, v164, s34, v227
	v_med3_f32 v165, v165, s34, v227
	v_med3_f32 v166, v166, s34, v227
	v_med3_f32 v167, v167, s34, v227
	v_med3_f32 v168, v168, s34, v227
	v_med3_f32 v169, v169, s34, v227
	v_med3_f32 v170, v170, s34, v227
	v_med3_f32 v171, v171, s34, v227
	v_pk_mul_f32 v[164:165], v[164:165], s[44:45]
	v_pk_mul_f32 v[166:167], v[166:167], s[44:45]
	v_pk_mul_f32 v[168:169], v[168:169], s[44:45]
	v_pk_mul_f32 v[170:171], v[170:171], s[44:45]
	v_exp_f32_e32 v164, v164
	v_exp_f32_e32 v165, v165
	v_exp_f32_e32 v166, v166
	v_exp_f32_e32 v167, v167
	v_exp_f32_e32 v168, v168
	v_exp_f32_e32 v169, v169
	v_exp_f32_e32 v170, v170
	v_exp_f32_e32 v171, v171
	v_pk_add_f32 v[164:165], v[164:165], 1.0 op_sel_hi:[1,0]
	v_pk_add_f32 v[166:167], v[166:167], 1.0 op_sel_hi:[1,0]
	v_pk_add_f32 v[168:169], v[168:169], 1.0 op_sel_hi:[1,0]
	v_pk_add_f32 v[170:171], v[170:171], 1.0 op_sel_hi:[1,0]
	v_rcp_f32_e32 v164, v164
	v_rcp_f32_e32 v165, v165
	v_rcp_f32_e32 v166, v166
	v_rcp_f32_e32 v167, v167
	v_rcp_f32_e32 v168, v168
	v_rcp_f32_e32 v169, v169
	v_rcp_f32_e32 v170, v170
	v_rcp_f32_e32 v171, v171
	v_pk_mul_f32 v[164:165], v[80:81], v[164:165]
	v_pk_mul_f32 v[166:167], v[82:83], v[166:167]
	v_pk_mul_f32 v[168:169], v[76:77], v[168:169]
	v_pk_mul_f32 v[170:171], v[78:79], v[170:171]
	v_cvt_pk_bf16_f32 v174, v164, v165
	v_cvt_pk_bf16_f32 v175, v166, v167
	v_cvt_pk_bf16_f32 v176, v168, v169
	v_cvt_pk_bf16_f32 v177, v170, v171
	global_store_dwordx4 v1, v[174:177], s[22:23] offset:-4096
	s_waitcnt vmcnt(15)
	v_lshlrev_b32_e32 v164, 16, v236
	v_and_b32_e32 v165, 0xffff0000, v236
	v_lshlrev_b32_e32 v166, 16, v237
	v_and_b32_e32 v167, 0xffff0000, v237
	v_lshlrev_b32_e32 v168, 16, v238
	v_and_b32_e32 v169, 0xffff0000, v238
	v_lshlrev_b32_e32 v170, 16, v239
	v_and_b32_e32 v171, 0xffff0000, v239
	v_med3_f32 v164, v164, s34, v227
	v_med3_f32 v165, v165, s34, v227
	v_med3_f32 v166, v166, s34, v227
	v_med3_f32 v167, v167, s34, v227
	v_med3_f32 v168, v168, s34, v227
	v_med3_f32 v169, v169, s34, v227
	v_med3_f32 v170, v170, s34, v227
	v_med3_f32 v171, v171, s34, v227
	v_pk_mul_f32 v[164:165], v[164:165], s[44:45]
	v_pk_mul_f32 v[166:167], v[166:167], s[44:45]
	v_pk_mul_f32 v[168:169], v[168:169], s[44:45]
	v_pk_mul_f32 v[170:171], v[170:171], s[44:45]
	v_exp_f32_e32 v164, v164
	v_exp_f32_e32 v165, v165
	v_exp_f32_e32 v166, v166
	v_exp_f32_e32 v167, v167
	v_exp_f32_e32 v168, v168
	v_exp_f32_e32 v169, v169
	v_exp_f32_e32 v170, v170
	v_exp_f32_e32 v171, v171
	v_pk_add_f32 v[164:165], v[164:165], 1.0 op_sel_hi:[1,0]
	v_pk_add_f32 v[166:167], v[166:167], 1.0 op_sel_hi:[1,0]
	v_pk_add_f32 v[168:169], v[168:169], 1.0 op_sel_hi:[1,0]
	v_pk_add_f32 v[170:171], v[170:171], 1.0 op_sel_hi:[1,0]
	v_rcp_f32_e32 v164, v164
	v_rcp_f32_e32 v165, v165
	v_rcp_f32_e32 v166, v166
	v_rcp_f32_e32 v167, v167
	v_rcp_f32_e32 v168, v168
	v_rcp_f32_e32 v169, v169
	v_rcp_f32_e32 v170, v170
	v_rcp_f32_e32 v171, v171
	v_pk_mul_f32 v[164:165], v[48:49], v[164:165]
	v_pk_mul_f32 v[166:167], v[50:51], v[166:167]
	v_pk_mul_f32 v[168:169], v[44:45], v[168:169]
	v_pk_mul_f32 v[170:171], v[46:47], v[170:171]
	v_cvt_pk_bf16_f32 v174, v164, v165
	v_cvt_pk_bf16_f32 v175, v166, v167
	v_cvt_pk_bf16_f32 v176, v168, v169
	v_cvt_pk_bf16_f32 v177, v170, v171
	global_store_dwordx4 v1, v[174:177], s[22:23] offset:-3840
	s_waitcnt vmcnt(15)
	v_lshlrev_b32_e32 v164, 16, v240
	v_and_b32_e32 v165, 0xffff0000, v240
	v_lshlrev_b32_e32 v166, 16, v241
	v_and_b32_e32 v167, 0xffff0000, v241
	v_lshlrev_b32_e32 v168, 16, v242
	v_and_b32_e32 v169, 0xffff0000, v242
	v_lshlrev_b32_e32 v170, 16, v243
	v_and_b32_e32 v171, 0xffff0000, v243
	v_add_u32_e32 v1, s46, v154
	v_lshl_add_u32 v1, v1, 11, v0
	v_med3_f32 v164, v164, s34, v227
	v_med3_f32 v165, v165, s34, v227
	v_med3_f32 v166, v166, s34, v227
	v_med3_f32 v167, v167, s34, v227
	v_med3_f32 v168, v168, s34, v227
	v_med3_f32 v169, v169, s34, v227
	v_med3_f32 v170, v170, s34, v227
	v_med3_f32 v171, v171, s34, v227
	v_pk_mul_f32 v[164:165], v[164:165], s[44:45]
	v_pk_mul_f32 v[166:167], v[166:167], s[44:45]
	v_pk_mul_f32 v[168:169], v[168:169], s[44:45]
	v_pk_mul_f32 v[170:171], v[170:171], s[44:45]
	v_exp_f32_e32 v164, v164
	v_exp_f32_e32 v165, v165
	v_exp_f32_e32 v166, v166
	v_exp_f32_e32 v167, v167
	v_exp_f32_e32 v168, v168
	v_exp_f32_e32 v169, v169
	v_exp_f32_e32 v170, v170
	v_exp_f32_e32 v171, v171
	v_pk_add_f32 v[164:165], v[164:165], 1.0 op_sel_hi:[1,0]
	v_pk_add_f32 v[166:167], v[166:167], 1.0 op_sel_hi:[1,0]
	v_pk_add_f32 v[168:169], v[168:169], 1.0 op_sel_hi:[1,0]
	v_pk_add_f32 v[170:171], v[170:171], 1.0 op_sel_hi:[1,0]
	v_rcp_f32_e32 v164, v164
	v_rcp_f32_e32 v165, v165
	v_rcp_f32_e32 v166, v166
	v_rcp_f32_e32 v167, v167
	v_rcp_f32_e32 v168, v168
	v_rcp_f32_e32 v169, v169
	v_rcp_f32_e32 v170, v170
	v_rcp_f32_e32 v171, v171
	v_pk_mul_f32 v[164:165], v[72:73], v[164:165]
	v_pk_mul_f32 v[166:167], v[74:75], v[166:167]
	v_pk_mul_f32 v[168:169], v[68:69], v[168:169]
	v_pk_mul_f32 v[170:171], v[70:71], v[170:171]
	v_cvt_pk_bf16_f32 v174, v164, v165
	v_cvt_pk_bf16_f32 v175, v166, v167
	v_cvt_pk_bf16_f32 v176, v168, v169
	v_cvt_pk_bf16_f32 v177, v170, v171
	global_store_dwordx4 v1, v[174:177], s[22:23] offset:-4096
	s_waitcnt vmcnt(15)
	v_lshlrev_b32_e32 v164, 16, v244
	v_and_b32_e32 v165, 0xffff0000, v244
	v_lshlrev_b32_e32 v166, 16, v245
	v_and_b32_e32 v167, 0xffff0000, v245
	v_lshlrev_b32_e32 v168, 16, v246
	v_and_b32_e32 v169, 0xffff0000, v246
	v_lshlrev_b32_e32 v170, 16, v247
	v_and_b32_e32 v171, 0xffff0000, v247
	v_med3_f32 v164, v164, s34, v227
	v_med3_f32 v165, v165, s34, v227
	v_med3_f32 v166, v166, s34, v227
	v_med3_f32 v167, v167, s34, v227
	v_med3_f32 v168, v168, s34, v227
	v_med3_f32 v169, v169, s34, v227
	v_med3_f32 v170, v170, s34, v227
	v_med3_f32 v171, v171, s34, v227
	v_pk_mul_f32 v[164:165], v[164:165], s[44:45]
	v_pk_mul_f32 v[166:167], v[166:167], s[44:45]
	v_pk_mul_f32 v[168:169], v[168:169], s[44:45]
	v_pk_mul_f32 v[170:171], v[170:171], s[44:45]
	v_exp_f32_e32 v164, v164
	v_exp_f32_e32 v165, v165
	v_exp_f32_e32 v166, v166
	v_exp_f32_e32 v167, v167
	v_exp_f32_e32 v168, v168
	v_exp_f32_e32 v169, v169
	v_exp_f32_e32 v170, v170
	v_exp_f32_e32 v171, v171
	v_pk_add_f32 v[164:165], v[164:165], 1.0 op_sel_hi:[1,0]
	v_pk_add_f32 v[166:167], v[166:167], 1.0 op_sel_hi:[1,0]
	v_pk_add_f32 v[168:169], v[168:169], 1.0 op_sel_hi:[1,0]
	v_pk_add_f32 v[170:171], v[170:171], 1.0 op_sel_hi:[1,0]
	v_rcp_f32_e32 v164, v164
	v_rcp_f32_e32 v165, v165
	v_rcp_f32_e32 v166, v166
	v_rcp_f32_e32 v167, v167
	v_rcp_f32_e32 v168, v168
	v_rcp_f32_e32 v169, v169
	v_rcp_f32_e32 v170, v170
	v_rcp_f32_e32 v171, v171
	v_pk_mul_f32 v[164:165], v[40:41], v[164:165]
	v_pk_mul_f32 v[166:167], v[42:43], v[166:167]
	v_pk_mul_f32 v[168:169], v[36:37], v[168:169]
	v_pk_mul_f32 v[170:171], v[38:39], v[170:171]
	v_cvt_pk_bf16_f32 v174, v164, v165
	v_cvt_pk_bf16_f32 v175, v166, v167
	v_cvt_pk_bf16_f32 v176, v168, v169
	v_cvt_pk_bf16_f32 v177, v170, v171
	global_store_dwordx4 v1, v[174:177], s[22:23] offset:-3840
	s_waitcnt vmcnt(15)
	v_lshlrev_b32_e32 v164, 16, v248
	v_and_b32_e32 v165, 0xffff0000, v248
	v_lshlrev_b32_e32 v166, 16, v249
	v_and_b32_e32 v167, 0xffff0000, v249
	v_lshlrev_b32_e32 v168, 16, v250
	v_and_b32_e32 v169, 0xffff0000, v250
	v_lshlrev_b32_e32 v170, 16, v251
	v_and_b32_e32 v171, 0xffff0000, v251
	v_add_u32_e32 v1, s46, v156
	v_lshl_add_u32 v1, v1, 11, v0
	v_med3_f32 v164, v164, s34, v227
	v_med3_f32 v165, v165, s34, v227
	v_med3_f32 v166, v166, s34, v227
	v_med3_f32 v167, v167, s34, v227
	v_med3_f32 v168, v168, s34, v227
	v_med3_f32 v169, v169, s34, v227
	v_med3_f32 v170, v170, s34, v227
	v_med3_f32 v171, v171, s34, v227
	v_pk_mul_f32 v[164:165], v[164:165], s[44:45]
	v_pk_mul_f32 v[166:167], v[166:167], s[44:45]
	v_pk_mul_f32 v[168:169], v[168:169], s[44:45]
	v_pk_mul_f32 v[170:171], v[170:171], s[44:45]
	v_exp_f32_e32 v164, v164
	v_exp_f32_e32 v165, v165
	v_exp_f32_e32 v166, v166
	v_exp_f32_e32 v167, v167
	v_exp_f32_e32 v168, v168
	v_exp_f32_e32 v169, v169
	v_exp_f32_e32 v170, v170
	v_exp_f32_e32 v171, v171
	v_pk_add_f32 v[164:165], v[164:165], 1.0 op_sel_hi:[1,0]
	v_pk_add_f32 v[166:167], v[166:167], 1.0 op_sel_hi:[1,0]
	v_pk_add_f32 v[168:169], v[168:169], 1.0 op_sel_hi:[1,0]
	v_pk_add_f32 v[170:171], v[170:171], 1.0 op_sel_hi:[1,0]
	v_rcp_f32_e32 v164, v164
	v_rcp_f32_e32 v165, v165
	v_rcp_f32_e32 v166, v166
	v_rcp_f32_e32 v167, v167
	v_rcp_f32_e32 v168, v168
	v_rcp_f32_e32 v169, v169
	v_rcp_f32_e32 v170, v170
	v_rcp_f32_e32 v171, v171
	v_pk_mul_f32 v[164:165], v[64:65], v[164:165]
	v_pk_mul_f32 v[166:167], v[66:67], v[166:167]
	v_pk_mul_f32 v[168:169], v[60:61], v[168:169]
	v_pk_mul_f32 v[170:171], v[62:63], v[170:171]
	v_cvt_pk_bf16_f32 v174, v164, v165
	v_cvt_pk_bf16_f32 v175, v166, v167
	v_cvt_pk_bf16_f32 v176, v168, v169
	v_cvt_pk_bf16_f32 v177, v170, v171
	global_store_dwordx4 v1, v[174:177], s[22:23] offset:-4096
	s_waitcnt vmcnt(15)
	v_lshlrev_b32_e32 v164, 16, v132
	v_and_b32_e32 v165, 0xffff0000, v132
	v_lshlrev_b32_e32 v166, 16, v133
	v_and_b32_e32 v167, 0xffff0000, v133
	v_lshlrev_b32_e32 v168, 16, v134
	v_and_b32_e32 v169, 0xffff0000, v134
	v_lshlrev_b32_e32 v170, 16, v135
	v_and_b32_e32 v171, 0xffff0000, v135
	v_med3_f32 v164, v164, s34, v227
	v_med3_f32 v165, v165, s34, v227
	v_med3_f32 v166, v166, s34, v227
	v_med3_f32 v167, v167, s34, v227
	v_med3_f32 v168, v168, s34, v227
	v_med3_f32 v169, v169, s34, v227
	v_med3_f32 v170, v170, s34, v227
	v_med3_f32 v171, v171, s34, v227
	v_pk_mul_f32 v[164:165], v[164:165], s[44:45]
	v_pk_mul_f32 v[166:167], v[166:167], s[44:45]
	v_pk_mul_f32 v[168:169], v[168:169], s[44:45]
	v_pk_mul_f32 v[170:171], v[170:171], s[44:45]
	v_exp_f32_e32 v164, v164
	v_exp_f32_e32 v165, v165
	v_exp_f32_e32 v166, v166
	v_exp_f32_e32 v167, v167
	v_exp_f32_e32 v168, v168
	v_exp_f32_e32 v169, v169
	v_exp_f32_e32 v170, v170
	v_exp_f32_e32 v171, v171
	v_pk_add_f32 v[164:165], v[164:165], 1.0 op_sel_hi:[1,0]
	v_pk_add_f32 v[166:167], v[166:167], 1.0 op_sel_hi:[1,0]
	v_pk_add_f32 v[168:169], v[168:169], 1.0 op_sel_hi:[1,0]
	v_pk_add_f32 v[170:171], v[170:171], 1.0 op_sel_hi:[1,0]
	v_rcp_f32_e32 v164, v164
	v_rcp_f32_e32 v165, v165
	v_rcp_f32_e32 v166, v166
	v_rcp_f32_e32 v167, v167
	v_rcp_f32_e32 v168, v168
	v_rcp_f32_e32 v169, v169
	v_rcp_f32_e32 v170, v170
	v_rcp_f32_e32 v171, v171
	v_pk_mul_f32 v[164:165], v[32:33], v[164:165]
	v_pk_mul_f32 v[166:167], v[34:35], v[166:167]
	v_pk_mul_f32 v[168:169], v[28:29], v[168:169]
	v_pk_mul_f32 v[170:171], v[30:31], v[170:171]
	v_cvt_pk_bf16_f32 v174, v164, v165
	v_cvt_pk_bf16_f32 v175, v166, v167
	v_cvt_pk_bf16_f32 v176, v168, v169
	v_cvt_pk_bf16_f32 v177, v170, v171
	global_store_dwordx4 v1, v[174:177], s[22:23] offset:-3840
	s_waitcnt vmcnt(14)
	v_lshlrev_b32_e32 v164, 16, v178
	v_and_b32_e32 v165, 0xffff0000, v178
	v_lshlrev_b32_e32 v166, 16, v179
	v_and_b32_e32 v167, 0xffff0000, v179
	v_lshlrev_b32_e32 v168, 16, v180
	v_and_b32_e32 v169, 0xffff0000, v180
	v_lshlrev_b32_e32 v170, 16, v181
	v_and_b32_e32 v171, 0xffff0000, v181
	v_add_u32_e32 v1, s46, v158
	v_lshl_add_u32 v1, v1, 11, v0
	v_med3_f32 v164, v164, s34, v227
	v_med3_f32 v165, v165, s34, v227
	v_med3_f32 v166, v166, s34, v227
	v_med3_f32 v167, v167, s34, v227
	v_med3_f32 v168, v168, s34, v227
	v_med3_f32 v169, v169, s34, v227
	v_med3_f32 v170, v170, s34, v227
	v_med3_f32 v171, v171, s34, v227
	v_pk_mul_f32 v[164:165], v[164:165], s[44:45]
	v_pk_mul_f32 v[166:167], v[166:167], s[44:45]
	v_pk_mul_f32 v[168:169], v[168:169], s[44:45]
	v_pk_mul_f32 v[170:171], v[170:171], s[44:45]
	v_exp_f32_e32 v164, v164
	v_exp_f32_e32 v165, v165
	v_exp_f32_e32 v166, v166
	v_exp_f32_e32 v167, v167
	v_exp_f32_e32 v168, v168
	v_exp_f32_e32 v169, v169
	v_exp_f32_e32 v170, v170
	v_exp_f32_e32 v171, v171
	v_pk_add_f32 v[164:165], v[164:165], 1.0 op_sel_hi:[1,0]
	v_pk_add_f32 v[166:167], v[166:167], 1.0 op_sel_hi:[1,0]
	v_pk_add_f32 v[168:169], v[168:169], 1.0 op_sel_hi:[1,0]
	v_pk_add_f32 v[170:171], v[170:171], 1.0 op_sel_hi:[1,0]
	v_rcp_f32_e32 v164, v164
	v_rcp_f32_e32 v165, v165
	v_rcp_f32_e32 v166, v166
	v_rcp_f32_e32 v167, v167
	v_rcp_f32_e32 v168, v168
	v_rcp_f32_e32 v169, v169
	v_rcp_f32_e32 v170, v170
	v_rcp_f32_e32 v171, v171
	v_pk_mul_f32 v[164:165], v[56:57], v[164:165]
	v_pk_mul_f32 v[166:167], v[58:59], v[166:167]
	v_pk_mul_f32 v[168:169], v[52:53], v[168:169]
	v_pk_mul_f32 v[170:171], v[54:55], v[170:171]
	v_cvt_pk_bf16_f32 v174, v164, v165
	v_cvt_pk_bf16_f32 v175, v166, v167
	v_cvt_pk_bf16_f32 v176, v168, v169
	v_cvt_pk_bf16_f32 v177, v170, v171
	global_store_dwordx4 v1, v[174:177], s[22:23] offset:-4096
	s_waitcnt vmcnt(13)
	v_lshlrev_b32_e32 v164, 16, v182
	v_and_b32_e32 v165, 0xffff0000, v182
	v_lshlrev_b32_e32 v166, 16, v183
	v_and_b32_e32 v167, 0xffff0000, v183
	v_lshlrev_b32_e32 v168, 16, v184
	v_and_b32_e32 v169, 0xffff0000, v184
	v_lshlrev_b32_e32 v170, 16, v185
	v_and_b32_e32 v171, 0xffff0000, v185
	v_med3_f32 v164, v164, s34, v227
	v_med3_f32 v165, v165, s34, v227
	v_med3_f32 v166, v166, s34, v227
	v_med3_f32 v167, v167, s34, v227
	v_med3_f32 v168, v168, s34, v227
	v_med3_f32 v169, v169, s34, v227
	v_med3_f32 v170, v170, s34, v227
	v_med3_f32 v171, v171, s34, v227
	v_pk_mul_f32 v[164:165], v[164:165], s[44:45]
	v_pk_mul_f32 v[166:167], v[166:167], s[44:45]
	v_pk_mul_f32 v[168:169], v[168:169], s[44:45]
	v_pk_mul_f32 v[170:171], v[170:171], s[44:45]
	v_exp_f32_e32 v164, v164
	v_exp_f32_e32 v165, v165
	v_exp_f32_e32 v166, v166
	v_exp_f32_e32 v167, v167
	v_exp_f32_e32 v168, v168
	v_exp_f32_e32 v169, v169
	v_exp_f32_e32 v170, v170
	v_exp_f32_e32 v171, v171
	v_pk_add_f32 v[164:165], v[164:165], 1.0 op_sel_hi:[1,0]
	v_pk_add_f32 v[166:167], v[166:167], 1.0 op_sel_hi:[1,0]
	v_pk_add_f32 v[168:169], v[168:169], 1.0 op_sel_hi:[1,0]
	v_pk_add_f32 v[170:171], v[170:171], 1.0 op_sel_hi:[1,0]
	v_rcp_f32_e32 v164, v164
	v_rcp_f32_e32 v165, v165
	v_rcp_f32_e32 v166, v166
	v_rcp_f32_e32 v167, v167
	v_rcp_f32_e32 v168, v168
	v_rcp_f32_e32 v169, v169
	v_rcp_f32_e32 v170, v170
	v_rcp_f32_e32 v171, v171
	v_pk_mul_f32 v[164:165], v[24:25], v[164:165]
	v_pk_mul_f32 v[166:167], v[26:27], v[166:167]
	v_pk_mul_f32 v[168:169], v[20:21], v[168:169]
	v_pk_mul_f32 v[170:171], v[22:23], v[170:171]
	v_cvt_pk_bf16_f32 v174, v164, v165
	v_cvt_pk_bf16_f32 v175, v166, v167
	v_cvt_pk_bf16_f32 v176, v168, v169
	v_cvt_pk_bf16_f32 v177, v170, v171
	global_store_dwordx4 v1, v[174:177], s[22:23] offset:-3840
	s_mov_b64 s[40:41], 0
	s_branch .LBB0_206

.LBB0_232:
	s_and_b32 s22, 0xffff, s22
	s_cmp_lg_u32 s22, 0
	s_cselect_b64 s[26:27], -1, 0
	s_cmp_lg_u64 s[26:27], 0
	s_addc_u32 s83, s20, 0
	s_and_b32 s20, s23, 3
	s_add_i32 m0, s67, 0x18000
	v_lshl_add_u64 v[10:11], v[10:11], 0, s[76:77]
	s_lshl_b32 s31, s24, 6
	s_lshl_b32 s24, s24, 13
	s_lshl_b32 s49, s20, 5
	s_lshl_b32 s25, s20, 12
	s_waitcnt vmcnt(2)
	s_barrier
	global_load_lds_dwordx4 v[10:11], off
	v_lshl_add_u64 v[8:9], v[8:9], 0, s[76:77]
	s_add_i32 m0, s67, 0x1a000
	s_add_i32 s48, s67, 0x8000
	s_add_i32 s50, s67, 0xa000
	global_load_lds_dwordx4 v[8:9], off
	v_lshl_add_u64 v[6:7], v[6:7], 0, s[76:77]
	s_mov_b32 m0, s48
	s_add_u32 s22, s44, 0x40080
	global_load_lds_dwordx4 v[6:7], off
	v_lshl_add_u64 v[4:5], v[4:5], 0, s[76:77]
	s_mov_b32 m0, s50
	s_addc_u32 s23, s45, 0
	global_load_lds_dwordx4 v[4:5], off
	s_add_i32 m0, s67, 0x1c000
	v_lshl_add_u64 v[4:5], s[22:23], 0, v[176:177]
	global_load_lds_dwordx4 v[4:5], off
	v_lshl_add_u64 v[4:5], s[22:23], 0, v[180:181]
	s_add_i32 m0, s67, 0x1e000
	v_and_b32_e32 v183, 15, v2
	global_load_lds_dwordx4 v[4:5], off
	v_lshrrev_b32_e32 v4, 1, v2
	v_and_b32_e32 v182, 24, v4
	v_lshlrev_b32_e32 v4, 1, v182
	v_lshlrev_b32_e32 v2, 2, v2
	s_cmp_eq_u32 s20, 0
	v_lshl_or_b32 v4, v183, 6, v4
	v_and_b32_e32 v2, 32, v2
	s_cselect_b64 s[80:81], -1, 0
	s_cmpk_lt_u32 s21, 0x100
	v_bitop3_b32 v6, v4, s24, v2 bitop3:0xde
	v_bitop3_b32 v187, v4, s25, v2 bitop3:0xde
	s_cselect_b64 s[2:3], -1, 0
	v_readlane_b32 s12, v254, 42
	v_writelane_b32 v255, s2, 3
	v_readlane_b32 s20, v254, 50
	v_readlane_b32 s21, v254, 51
	v_or_b32_e32 v2, s49, v182
	v_writelane_b32 v255, s3, 4
	v_readlane_b32 s20, v252, 52
	v_or_b32_e32 v201, 0xfffff800, v2
	v_lshlrev_b32_e32 v2, 2, v182
	v_readlane_b32 s24, v254, 54
	v_readlane_b32 s25, v254, 55
	v_readlane_b32 s21, v252, 53
	v_readlane_b32 s2, v255, 1
	v_lshl_add_u64 v[188:189], s[24:25], 0, v[2:3]
	v_lshl_add_u64 v[190:191], s[20:21], 0, v[2:3]
	v_readlane_b32 s3, v255, 2
	v_lshlrev_b32_e32 v2, 14, v12
	v_add_u32_e32 v184, -13, v183
	v_mov_b64_e32 v[4:5], s[2:3]
	v_and_b32_e32 v2, 0xffff8000, v2
	v_mad_u64_u32 v[192:193], s[20:21], v184, s68, v[4:5]
	v_lshl_add_u32 v2, v13, 11, v2
	v_and_b32_e32 v4, 1, v12
	v_lshl_or_b32 v2, v4, 6, v2
	v_lshl_add_u32 v194, v14, 1, v2
	v_lshlrev_b32_e32 v2, 14, v15
	v_and_b32_e32 v2, 0xffff8000, v2
	s_waitcnt vmcnt(6)
	v_lshl_add_u32 v2, v16, 11, v2
	v_and_b32_e32 v4, 1, v15
	v_or_b32_e32 v185, s31, v183
	v_lshl_or_b32 v2, v4, 6, v2
	s_mov_b32 s51, 0
	v_or_b32_e32 v219, 16, v185
	v_or_b32_e32 v221, 32, v185
	v_or_b32_e32 v235, 48, v185
	v_add_u32_e32 v224, 0x80, v185
	v_add_u32_e32 v241, 0x90, v185
	v_add_u32_e32 v238, 0xa0, v185
	v_add_u32_e32 v239, 0xb0, v185
	v_cmp_gt_u32_e64 s[38:39], 3, v183
	v_cmp_lt_u32_e64 s[40:41], 12, v183
	v_add_u32_e32 v186, 3, v183
	s_ashr_i32 s70, s83, 31
	s_ashr_i32 s78, s9, 31
	v_mov_b32_e32 v195, v3
	v_lshl_add_u32 v202, v17, 1, v2
	v_mov_b32_e32 v203, v3
	v_add_u32_e32 v240, 0, v6
	s_mov_b64 s[56:57], s[0:1]
	s_mov_b64 s[58:59], s[44:45]
	s_movk_i32 s4, 0x6000
	s_movk_i32 s7, 0x3000
	s_mov_b32 s8, 0x9000
	s_barrier
	v_readlane_b32 s13, v254, 43
	v_readlane_b32 s14, v254, 44
	v_readlane_b32 s15, v254, 45
	v_readlane_b32 s16, v254, 46
	v_readlane_b32 s17, v254, 47
	v_readlane_b32 s18, v254, 48
	v_readlane_b32 s19, v254, 49
	v_readlane_b32 s22, v254, 52
	v_readlane_b32 s23, v254, 53
	v_readlane_b32 s26, v254, 56
	v_readlane_b32 s27, v254, 57
	s_branch .LBB0_235

.LBB0_242:
	s_add_u32 s23, s0, 0xfffc0080
	s_addc_u32 s24, s1, -1
	ds_read_b128 v[132:135], v216
	ds_read_b128 v[136:139], v216 offset:1024
	ds_read_b128 v[140:143], v216 offset:2048
	ds_read_b128 v[144:147], v216 offset:3072
	s_cmp_eq_u32 s22, 12
	s_cselect_b32 s47, s57, s24
	s_cselect_b32 s46, s56, s23
	s_cselect_b32 s45, s59, s21
	s_cselect_b32 s44, s58, s20
	s_add_i32 m0, s67, 0xc000
	ds_read_b128 v[148:151], v240
	ds_read_b128 v[152:155], v240 offset:1024
	ds_read_b128 v[156:159], v240 offset:2048
	ds_read_b128 v[160:163], v240 offset:3072
	ds_read_b128 v[164:167], v240 offset:4096
	ds_read_b128 v[168:171], v240 offset:5120
	ds_read_b128 v[172:175], v240 offset:6144
	global_load_lds_dwordx4 v194, s[0:1]
	s_add_i32 m0, s67, 0xe000
	ds_read_b128 v[204:207], v240 offset:7168
	global_load_lds_dwordx4 v202, s[0:1]
	ds_read_b128 v[208:211], v216 offset:16384
	ds_read_b128 v[212:215], v216 offset:17408
	ds_read_b128 v[242:245], v216 offset:18432
	ds_read_b128 v[246:249], v216 offset:19456
	s_waitcnt vmcnt(8)
	s_barrier
	s_waitcnt lgkmcnt(0)
	v_mfma_f32_16x16x32_bf16 v[128:131], v[132:135], v[148:151], v[128:131]
	v_mfma_f32_16x16x32_bf16 v[124:127], v[140:143], v[148:151], v[124:127]
	v_mfma_f32_16x16x32_bf16 v[120:123], v[132:135], v[156:159], v[120:123]
	v_mfma_f32_16x16x32_bf16 v[116:119], v[140:143], v[156:159], v[116:119]
	v_mfma_f32_16x16x32_bf16 v[112:115], v[132:135], v[164:167], v[112:115]
	v_mfma_f32_16x16x32_bf16 v[108:111], v[140:143], v[164:167], v[108:111]
	v_mfma_f32_16x16x32_bf16 v[104:107], v[132:135], v[172:175], v[104:107]
	v_mfma_f32_16x16x32_bf16 v[100:103], v[140:143], v[172:175], v[100:103]
	v_mfma_f32_16x16x32_bf16 v[128:131], v[136:139], v[152:155], v[128:131]
	v_mfma_f32_16x16x32_bf16 v[124:127], v[144:147], v[152:155], v[124:127]
	v_mfma_f32_16x16x32_bf16 v[120:123], v[136:139], v[160:163], v[120:123]
	v_mfma_f32_16x16x32_bf16 v[116:119], v[144:147], v[160:163], v[116:119]
	v_mfma_f32_16x16x32_bf16 v[112:115], v[136:139], v[168:171], v[112:115]
	v_mfma_f32_16x16x32_bf16 v[108:111], v[144:147], v[168:171], v[108:111]
	v_mfma_f32_16x16x32_bf16 v[104:107], v[136:139], v[204:207], v[104:107]
	v_mfma_f32_16x16x32_bf16 v[100:103], v[144:147], v[204:207], v[100:103]
	v_mfma_f32_16x16x32_bf16 v[64:67], v[208:211], v[148:151], v[64:67]
	v_mfma_f32_16x16x32_bf16 v[60:63], v[242:245], v[148:151], v[60:63]
	v_mfma_f32_16x16x32_bf16 v[56:59], v[208:211], v[156:159], v[56:59]
	v_mfma_f32_16x16x32_bf16 v[52:55], v[242:245], v[156:159], v[52:55]
	v_mfma_f32_16x16x32_bf16 v[48:51], v[208:211], v[164:167], v[48:51]
	v_mfma_f32_16x16x32_bf16 v[44:47], v[242:245], v[164:167], v[44:47]
	v_mfma_f32_16x16x32_bf16 v[40:43], v[208:211], v[172:175], v[40:43]
	v_mfma_f32_16x16x32_bf16 v[36:39], v[242:245], v[172:175], v[36:39]
	v_mfma_f32_16x16x32_bf16 v[64:67], v[212:215], v[152:155], v[64:67]
	v_mfma_f32_16x16x32_bf16 v[60:63], v[246:249], v[152:155], v[60:63]
	v_mfma_f32_16x16x32_bf16 v[56:59], v[212:215], v[160:163], v[56:59]
	v_mfma_f32_16x16x32_bf16 v[52:55], v[246:249], v[160:163], v[52:55]
	v_mfma_f32_16x16x32_bf16 v[48:51], v[212:215], v[168:171], v[48:51]
	v_mfma_f32_16x16x32_bf16 v[44:47], v[246:249], v[168:171], v[44:47]
	v_mfma_f32_16x16x32_bf16 v[40:43], v[212:215], v[204:207], v[40:43]
	v_mfma_f32_16x16x32_bf16 v[36:39], v[246:249], v[204:207], v[36:39]
	s_barrier
	ds_read_b128 v[148:151], v240 offset:16384
	ds_read_b128 v[152:155], v240 offset:17408
	ds_read_b128 v[156:159], v240 offset:18432
	ds_read_b128 v[160:163], v240 offset:19456
	s_add_i32 m0, s61, 0x10000
	ds_read_b128 v[164:167], v240 offset:20480
	global_load_lds_dwordx4 v176, s[44:45]
	s_add_i32 m0, s61, 0x12000
	ds_read_b128 v[168:171], v240 offset:21504
	global_load_lds_dwordx4 v180, s[44:45]
	s_mov_b32 m0, s67
	ds_read_b128 v[172:175], v240 offset:22528
	global_load_lds_dwordx4 v0, s[46:47]
	s_mov_b32 m0, s74
	ds_read_b128 v[204:207], v240 offset:23552
	global_load_lds_dwordx4 v178, s[46:47]
	s_add_i32 m0, s61, 0x14000
	s_add_u32 s24, s44, 0x40000
	s_addc_u32 s25, s45, 0
	global_load_lds_dwordx4 v176, s[24:25]
	s_add_i32 m0, s61, 0x16000
	s_waitcnt vmcnt(7)
	global_load_lds_dwordx4 v180, s[24:25]
	s_barrier
	s_waitcnt lgkmcnt(0)
	v_mfma_f32_16x16x32_bf16 v[96:99], v[132:135], v[148:151], v[96:99]
	v_mfma_f32_16x16x32_bf16 v[92:95], v[140:143], v[148:151], v[92:95]
	v_mfma_f32_16x16x32_bf16 v[88:91], v[132:135], v[156:159], v[88:91]
	v_mfma_f32_16x16x32_bf16 v[84:87], v[140:143], v[156:159], v[84:87]
	v_mfma_f32_16x16x32_bf16 v[80:83], v[132:135], v[164:167], v[80:83]
	v_mfma_f32_16x16x32_bf16 v[76:79], v[140:143], v[164:167], v[76:79]
	v_mfma_f32_16x16x32_bf16 v[72:75], v[132:135], v[172:175], v[72:75]
	v_mfma_f32_16x16x32_bf16 v[68:71], v[140:143], v[172:175], v[68:71]
	v_mfma_f32_16x16x32_bf16 v[96:99], v[136:139], v[152:155], v[96:99]
	v_mfma_f32_16x16x32_bf16 v[92:95], v[144:147], v[152:155], v[92:95]
	v_mfma_f32_16x16x32_bf16 v[88:91], v[136:139], v[160:163], v[88:91]
	v_mfma_f32_16x16x32_bf16 v[84:87], v[144:147], v[160:163], v[84:87]
	v_mfma_f32_16x16x32_bf16 v[80:83], v[136:139], v[168:171], v[80:83]
	v_mfma_f32_16x16x32_bf16 v[76:79], v[144:147], v[168:171], v[76:79]
	v_mfma_f32_16x16x32_bf16 v[72:75], v[136:139], v[204:207], v[72:75]
	v_mfma_f32_16x16x32_bf16 v[68:71], v[144:147], v[204:207], v[68:71]
	v_mfma_f32_16x16x32_bf16 v[32:35], v[208:211], v[148:151], v[32:35]
	v_mfma_f32_16x16x32_bf16 v[28:31], v[242:245], v[148:151], v[28:31]
	v_mfma_f32_16x16x32_bf16 v[24:27], v[208:211], v[156:159], v[24:27]
	v_mfma_f32_16x16x32_bf16 v[20:23], v[242:245], v[156:159], v[20:23]
	v_mfma_f32_16x16x32_bf16 v[16:19], v[208:211], v[164:167], v[16:19]
	v_mfma_f32_16x16x32_bf16 v[12:15], v[242:245], v[164:167], v[12:15]
	v_mfma_f32_16x16x32_bf16 v[8:11], v[208:211], v[172:175], v[8:11]
	v_mfma_f32_16x16x32_bf16 v[4:7], v[242:245], v[172:175], v[4:7]
	v_mfma_f32_16x16x32_bf16 v[32:35], v[212:215], v[152:155], v[32:35]
	v_mfma_f32_16x16x32_bf16 v[28:31], v[246:249], v[152:155], v[28:31]
	v_mfma_f32_16x16x32_bf16 v[24:27], v[212:215], v[160:163], v[24:27]
	v_mfma_f32_16x16x32_bf16 v[20:23], v[246:249], v[160:163], v[20:23]
	v_mfma_f32_16x16x32_bf16 v[16:19], v[212:215], v[168:171], v[16:19]
	v_mfma_f32_16x16x32_bf16 v[12:15], v[246:249], v[168:171], v[12:15]
	v_mfma_f32_16x16x32_bf16 v[8:11], v[212:215], v[204:207], v[8:11]
	v_mfma_f32_16x16x32_bf16 v[4:7], v[246:249], v[204:207], v[4:7]
	s_barrier
	ds_read_b128 v[132:135], v216 offset:32768
	ds_read_b128 v[136:139], v216 offset:33792
	ds_read_b128 v[140:143], v216 offset:34816
	ds_read_b128 v[144:147], v216 offset:35840
	s_add_u32 s24, s46, 0x40000
	s_addc_u32 s25, s47, 0
	s_mov_b32 m0, s75
	ds_read_b128 v[148:151], v240 offset:32768
	ds_read_b128 v[152:155], v240 offset:33792
	ds_read_b128 v[156:159], v240 offset:34816
	ds_read_b128 v[160:163], v240 offset:35840
	ds_read_b128 v[164:167], v240 offset:36864
	ds_read_b128 v[168:171], v240 offset:37888
	ds_read_b128 v[172:175], v240 offset:38912
	global_load_lds_dwordx4 v0, s[24:25]
	s_mov_b32 m0, s82
	ds_read_b128 v[204:207], v240 offset:39936
	global_load_lds_dwordx4 v178, s[24:25]
	ds_read_b128 v[208:211], v216 offset:49152
	ds_read_b128 v[212:215], v216 offset:50176
	ds_read_b128 v[242:245], v216 offset:51200
	ds_read_b128 v[246:249], v216 offset:52224
	s_waitcnt vmcnt(8)
	s_barrier
	s_waitcnt lgkmcnt(0)
	v_mfma_f32_16x16x32_bf16 v[128:131], v[132:135], v[148:151], v[128:131]
	v_mfma_f32_16x16x32_bf16 v[124:127], v[140:143], v[148:151], v[124:127]
	v_mfma_f32_16x16x32_bf16 v[120:123], v[132:135], v[156:159], v[120:123]
	v_mfma_f32_16x16x32_bf16 v[116:119], v[140:143], v[156:159], v[116:119]
	v_mfma_f32_16x16x32_bf16 v[112:115], v[132:135], v[164:167], v[112:115]
	v_mfma_f32_16x16x32_bf16 v[108:111], v[140:143], v[164:167], v[108:111]
	v_mfma_f32_16x16x32_bf16 v[104:107], v[132:135], v[172:175], v[104:107]
	v_mfma_f32_16x16x32_bf16 v[100:103], v[140:143], v[172:175], v[100:103]
	v_mfma_f32_16x16x32_bf16 v[128:131], v[136:139], v[152:155], v[128:131]
	v_mfma_f32_16x16x32_bf16 v[124:127], v[144:147], v[152:155], v[124:127]
	v_mfma_f32_16x16x32_bf16 v[120:123], v[136:139], v[160:163], v[120:123]
	v_mfma_f32_16x16x32_bf16 v[116:119], v[144:147], v[160:163], v[116:119]
	v_mfma_f32_16x16x32_bf16 v[112:115], v[136:139], v[168:171], v[112:115]
	v_mfma_f32_16x16x32_bf16 v[108:111], v[144:147], v[168:171], v[108:111]
	v_mfma_f32_16x16x32_bf16 v[104:107], v[136:139], v[204:207], v[104:107]
	v_mfma_f32_16x16x32_bf16 v[100:103], v[144:147], v[204:207], v[100:103]
	v_mfma_f32_16x16x32_bf16 v[64:67], v[208:211], v[148:151], v[64:67]
	v_mfma_f32_16x16x32_bf16 v[60:63], v[242:245], v[148:151], v[60:63]
	v_mfma_f32_16x16x32_bf16 v[56:59], v[208:211], v[156:159], v[56:59]
	v_mfma_f32_16x16x32_bf16 v[52:55], v[242:245], v[156:159], v[52:55]
	v_mfma_f32_16x16x32_bf16 v[48:51], v[208:211], v[164:167], v[48:51]
	v_mfma_f32_16x16x32_bf16 v[44:47], v[242:245], v[164:167], v[44:47]
	v_mfma_f32_16x16x32_bf16 v[40:43], v[208:211], v[172:175], v[40:43]
	v_mfma_f32_16x16x32_bf16 v[36:39], v[242:245], v[172:175], v[36:39]
	v_mfma_f32_16x16x32_bf16 v[64:67], v[212:215], v[152:155], v[64:67]
	v_mfma_f32_16x16x32_bf16 v[60:63], v[246:249], v[152:155], v[60:63]
	v_mfma_f32_16x16x32_bf16 v[56:59], v[212:215], v[160:163], v[56:59]
	v_mfma_f32_16x16x32_bf16 v[52:55], v[246:249], v[160:163], v[52:55]
	v_mfma_f32_16x16x32_bf16 v[48:51], v[212:215], v[168:171], v[48:51]
	v_mfma_f32_16x16x32_bf16 v[44:47], v[246:249], v[168:171], v[44:47]
	v_mfma_f32_16x16x32_bf16 v[40:43], v[212:215], v[204:207], v[40:43]
	v_mfma_f32_16x16x32_bf16 v[36:39], v[246:249], v[204:207], v[36:39]
	s_barrier
	ds_read_b128 v[148:151], v240 offset:49152
	ds_read_b128 v[152:155], v240 offset:50176
	ds_read_b128 v[156:159], v240 offset:51200
	ds_read_b128 v[160:163], v240 offset:52224
	ds_read_b128 v[164:167], v240 offset:53248
	ds_read_b128 v[168:171], v240 offset:54272
	s_add_i32 m0, s61, 0x18000
	s_add_u32 s98, s44, 0x80
	s_addc_u32 s99, s45, 0
	global_load_lds_dwordx4 v176, s[98:99]
	s_add_i32 m0, s61, 0x1a000
	ds_read_b128 v[172:175], v240 offset:55296
	global_load_lds_dwordx4 v180, s[98:99]
	s_mov_b32 m0, s48
	s_add_u32 s98, s46, 0x80
	s_addc_u32 s99, s47, 0
	global_load_lds_dwordx4 v0, s[98:99]
	s_mov_b32 m0, s50
	ds_read_b128 v[204:207], v240 offset:56320
	global_load_lds_dwordx4 v178, s[98:99]
	s_add_i32 m0, s61, 0x1c000
	s_add_u32 s24, s44, 0x40080
	s_addc_u32 s25, s45, 0
	global_load_lds_dwordx4 v176, s[24:25]
	s_add_i32 m0, s61, 0x1e000
	s_waitcnt vmcnt(7)
	global_load_lds_dwordx4 v180, s[24:25]
	s_barrier
	s_waitcnt lgkmcnt(0)
	v_mfma_f32_16x16x32_bf16 v[96:99], v[132:135], v[148:151], v[96:99]
	v_mfma_f32_16x16x32_bf16 v[92:95], v[140:143], v[148:151], v[92:95]
	v_mfma_f32_16x16x32_bf16 v[88:91], v[132:135], v[156:159], v[88:91]
	v_mfma_f32_16x16x32_bf16 v[84:87], v[140:143], v[156:159], v[84:87]
	v_mfma_f32_16x16x32_bf16 v[80:83], v[132:135], v[164:167], v[80:83]
	v_mfma_f32_16x16x32_bf16 v[76:79], v[140:143], v[164:167], v[76:79]
	v_mfma_f32_16x16x32_bf16 v[72:75], v[132:135], v[172:175], v[72:75]
	v_mfma_f32_16x16x32_bf16 v[68:71], v[140:143], v[172:175], v[68:71]
	v_mfma_f32_16x16x32_bf16 v[96:99], v[136:139], v[152:155], v[96:99]
	v_mfma_f32_16x16x32_bf16 v[92:95], v[144:147], v[152:155], v[92:95]
	v_mfma_f32_16x16x32_bf16 v[88:91], v[136:139], v[160:163], v[88:91]
	v_mfma_f32_16x16x32_bf16 v[84:87], v[144:147], v[160:163], v[84:87]
	v_mfma_f32_16x16x32_bf16 v[80:83], v[136:139], v[168:171], v[80:83]
	v_mfma_f32_16x16x32_bf16 v[76:79], v[144:147], v[168:171], v[76:79]
	v_mfma_f32_16x16x32_bf16 v[72:75], v[136:139], v[204:207], v[72:75]
	v_mfma_f32_16x16x32_bf16 v[68:71], v[144:147], v[204:207], v[68:71]
	v_mfma_f32_16x16x32_bf16 v[32:35], v[208:211], v[148:151], v[32:35]
	v_mfma_f32_16x16x32_bf16 v[28:31], v[242:245], v[148:151], v[28:31]
	v_mfma_f32_16x16x32_bf16 v[24:27], v[208:211], v[156:159], v[24:27]
	v_mfma_f32_16x16x32_bf16 v[20:23], v[242:245], v[156:159], v[20:23]
	v_mfma_f32_16x16x32_bf16 v[16:19], v[208:211], v[164:167], v[16:19]
	v_mfma_f32_16x16x32_bf16 v[12:15], v[242:245], v[164:167], v[12:15]
	v_mfma_f32_16x16x32_bf16 v[8:11], v[208:211], v[172:175], v[8:11]
	v_mfma_f32_16x16x32_bf16 v[4:7], v[242:245], v[172:175], v[4:7]
	v_mfma_f32_16x16x32_bf16 v[32:35], v[212:215], v[152:155], v[32:35]
	v_mfma_f32_16x16x32_bf16 v[28:31], v[246:249], v[152:155], v[28:31]
	v_mfma_f32_16x16x32_bf16 v[24:27], v[212:215], v[160:163], v[24:27]
	v_mfma_f32_16x16x32_bf16 v[20:23], v[246:249], v[160:163], v[20:23]
	v_mfma_f32_16x16x32_bf16 v[16:19], v[212:215], v[168:171], v[16:19]
	v_mfma_f32_16x16x32_bf16 v[12:15], v[246:249], v[168:171], v[12:15]
	v_mfma_f32_16x16x32_bf16 v[8:11], v[212:215], v[204:207], v[8:11]
	v_mfma_f32_16x16x32_bf16 v[4:7], v[246:249], v[204:207], v[4:7]
	s_add_i32 s22, s22, 2
	s_add_u32 s0, s0, 0x100
	s_addc_u32 s1, s1, 0
	s_add_u32 s20, s20, 0x100
	s_addc_u32 s21, s21, 0
	s_cmp_gt_u32 s22, 13
	s_barrier
	s_cbranch_scc0 .LBB0_242
	s_add_i32 s0, s66, -8
	s_cmp_lt_u32 s0, 12
	s_mov_b64 s[0:1], -1
	s_cbranch_scc1 .LBB0_266
	s_cmp_gt_i32 s66, 33
	s_cselect_b64 s[64:65], -1, 0
	s_lshl_b32 s0, s66, 8
	s_lshl_b32 s53, s60, 8
	s_add_i32 s1, s0, 0xffffee00
	s_cmp_lt_i32 s66, 26
	v_cndmask_b32_e64 v2, 0, 1, s[80:81]
	s_cselect_b32 s62, s0, s1
	s_mov_b64 s[0:1], -1
	s_and_b64 vcc, exec, s[64:65]
	v_cmp_ne_u32_e64 s[44:45], 1, v2
	s_cbranch_vccz .LBB0_248
	s_and_b64 vcc, exec, s[44:45]
	s_cbranch_vccnz .LBB0_247
	v_add_u32_e32 v132, s53, v185
	v_ashrrev_i32_e32 v133, 31, v132
	v_lshlrev_b64 v[140:141], 7, v[132:133]
	global_load_dwordx4 v[132:135], v[188:189], off offset:16
	global_load_dwordx4 v[136:139], v[188:189], off
	s_mov_b32 s3, 0xbfb8aa3b
	s_mov_b32 s2, 0x800000
	s_mov_b32 s5, 0x3f317217
	s_mov_b32 s6, 0x7f800000
	s_waitcnt vmcnt(0)
	v_add_f32_e32 v147, v126, v134
	v_add_f32_e32 v2, v128, v136
	v_max_f32_e32 v142, 0, v2
	v_mul_f32_e64 v2, |v2|, s3
	v_exp_f32_e32 v2, v2
	v_add_f32_e32 v136, v124, v132
	v_add_f32_e32 v149, v127, v135
	v_add_f32_e32 v2, 1.0, v2
	v_cmp_gt_f32_e32 vcc, s2, v2
	s_nop 1
	v_cndmask_b32_e64 v132, 0, 32, vcc
	v_ldexp_f32 v2, v2, v132
	v_log_f32_e32 v2, v2
	s_nop 0
	v_mul_f32_e32 v132, 0x3f317217, v2
	v_fma_f32 v132, v2, s5, -v132
	v_fmac_f32_e32 v132, 0x3377d1cf, v2
	v_fmac_f32_e32 v132, 0x3f317217, v2
	v_cmp_lt_f32_e64 s[0:1], |v2|, s6
	s_nop 1
	v_cndmask_b32_e64 v2, v2, v132, s[0:1]
	v_cndmask_b32_e32 v132, 0, v228, vcc
	v_sub_f32_e32 v144, v2, v132
	v_mul_f32_e64 v2, |v136|, s3
	v_exp_f32_e32 v2, v2
	v_max_f32_e32 v132, 0, v136
	v_add_f32_e32 v2, 1.0, v2
	v_cmp_gt_f32_e32 vcc, s2, v2
	s_nop 1
	v_cndmask_b32_e64 v136, 0, 32, vcc
	v_ldexp_f32 v2, v2, v136
	v_log_f32_e32 v2, v2
	s_nop 0
	v_mul_f32_e32 v136, 0x3f317217, v2
	v_fma_f32 v136, v2, s5, -v136
	v_fmac_f32_e32 v136, 0x3377d1cf, v2
	v_fmac_f32_e32 v136, 0x3f317217, v2
	v_cmp_lt_f32_e64 s[0:1], |v2|, s6
	s_nop 1
	v_cndmask_b32_e64 v2, v2, v136, s[0:1]
	v_cndmask_b32_e32 v136, 0, v228, vcc
	v_sub_f32_e32 v136, v2, v136
	v_add_f32_e32 v2, v129, v137
	v_max_f32_e32 v143, 0, v2
	v_mul_f32_e64 v2, |v2|, s3
	v_exp_f32_e32 v2, v2
	v_add_f32_e32 v137, v125, v133
	v_add_f32_e32 v2, 1.0, v2
	v_cmp_gt_f32_e32 vcc, s2, v2
	s_nop 1
	v_cndmask_b32_e64 v133, 0, 32, vcc
	v_ldexp_f32 v2, v2, v133
	v_log_f32_e32 v2, v2
	s_nop 0
	v_mul_f32_e32 v133, 0x3f317217, v2
	v_fma_f32 v133, v2, s5, -v133
	v_fmac_f32_e32 v133, 0x3377d1cf, v2
	v_fmac_f32_e32 v133, 0x3f317217, v2
	v_cmp_lt_f32_e64 s[0:1], |v2|, s6
	s_nop 1
	v_cndmask_b32_e64 v2, v2, v133, s[0:1]
	v_cndmask_b32_e32 v133, 0, v228, vcc
	v_sub_f32_e32 v145, v2, v133
	v_mul_f32_e64 v2, |v137|, s3
	v_exp_f32_e32 v2, v2
	v_max_f32_e32 v133, 0, v137
	v_pk_add_f32 v[142:143], v[142:143], v[144:145]
	v_add_f32_e32 v2, 1.0, v2
	v_cmp_gt_f32_e32 vcc, s2, v2
	s_nop 1
	v_cndmask_b32_e64 v137, 0, 32, vcc
	v_ldexp_f32 v2, v2, v137
	v_log_f32_e32 v2, v2
	s_nop 0
	v_mul_f32_e32 v137, 0x3f317217, v2
	v_fma_f32 v137, v2, s5, -v137
	v_fmac_f32_e32 v137, 0x3377d1cf, v2
	v_fmac_f32_e32 v137, 0x3f317217, v2
	v_cmp_lt_f32_e64 s[0:1], |v2|, s6
	s_nop 1
	v_cndmask_b32_e64 v2, v2, v137, s[0:1]
	v_cndmask_b32_e32 v137, 0, v228, vcc
	v_sub_f32_e32 v137, v2, v137
	v_add_f32_e32 v2, v130, v138
	v_max_f32_e32 v138, 0, v2
	v_mul_f32_e64 v2, |v2|, s3
	v_exp_f32_e32 v2, v2
	v_pk_add_f32 v[132:133], v[132:133], v[136:137]
	v_lshl_add_u64 v[136:137], v[190:191], 0, v[140:141]
	v_add_f32_e32 v2, 1.0, v2
	v_cmp_gt_f32_e32 vcc, s2, v2
	s_nop 1
	v_cndmask_b32_e64 v134, 0, 32, vcc
	v_ldexp_f32 v2, v2, v134
	v_log_f32_e32 v2, v2
	s_nop 0
	v_mul_f32_e32 v134, 0x3f317217, v2
	v_fma_f32 v134, v2, s5, -v134
	v_fmac_f32_e32 v134, 0x3377d1cf, v2
	v_fmac_f32_e32 v134, 0x3f317217, v2
	v_cmp_lt_f32_e64 s[0:1], |v2|, s6
	s_nop 1
	v_cndmask_b32_e64 v2, v2, v134, s[0:1]
	v_cndmask_b32_e32 v134, 0, v228, vcc
	v_sub_f32_e32 v146, v2, v134
	v_mul_f32_e64 v2, |v147|, s3
	v_exp_f32_e32 v2, v2
	v_max_f32_e32 v134, 0, v147
	v_add_f32_e32 v2, 1.0, v2
	v_cmp_gt_f32_e32 vcc, s2, v2
	s_nop 1
	v_cndmask_b32_e64 v147, 0, 32, vcc
	v_ldexp_f32 v2, v2, v147
	v_log_f32_e32 v2, v2
	s_nop 0
	v_mul_f32_e32 v147, 0x3f317217, v2
	v_fma_f32 v147, v2, s5, -v147
	v_fmac_f32_e32 v147, 0x3377d1cf, v2
	v_fmac_f32_e32 v147, 0x3f317217, v2
	v_cmp_lt_f32_e64 s[0:1], |v2|, s6
	s_nop 1
	v_cndmask_b32_e64 v2, v2, v147, s[0:1]
	v_cndmask_b32_e32 v147, 0, v228, vcc
	v_sub_f32_e32 v148, v2, v147
	v_add_f32_e32 v2, v131, v139
	v_max_f32_e32 v139, 0, v2
	v_mul_f32_e64 v2, |v2|, s3
	v_exp_f32_e32 v2, v2
	s_nop 0
	v_add_f32_e32 v2, 1.0, v2
	v_cmp_gt_f32_e32 vcc, s2, v2
	s_nop 1
	v_cndmask_b32_e64 v135, 0, 32, vcc
	v_ldexp_f32 v2, v2, v135
	v_log_f32_e32 v2, v2
	s_nop 0
	v_mul_f32_e32 v135, 0x3f317217, v2
	v_fma_f32 v135, v2, s5, -v135
	v_fmac_f32_e32 v135, 0x3377d1cf, v2
	v_fmac_f32_e32 v135, 0x3f317217, v2
	v_cmp_lt_f32_e64 s[0:1], |v2|, s6
	s_nop 1
	v_cndmask_b32_e64 v2, v2, v135, s[0:1]
	v_cndmask_b32_e32 v135, 0, v228, vcc
	v_sub_f32_e32 v147, v2, v135
	v_mul_f32_e64 v2, |v149|, s3
	v_exp_f32_e32 v2, v2
	v_pk_add_f32 v[144:145], v[138:139], v[146:147]
	v_max_f32_e32 v135, 0, v149
	v_add_f32_e32 v2, 1.0, v2
	v_cmp_gt_f32_e32 vcc, s2, v2
	s_nop 1
	v_cndmask_b32_e64 v138, 0, 32, vcc
	v_ldexp_f32 v2, v2, v138
	v_log_f32_e32 v2, v2
	s_nop 0
	v_mul_f32_e32 v138, 0x3f317217, v2
	v_fma_f32 v138, v2, s5, -v138
	v_fmac_f32_e32 v138, 0x3377d1cf, v2
	v_fmac_f32_e32 v138, 0x3f317217, v2
	v_cmp_lt_f32_e64 s[0:1], |v2|, s6
	s_nop 1
	v_cndmask_b32_e64 v2, v2, v138, s[0:1]
	v_cndmask_b32_e32 v138, 0, v228, vcc
	v_sub_f32_e32 v149, v2, v138
	v_pk_add_f32 v[134:135], v[134:135], v[148:149]
	global_store_dwordx4 v[136:137], v[142:145], off
	global_store_dwordx4 v[136:137], v[132:135], off offset:16

.LBB0_390:
	s_and_b32 s21, s21, 3
	s_add_i32 m0, s74, 0x18000
	v_lshl_add_u64 v[10:11], v[10:11], 0, s[76:77]
	s_lshl_b32 s11, s22, 6
	s_lshl_b32 s24, s22, 13
	s_lshl_b32 s49, s21, 5
	s_lshl_b32 s25, s21, 12
	s_waitcnt vmcnt(2)
	s_barrier
	global_load_lds_dwordx4 v[10:11], off
	v_lshl_add_u64 v[8:9], v[8:9], 0, s[76:77]
	s_add_i32 m0, s74, 0x1a000
	s_add_i32 s48, s74, 0x8000
	s_add_i32 s50, s74, 0xa000
	global_load_lds_dwordx4 v[8:9], off
	v_lshl_add_u64 v[6:7], v[6:7], 0, s[76:77]
	s_mov_b32 m0, s48
	s_add_u32 s22, s44, 0x40080
	global_load_lds_dwordx4 v[6:7], off
	v_lshl_add_u64 v[4:5], v[4:5], 0, s[76:77]
	s_mov_b32 m0, s50
	s_addc_u32 s23, s45, 0
	global_load_lds_dwordx4 v[4:5], off
	s_add_i32 m0, s74, 0x1c000
	v_lshl_add_u64 v[4:5], s[22:23], 0, v[176:177]
	global_load_lds_dwordx4 v[4:5], off
	v_lshl_add_u64 v[4:5], s[22:23], 0, v[180:181]
	s_add_i32 m0, s74, 0x1e000
	v_and_b32_e32 v183, 15, v2
	global_load_lds_dwordx4 v[4:5], off
	v_lshrrev_b32_e32 v4, 1, v2
	v_and_b32_e32 v182, 24, v4
	v_lshlrev_b32_e32 v4, 1, v182
	v_lshlrev_b32_e32 v2, 2, v2
	s_cmp_eq_u32 s21, 0
	v_lshl_or_b32 v4, v183, 6, v4
	v_and_b32_e32 v2, 32, v2
	s_cselect_b64 s[36:37], -1, 0
	s_cmpk_lt_u32 s20, 0x100
	v_bitop3_b32 v6, v4, s24, v2 bitop3:0xde
	v_bitop3_b32 v187, v4, s25, v2 bitop3:0xde
	s_cselect_b64 s[2:3], -1, 0
	v_readlane_b32 s12, v254, 42
	v_writelane_b32 v255, s2, 3
	v_readlane_b32 s20, v254, 50
	v_readlane_b32 s21, v254, 51
	v_or_b32_e32 v2, s49, v182
	v_writelane_b32 v255, s3, 4
	v_readlane_b32 s20, v252, 52
	v_or_b32_e32 v201, 0xfffff800, v2
	v_lshlrev_b32_e32 v2, 2, v182
	v_readlane_b32 s24, v254, 54
	v_readlane_b32 s25, v254, 55
	v_readlane_b32 s21, v252, 53
	v_readlane_b32 s2, v255, 1
	v_lshl_add_u64 v[188:189], s[24:25], 0, v[2:3]
	v_lshl_add_u64 v[190:191], s[20:21], 0, v[2:3]
	v_readlane_b32 s3, v255, 2
	v_lshlrev_b32_e32 v2, 14, v12
	v_add_u32_e32 v184, -13, v183
	v_mov_b64_e32 v[4:5], s[2:3]
	v_and_b32_e32 v2, 0xffff8000, v2
	v_mad_u64_u32 v[192:193], s[20:21], v184, s68, v[4:5]
	v_lshl_add_u32 v2, v13, 11, v2
	v_and_b32_e32 v4, 1, v12
	v_lshl_or_b32 v2, v4, 6, v2
	v_lshl_add_u32 v194, v14, 1, v2
	v_bfe_u32 v20, v194, 11, 4
	v_bfe_u32 v21, v194, 15, 2
	v_and_b32_e32 v194, 0xfffe07ff, v194
	v_lshl_or_b32 v194, v20, 13, v194
	v_lshl_or_b32 v194, v21, 11, v194
	v_lshlrev_b32_e32 v2, 14, v15
	v_and_b32_e32 v2, 0xffff8000, v2
	s_waitcnt vmcnt(6)
	v_lshl_add_u32 v2, v16, 11, v2
	v_and_b32_e32 v4, 1, v15
	v_lshl_or_b32 v185, v183, 2, s11
	v_lshl_or_b32 v2, v4, 6, v2
	s_mov_b32 s51, 0
	v_or_b32_e32 v241, 1, v185
	v_or_b32_e32 v219, 2, v185
	v_or_b32_e32 v235, 3, v185
	v_add_u32_e32 v221, 0x80, v185
	v_add_u32_e32 v224, 0x81, v185
	v_add_u32_e32 v238, 0x82, v185
	v_add_u32_e32 v239, 0x83, v185
	v_cmp_gt_u32_e64 s[38:39], 3, v183
	v_cmp_lt_u32_e64 s[40:41], 12, v183
	v_add_u32_e32 v186, 3, v183
	s_waitcnt lgkmcnt(0)
	s_ashr_i32 s31, s10, 31
	s_ashr_i32 s78, s66, 31
	v_mov_b32_e32 v195, v3
	v_lshl_add_u32 v202, v17, 1, v2
	v_bfe_u32 v20, v202, 11, 4
	v_bfe_u32 v21, v202, 15, 2
	v_and_b32_e32 v202, 0xfffe07ff, v202
	v_lshl_or_b32 v202, v20, 13, v202
	v_lshl_or_b32 v202, v21, 11, v202
	v_mov_b32_e32 v203, v3
	v_add_u32_e32 v240, 0, v6
	s_mov_b64 s[56:57], s[0:1]
	s_mov_b64 s[58:59], s[44:45]
	s_barrier
	v_readlane_b32 s13, v254, 43
	v_readlane_b32 s14, v254, 44
	v_readlane_b32 s15, v254, 45
	v_readlane_b32 s16, v254, 46
	v_readlane_b32 s17, v254, 47
	v_readlane_b32 s18, v254, 48
	v_readlane_b32 s19, v254, 49
	v_readlane_b32 s22, v254, 52
	v_readlane_b32 s23, v254, 53
	v_readlane_b32 s26, v254, 56
	v_readlane_b32 s27, v254, 57
	s_branch .LBB0_420

.LBB0_427:
	s_add_u32 s23, s0, 0xfffc0080
	s_addc_u32 s24, s1, -1
	ds_read_b128 v[132:135], v216
	ds_read_b128 v[136:139], v216 offset:1024
	ds_read_b128 v[140:143], v216 offset:2048
	ds_read_b128 v[144:147], v216 offset:3072
	s_cmp_eq_u32 s22, 12
	s_cselect_b32 s47, s57, s24
	s_cselect_b32 s46, s56, s23
	s_cselect_b32 s45, s59, s21
	s_cselect_b32 s44, s58, s20
	s_add_i32 m0, s74, 0xc000
	ds_read_b128 v[148:151], v240
	ds_read_b128 v[152:155], v240 offset:1024
	ds_read_b128 v[156:159], v240 offset:2048
	ds_read_b128 v[160:163], v240 offset:3072
	ds_read_b128 v[164:167], v240 offset:4096
	ds_read_b128 v[168:171], v240 offset:5120
	ds_read_b128 v[172:175], v240 offset:6144
	global_load_lds_dwordx4 v194, s[0:1]
	s_add_i32 m0, s74, 0xe000
	ds_read_b128 v[204:207], v240 offset:7168
	global_load_lds_dwordx4 v202, s[0:1]
	ds_read_b128 v[208:211], v216 offset:16384
	ds_read_b128 v[212:215], v216 offset:17408
	ds_read_b128 v[242:245], v216 offset:18432
	ds_read_b128 v[246:249], v216 offset:19456
	s_waitcnt vmcnt(8)
	s_barrier
	s_waitcnt lgkmcnt(0)
	v_mfma_f32_16x16x32_bf16 v[128:131], v[132:135], v[148:151], v[128:131]
	v_mfma_f32_16x16x32_bf16 v[124:127], v[140:143], v[148:151], v[124:127]
	v_mfma_f32_16x16x32_bf16 v[120:123], v[132:135], v[156:159], v[120:123]
	v_mfma_f32_16x16x32_bf16 v[116:119], v[140:143], v[156:159], v[116:119]
	v_mfma_f32_16x16x32_bf16 v[112:115], v[132:135], v[164:167], v[112:115]
	v_mfma_f32_16x16x32_bf16 v[108:111], v[140:143], v[164:167], v[108:111]
	v_mfma_f32_16x16x32_bf16 v[104:107], v[132:135], v[172:175], v[104:107]
	v_mfma_f32_16x16x32_bf16 v[100:103], v[140:143], v[172:175], v[100:103]
	v_mfma_f32_16x16x32_bf16 v[128:131], v[136:139], v[152:155], v[128:131]
	v_mfma_f32_16x16x32_bf16 v[124:127], v[144:147], v[152:155], v[124:127]
	v_mfma_f32_16x16x32_bf16 v[120:123], v[136:139], v[160:163], v[120:123]
	v_mfma_f32_16x16x32_bf16 v[116:119], v[144:147], v[160:163], v[116:119]
	v_mfma_f32_16x16x32_bf16 v[112:115], v[136:139], v[168:171], v[112:115]
	v_mfma_f32_16x16x32_bf16 v[108:111], v[144:147], v[168:171], v[108:111]
	v_mfma_f32_16x16x32_bf16 v[104:107], v[136:139], v[204:207], v[104:107]
	v_mfma_f32_16x16x32_bf16 v[100:103], v[144:147], v[204:207], v[100:103]
	v_mfma_f32_16x16x32_bf16 v[64:67], v[208:211], v[148:151], v[64:67]
	v_mfma_f32_16x16x32_bf16 v[60:63], v[242:245], v[148:151], v[60:63]
	v_mfma_f32_16x16x32_bf16 v[56:59], v[208:211], v[156:159], v[56:59]
	v_mfma_f32_16x16x32_bf16 v[52:55], v[242:245], v[156:159], v[52:55]
	v_mfma_f32_16x16x32_bf16 v[48:51], v[208:211], v[164:167], v[48:51]
	v_mfma_f32_16x16x32_bf16 v[44:47], v[242:245], v[164:167], v[44:47]
	v_mfma_f32_16x16x32_bf16 v[40:43], v[208:211], v[172:175], v[40:43]
	v_mfma_f32_16x16x32_bf16 v[36:39], v[242:245], v[172:175], v[36:39]
	v_mfma_f32_16x16x32_bf16 v[64:67], v[212:215], v[152:155], v[64:67]
	v_mfma_f32_16x16x32_bf16 v[60:63], v[246:249], v[152:155], v[60:63]
	v_mfma_f32_16x16x32_bf16 v[56:59], v[212:215], v[160:163], v[56:59]
	v_mfma_f32_16x16x32_bf16 v[52:55], v[246:249], v[160:163], v[52:55]
	v_mfma_f32_16x16x32_bf16 v[48:51], v[212:215], v[168:171], v[48:51]
	v_mfma_f32_16x16x32_bf16 v[44:47], v[246:249], v[168:171], v[44:47]
	v_mfma_f32_16x16x32_bf16 v[40:43], v[212:215], v[204:207], v[40:43]
	v_mfma_f32_16x16x32_bf16 v[36:39], v[246:249], v[204:207], v[36:39]
	s_barrier
	ds_read_b128 v[148:151], v240 offset:16384
	ds_read_b128 v[152:155], v240 offset:17408
	ds_read_b128 v[156:159], v240 offset:18432
	ds_read_b128 v[160:163], v240 offset:19456
	s_add_i32 m0, s67, 0x10000
	ds_read_b128 v[164:167], v240 offset:20480
	global_load_lds_dwordx4 v176, s[44:45]
	s_add_i32 m0, s67, 0x12000
	ds_read_b128 v[168:171], v240 offset:21504
	global_load_lds_dwordx4 v180, s[44:45]
	s_mov_b32 m0, s74
	ds_read_b128 v[172:175], v240 offset:22528
	global_load_lds_dwordx4 v0, s[46:47]
	s_mov_b32 m0, s75
	ds_read_b128 v[204:207], v240 offset:23552
	global_load_lds_dwordx4 v178, s[46:47]
	s_add_i32 m0, s67, 0x14000
	s_add_u32 s24, s44, 0x40000
	s_addc_u32 s25, s45, 0
	global_load_lds_dwordx4 v176, s[24:25]
	s_add_i32 m0, s67, 0x16000
	s_waitcnt vmcnt(7)
	global_load_lds_dwordx4 v180, s[24:25]
	s_barrier
	s_waitcnt lgkmcnt(0)
	v_mfma_f32_16x16x32_bf16 v[96:99], v[132:135], v[148:151], v[96:99]
	v_mfma_f32_16x16x32_bf16 v[92:95], v[140:143], v[148:151], v[92:95]
	v_mfma_f32_16x16x32_bf16 v[88:91], v[132:135], v[156:159], v[88:91]
	v_mfma_f32_16x16x32_bf16 v[84:87], v[140:143], v[156:159], v[84:87]
	v_mfma_f32_16x16x32_bf16 v[80:83], v[132:135], v[164:167], v[80:83]
	v_mfma_f32_16x16x32_bf16 v[76:79], v[140:143], v[164:167], v[76:79]
	v_mfma_f32_16x16x32_bf16 v[72:75], v[132:135], v[172:175], v[72:75]
	v_mfma_f32_16x16x32_bf16 v[68:71], v[140:143], v[172:175], v[68:71]
	v_mfma_f32_16x16x32_bf16 v[96:99], v[136:139], v[152:155], v[96:99]
	v_mfma_f32_16x16x32_bf16 v[92:95], v[144:147], v[152:155], v[92:95]
	v_mfma_f32_16x16x32_bf16 v[88:91], v[136:139], v[160:163], v[88:91]
	v_mfma_f32_16x16x32_bf16 v[84:87], v[144:147], v[160:163], v[84:87]
	v_mfma_f32_16x16x32_bf16 v[80:83], v[136:139], v[168:171], v[80:83]
	v_mfma_f32_16x16x32_bf16 v[76:79], v[144:147], v[168:171], v[76:79]
	v_mfma_f32_16x16x32_bf16 v[72:75], v[136:139], v[204:207], v[72:75]
	v_mfma_f32_16x16x32_bf16 v[68:71], v[144:147], v[204:207], v[68:71]
	v_mfma_f32_16x16x32_bf16 v[32:35], v[208:211], v[148:151], v[32:35]
	v_mfma_f32_16x16x32_bf16 v[28:31], v[242:245], v[148:151], v[28:31]
	v_mfma_f32_16x16x32_bf16 v[24:27], v[208:211], v[156:159], v[24:27]
	v_mfma_f32_16x16x32_bf16 v[20:23], v[242:245], v[156:159], v[20:23]
	v_mfma_f32_16x16x32_bf16 v[16:19], v[208:211], v[164:167], v[16:19]
	v_mfma_f32_16x16x32_bf16 v[12:15], v[242:245], v[164:167], v[12:15]
	v_mfma_f32_16x16x32_bf16 v[8:11], v[208:211], v[172:175], v[8:11]
	v_mfma_f32_16x16x32_bf16 v[4:7], v[242:245], v[172:175], v[4:7]
	v_mfma_f32_16x16x32_bf16 v[32:35], v[212:215], v[152:155], v[32:35]
	v_mfma_f32_16x16x32_bf16 v[28:31], v[246:249], v[152:155], v[28:31]
	v_mfma_f32_16x16x32_bf16 v[24:27], v[212:215], v[160:163], v[24:27]
	v_mfma_f32_16x16x32_bf16 v[20:23], v[246:249], v[160:163], v[20:23]
	v_mfma_f32_16x16x32_bf16 v[16:19], v[212:215], v[168:171], v[16:19]
	v_mfma_f32_16x16x32_bf16 v[12:15], v[246:249], v[168:171], v[12:15]
	v_mfma_f32_16x16x32_bf16 v[8:11], v[212:215], v[204:207], v[8:11]
	v_mfma_f32_16x16x32_bf16 v[4:7], v[246:249], v[204:207], v[4:7]
	s_barrier
	ds_read_b128 v[132:135], v216 offset:32768
	ds_read_b128 v[136:139], v216 offset:33792
	ds_read_b128 v[140:143], v216 offset:34816
	ds_read_b128 v[144:147], v216 offset:35840
	s_add_u32 s24, s46, 0x40000
	s_addc_u32 s25, s47, 0
	s_mov_b32 m0, s82
	ds_read_b128 v[148:151], v240 offset:32768
	ds_read_b128 v[152:155], v240 offset:33792
	ds_read_b128 v[156:159], v240 offset:34816
	ds_read_b128 v[160:163], v240 offset:35840
	ds_read_b128 v[164:167], v240 offset:36864
	ds_read_b128 v[168:171], v240 offset:37888
	ds_read_b128 v[172:175], v240 offset:38912
	global_load_lds_dwordx4 v0, s[24:25]
	s_mov_b32 m0, s83
	ds_read_b128 v[204:207], v240 offset:39936
	global_load_lds_dwordx4 v178, s[24:25]
	ds_read_b128 v[208:211], v216 offset:49152
	ds_read_b128 v[212:215], v216 offset:50176
	ds_read_b128 v[242:245], v216 offset:51200
	ds_read_b128 v[246:249], v216 offset:52224
	s_waitcnt vmcnt(8)
	s_barrier
	s_waitcnt lgkmcnt(0)
	v_mfma_f32_16x16x32_bf16 v[128:131], v[132:135], v[148:151], v[128:131]
	v_mfma_f32_16x16x32_bf16 v[124:127], v[140:143], v[148:151], v[124:127]
	v_mfma_f32_16x16x32_bf16 v[120:123], v[132:135], v[156:159], v[120:123]
	v_mfma_f32_16x16x32_bf16 v[116:119], v[140:143], v[156:159], v[116:119]
	v_mfma_f32_16x16x32_bf16 v[112:115], v[132:135], v[164:167], v[112:115]
	v_mfma_f32_16x16x32_bf16 v[108:111], v[140:143], v[164:167], v[108:111]
	v_mfma_f32_16x16x32_bf16 v[104:107], v[132:135], v[172:175], v[104:107]
	v_mfma_f32_16x16x32_bf16 v[100:103], v[140:143], v[172:175], v[100:103]
	v_mfma_f32_16x16x32_bf16 v[128:131], v[136:139], v[152:155], v[128:131]
	v_mfma_f32_16x16x32_bf16 v[124:127], v[144:147], v[152:155], v[124:127]
	v_mfma_f32_16x16x32_bf16 v[120:123], v[136:139], v[160:163], v[120:123]
	v_mfma_f32_16x16x32_bf16 v[116:119], v[144:147], v[160:163], v[116:119]
	v_mfma_f32_16x16x32_bf16 v[112:115], v[136:139], v[168:171], v[112:115]
	v_mfma_f32_16x16x32_bf16 v[108:111], v[144:147], v[168:171], v[108:111]
	v_mfma_f32_16x16x32_bf16 v[104:107], v[136:139], v[204:207], v[104:107]
	v_mfma_f32_16x16x32_bf16 v[100:103], v[144:147], v[204:207], v[100:103]
	v_mfma_f32_16x16x32_bf16 v[64:67], v[208:211], v[148:151], v[64:67]
	v_mfma_f32_16x16x32_bf16 v[60:63], v[242:245], v[148:151], v[60:63]
	v_mfma_f32_16x16x32_bf16 v[56:59], v[208:211], v[156:159], v[56:59]
	v_mfma_f32_16x16x32_bf16 v[52:55], v[242:245], v[156:159], v[52:55]
	v_mfma_f32_16x16x32_bf16 v[48:51], v[208:211], v[164:167], v[48:51]
	v_mfma_f32_16x16x32_bf16 v[44:47], v[242:245], v[164:167], v[44:47]
	v_mfma_f32_16x16x32_bf16 v[40:43], v[208:211], v[172:175], v[40:43]
	v_mfma_f32_16x16x32_bf16 v[36:39], v[242:245], v[172:175], v[36:39]
	v_mfma_f32_16x16x32_bf16 v[64:67], v[212:215], v[152:155], v[64:67]
	v_mfma_f32_16x16x32_bf16 v[60:63], v[246:249], v[152:155], v[60:63]
	v_mfma_f32_16x16x32_bf16 v[56:59], v[212:215], v[160:163], v[56:59]
	v_mfma_f32_16x16x32_bf16 v[52:55], v[246:249], v[160:163], v[52:55]
	v_mfma_f32_16x16x32_bf16 v[48:51], v[212:215], v[168:171], v[48:51]
	v_mfma_f32_16x16x32_bf16 v[44:47], v[246:249], v[168:171], v[44:47]
	v_mfma_f32_16x16x32_bf16 v[40:43], v[212:215], v[204:207], v[40:43]
	v_mfma_f32_16x16x32_bf16 v[36:39], v[246:249], v[204:207], v[36:39]
	s_barrier
	ds_read_b128 v[148:151], v240 offset:49152
	ds_read_b128 v[152:155], v240 offset:50176
	ds_read_b128 v[156:159], v240 offset:51200
	ds_read_b128 v[160:163], v240 offset:52224
	ds_read_b128 v[164:167], v240 offset:53248
	ds_read_b128 v[168:171], v240 offset:54272
	s_add_i32 m0, s67, 0x18000
	s_add_u32 s98, s44, 0x80
	s_addc_u32 s99, s45, 0
	global_load_lds_dwordx4 v176, s[98:99]
	s_add_i32 m0, s67, 0x1a000
	ds_read_b128 v[172:175], v240 offset:55296
	global_load_lds_dwordx4 v180, s[98:99]
	s_mov_b32 m0, s48
	s_add_u32 s98, s46, 0x80
	s_addc_u32 s99, s47, 0
	global_load_lds_dwordx4 v0, s[98:99]
	s_mov_b32 m0, s50
	ds_read_b128 v[204:207], v240 offset:56320
	global_load_lds_dwordx4 v178, s[98:99]
	s_add_i32 m0, s67, 0x1c000
	s_add_u32 s24, s44, 0x40080
	s_addc_u32 s25, s45, 0
	global_load_lds_dwordx4 v176, s[24:25]
	s_add_i32 m0, s67, 0x1e000
	s_waitcnt vmcnt(7)
	global_load_lds_dwordx4 v180, s[24:25]
	s_barrier
	s_waitcnt lgkmcnt(0)
	v_mfma_f32_16x16x32_bf16 v[96:99], v[132:135], v[148:151], v[96:99]
	v_mfma_f32_16x16x32_bf16 v[92:95], v[140:143], v[148:151], v[92:95]
	v_mfma_f32_16x16x32_bf16 v[88:91], v[132:135], v[156:159], v[88:91]
	v_mfma_f32_16x16x32_bf16 v[84:87], v[140:143], v[156:159], v[84:87]
	v_mfma_f32_16x16x32_bf16 v[80:83], v[132:135], v[164:167], v[80:83]
	v_mfma_f32_16x16x32_bf16 v[76:79], v[140:143], v[164:167], v[76:79]
	v_mfma_f32_16x16x32_bf16 v[72:75], v[132:135], v[172:175], v[72:75]
	v_mfma_f32_16x16x32_bf16 v[68:71], v[140:143], v[172:175], v[68:71]
	v_mfma_f32_16x16x32_bf16 v[96:99], v[136:139], v[152:155], v[96:99]
	v_mfma_f32_16x16x32_bf16 v[92:95], v[144:147], v[152:155], v[92:95]
	v_mfma_f32_16x16x32_bf16 v[88:91], v[136:139], v[160:163], v[88:91]
	v_mfma_f32_16x16x32_bf16 v[84:87], v[144:147], v[160:163], v[84:87]
	v_mfma_f32_16x16x32_bf16 v[80:83], v[136:139], v[168:171], v[80:83]
	v_mfma_f32_16x16x32_bf16 v[76:79], v[144:147], v[168:171], v[76:79]
	v_mfma_f32_16x16x32_bf16 v[72:75], v[136:139], v[204:207], v[72:75]
	v_mfma_f32_16x16x32_bf16 v[68:71], v[144:147], v[204:207], v[68:71]
	v_mfma_f32_16x16x32_bf16 v[32:35], v[208:211], v[148:151], v[32:35]
	v_mfma_f32_16x16x32_bf16 v[28:31], v[242:245], v[148:151], v[28:31]
	v_mfma_f32_16x16x32_bf16 v[24:27], v[208:211], v[156:159], v[24:27]
	v_mfma_f32_16x16x32_bf16 v[20:23], v[242:245], v[156:159], v[20:23]
	v_mfma_f32_16x16x32_bf16 v[16:19], v[208:211], v[164:167], v[16:19]
	v_mfma_f32_16x16x32_bf16 v[12:15], v[242:245], v[164:167], v[12:15]
	v_mfma_f32_16x16x32_bf16 v[8:11], v[208:211], v[172:175], v[8:11]
	v_mfma_f32_16x16x32_bf16 v[4:7], v[242:245], v[172:175], v[4:7]
	v_mfma_f32_16x16x32_bf16 v[32:35], v[212:215], v[152:155], v[32:35]
	v_mfma_f32_16x16x32_bf16 v[28:31], v[246:249], v[152:155], v[28:31]
	v_mfma_f32_16x16x32_bf16 v[24:27], v[212:215], v[160:163], v[24:27]
	v_mfma_f32_16x16x32_bf16 v[20:23], v[246:249], v[160:163], v[20:23]
	v_mfma_f32_16x16x32_bf16 v[16:19], v[212:215], v[168:171], v[16:19]
	v_mfma_f32_16x16x32_bf16 v[12:15], v[246:249], v[168:171], v[12:15]
	v_mfma_f32_16x16x32_bf16 v[8:11], v[212:215], v[204:207], v[8:11]
	v_mfma_f32_16x16x32_bf16 v[4:7], v[246:249], v[204:207], v[4:7]
	s_add_i32 s22, s22, 2
	s_add_u32 s0, s0, 0x100
	s_addc_u32 s1, s1, 0
	s_add_u32 s20, s20, 0x100
	s_addc_u32 s21, s21, 0
	s_cmp_gt_u32 s22, 13
	s_barrier
	s_cbranch_scc0 .LBB0_427
	s_add_i32 s0, s61, -8
	s_cmp_lt_u32 s0, 12
	s_mov_b64 s[0:1], -1
	s_cbranch_scc1 .LBB0_451
	s_cmp_gt_i32 s61, 33
	s_cselect_b64 s[64:65], -1, 0
	s_lshl_b32 s0, s61, 8
	s_lshl_b32 s53, s60, 8
	s_add_i32 s1, s0, 0xffffee00
	s_cmp_lt_i32 s61, 26
	v_cndmask_b32_e64 v2, 0, 1, s[36:37]
	s_cselect_b32 s62, s0, s1
	s_mov_b64 s[0:1], -1
	s_and_b64 vcc, exec, s[64:65]
	v_cmp_ne_u32_e64 s[44:45], 1, v2
	s_cbranch_vccz .LBB0_433
	s_and_b64 vcc, exec, s[44:45]
	s_cbranch_vccnz .LBB0_432
	v_add_u32_e32 v132, s53, v185
	v_ashrrev_i32_e32 v133, 31, v132
	v_lshlrev_b64 v[140:141], 7, v[132:133]
	global_load_dwordx4 v[204:207], v[188:189], off offset:16
	global_load_dwordx4 v[208:211], v[188:189], off
	s_mov_b32 s3, 0xbfb8aa3b
	s_mov_b32 s2, 0x800000
	s_mov_b32 s4, 0x3f317217
	s_mov_b32 s5, 0x7f800000
	s_waitcnt vmcnt(0)
	v_mov_b32_e32 v132, v204
	v_mov_b32_e32 v133, v205
	v_mov_b32_e32 v134, v206
	v_mov_b32_e32 v135, v207
	v_mov_b32_e32 v136, v208
	v_mov_b32_e32 v137, v209
	v_mov_b32_e32 v138, v210
	v_mov_b32_e32 v139, v211
	v_add_f32_e32 v147, v126, v134
	v_add_f32_e32 v2, v128, v136
	v_max_f32_e32 v142, 0, v2
	v_mul_f32_e64 v2, |v2|, s3
	v_exp_f32_e32 v2, v2
	v_add_f32_e32 v136, v124, v132
	v_add_f32_e32 v149, v127, v135
	v_add_f32_e32 v2, 1.0, v2
	v_cmp_gt_f32_e32 vcc, s2, v2
	s_nop 1
	v_cndmask_b32_e64 v132, 0, 32, vcc
	v_ldexp_f32 v2, v2, v132
	v_log_f32_e32 v2, v2
	s_nop 0
	v_mul_f32_e32 v132, 0x3f317217, v2
	v_fma_f32 v132, v2, s4, -v132
	v_fmac_f32_e32 v132, 0x3377d1cf, v2
	v_fmac_f32_e32 v132, 0x3f317217, v2
	v_cmp_lt_f32_e64 s[0:1], |v2|, s5
	s_nop 1
	v_cndmask_b32_e64 v2, v2, v132, s[0:1]
	v_cndmask_b32_e32 v132, 0, v228, vcc
	v_sub_f32_e32 v144, v2, v132
	v_mul_f32_e64 v2, |v136|, s3
	v_exp_f32_e32 v2, v2
	v_max_f32_e32 v132, 0, v136
	v_add_f32_e32 v2, 1.0, v2
	v_cmp_gt_f32_e32 vcc, s2, v2
	s_nop 1
	v_cndmask_b32_e64 v136, 0, 32, vcc
	v_ldexp_f32 v2, v2, v136
	v_log_f32_e32 v2, v2
	s_nop 0
	v_mul_f32_e32 v136, 0x3f317217, v2
	v_fma_f32 v136, v2, s4, -v136
	v_fmac_f32_e32 v136, 0x3377d1cf, v2
	v_fmac_f32_e32 v136, 0x3f317217, v2
	v_cmp_lt_f32_e64 s[0:1], |v2|, s5
	s_nop 1
	v_cndmask_b32_e64 v2, v2, v136, s[0:1]
	v_cndmask_b32_e32 v136, 0, v228, vcc
	v_sub_f32_e32 v136, v2, v136
	v_add_f32_e32 v2, v129, v137
	v_max_f32_e32 v143, 0, v2
	v_mul_f32_e64 v2, |v2|, s3
	v_exp_f32_e32 v2, v2
	v_add_f32_e32 v137, v125, v133
	v_add_f32_e32 v2, 1.0, v2
	v_cmp_gt_f32_e32 vcc, s2, v2
	s_nop 1
	v_cndmask_b32_e64 v133, 0, 32, vcc
	v_ldexp_f32 v2, v2, v133
	v_log_f32_e32 v2, v2
	s_nop 0
	v_mul_f32_e32 v133, 0x3f317217, v2
	v_fma_f32 v133, v2, s4, -v133
	v_fmac_f32_e32 v133, 0x3377d1cf, v2
	v_fmac_f32_e32 v133, 0x3f317217, v2
	v_cmp_lt_f32_e64 s[0:1], |v2|, s5
	s_nop 1
	v_cndmask_b32_e64 v2, v2, v133, s[0:1]
	v_cndmask_b32_e32 v133, 0, v228, vcc
	v_sub_f32_e32 v145, v2, v133
	v_mul_f32_e64 v2, |v137|, s3
	v_exp_f32_e32 v2, v2
	v_max_f32_e32 v133, 0, v137
	v_pk_add_f32 v[142:143], v[142:143], v[144:145]
	v_add_f32_e32 v2, 1.0, v2
	v_cmp_gt_f32_e32 vcc, s2, v2
	s_nop 1
	v_cndmask_b32_e64 v137, 0, 32, vcc
	v_ldexp_f32 v2, v2, v137
	v_log_f32_e32 v2, v2
	s_nop 0
	v_mul_f32_e32 v137, 0x3f317217, v2
	v_fma_f32 v137, v2, s4, -v137
	v_fmac_f32_e32 v137, 0x3377d1cf, v2
	v_fmac_f32_e32 v137, 0x3f317217, v2
	v_cmp_lt_f32_e64 s[0:1], |v2|, s5
	s_nop 1
	v_cndmask_b32_e64 v2, v2, v137, s[0:1]
	v_cndmask_b32_e32 v137, 0, v228, vcc
	v_sub_f32_e32 v137, v2, v137
	v_add_f32_e32 v2, v130, v138
	v_max_f32_e32 v138, 0, v2
	v_mul_f32_e64 v2, |v2|, s3
	v_exp_f32_e32 v2, v2
	v_pk_add_f32 v[132:133], v[132:133], v[136:137]
	v_lshl_add_u64 v[136:137], v[190:191], 0, v[140:141]
	v_add_f32_e32 v2, 1.0, v2
	v_cmp_gt_f32_e32 vcc, s2, v2
	s_nop 1
	v_cndmask_b32_e64 v134, 0, 32, vcc
	v_ldexp_f32 v2, v2, v134
	v_log_f32_e32 v2, v2
	s_nop 0
	v_mul_f32_e32 v134, 0x3f317217, v2
	v_fma_f32 v134, v2, s4, -v134
	v_fmac_f32_e32 v134, 0x3377d1cf, v2
	v_fmac_f32_e32 v134, 0x3f317217, v2
	v_cmp_lt_f32_e64 s[0:1], |v2|, s5
	s_nop 1
	v_cndmask_b32_e64 v2, v2, v134, s[0:1]
	v_cndmask_b32_e32 v134, 0, v228, vcc
	v_sub_f32_e32 v146, v2, v134
	v_mul_f32_e64 v2, |v147|, s3
	v_exp_f32_e32 v2, v2
	v_max_f32_e32 v134, 0, v147
	v_add_f32_e32 v2, 1.0, v2
	v_cmp_gt_f32_e32 vcc, s2, v2
	s_nop 1
	v_cndmask_b32_e64 v147, 0, 32, vcc
	v_ldexp_f32 v2, v2, v147
	v_log_f32_e32 v2, v2
	s_nop 0
	v_mul_f32_e32 v147, 0x3f317217, v2
	v_fma_f32 v147, v2, s4, -v147
	v_fmac_f32_e32 v147, 0x3377d1cf, v2
	v_fmac_f32_e32 v147, 0x3f317217, v2
	v_cmp_lt_f32_e64 s[0:1], |v2|, s5
	s_nop 1
	v_cndmask_b32_e64 v2, v2, v147, s[0:1]
	v_cndmask_b32_e32 v147, 0, v228, vcc
	v_sub_f32_e32 v148, v2, v147
	v_add_f32_e32 v2, v131, v139
	v_max_f32_e32 v139, 0, v2
	v_mul_f32_e64 v2, |v2|, s3
	v_exp_f32_e32 v2, v2
	s_nop 0
	v_add_f32_e32 v2, 1.0, v2
	v_cmp_gt_f32_e32 vcc, s2, v2
	s_nop 1
	v_cndmask_b32_e64 v135, 0, 32, vcc
	v_ldexp_f32 v2, v2, v135
	v_log_f32_e32 v2, v2
	s_nop 0
	v_mul_f32_e32 v135, 0x3f317217, v2
	v_fma_f32 v135, v2, s4, -v135
	v_fmac_f32_e32 v135, 0x3377d1cf, v2
	v_fmac_f32_e32 v135, 0x3f317217, v2
	v_cmp_lt_f32_e64 s[0:1], |v2|, s5
	s_nop 1
	v_cndmask_b32_e64 v2, v2, v135, s[0:1]
	v_cndmask_b32_e32 v135, 0, v228, vcc
	v_sub_f32_e32 v147, v2, v135
	v_mul_f32_e64 v2, |v149|, s3
	v_exp_f32_e32 v2, v2
	v_pk_add_f32 v[144:145], v[138:139], v[146:147]
	v_max_f32_e32 v135, 0, v149
	v_add_f32_e32 v2, 1.0, v2
	v_cmp_gt_f32_e32 vcc, s2, v2
	s_nop 1
	v_cndmask_b32_e64 v138, 0, 32, vcc
	v_ldexp_f32 v2, v2, v138
	v_log_f32_e32 v2, v2
	s_nop 0
	v_mul_f32_e32 v138, 0x3f317217, v2
	v_fma_f32 v138, v2, s4, -v138
	v_fmac_f32_e32 v138, 0x3377d1cf, v2
	v_fmac_f32_e32 v138, 0x3f317217, v2
	v_cmp_lt_f32_e64 s[0:1], |v2|, s5
	s_nop 1
	v_cndmask_b32_e64 v2, v2, v138, s[0:1]
	v_cndmask_b32_e32 v138, 0, v228, vcc
	v_sub_f32_e32 v149, v2, v138
	v_pk_add_f32 v[134:135], v[134:135], v[148:149]
	global_store_dwordx4 v[136:137], v[142:145], off
	global_store_dwordx4 v[136:137], v[132:135], off offset:16
